# non-temporal hint on the layer-0 and layer-1 input-projection epilogue stores
# speedup vs baseline: 1.0099x; 1.0064x over previous
.LBB0_480:
	v_readlane_b32 s68, v254, 15
	v_cvt_pk_bf16_f32 v168, v130, v131
	v_lshlrev_b64 v[130:131], 7, v[160:161]
	v_readlane_b32 s69, v254, 16
	v_lshlrev_b32_e32 v146, 1, v150
	v_cvt_pk_bf16_f32 v169, v132, v134
	v_cvt_pk_bf16_f32 v170, v133, v137
	v_cvt_pk_bf16_f32 v171, v164, v166
	s_and_b64 vcc, exec, s[14:15]
	v_lshl_add_u64 v[130:131], s[68:69], 0, v[130:131]
	v_lshl_add_u64 v[132:133], v[130:131], 0, v[146:147]
	global_store_dwordx4 v[132:133], v[168:171], off nt
	v_mov_b32_e32 v134, v110
	v_mov_b32_e32 v135, v111
	v_mov_b32_e32 v136, v112
	v_mov_b32_e32 v164, v113
	v_mov_b32_e32 v137, v106
	v_mov_b32_e32 v167, v107
	v_mov_b32_e32 v168, v108
	v_mov_b32_e32 v170, v109
	s_cbranch_vccnz .LBB0_482
	v_readlane_b32 s68, v254, 23
	v_mov_b32_e32 v134, s17
	v_readlane_b32 s69, v254, 24
	s_nop 1
	v_cndmask_b32_e64 v134, v174, v134, s[68:69]
	v_lshl_or_b32 v134, v134, 5, v151
	v_readlane_b32 s68, v254, 21
	v_ashrrev_i32_e32 v135, 31, v134
	v_readlane_b32 s69, v254, 22
	s_nop 1
	v_lshl_add_u64 v[134:135], v[134:135], 2, s[68:69]
	global_load_dwordx4 v[168:171], v[134:135], off offset:16
	global_load_dwordx4 v[164:167], v[134:135], off
	s_waitcnt vmcnt(0)
	v_pk_mul_f32 v[200:201], v[106:107], v[168:169] op_sel:[1,1] op_sel_hi:[1,0]
	v_pk_mul_f32 v[196:197], v[110:111], v[164:165] op_sel:[1,1] op_sel_hi:[1,0]
	v_pk_mul_f32 v[172:173], v[110:111], v[164:165]
	v_pk_fma_f32 v[134:135], v[110:111], v[164:165], v[196:197] op_sel_hi:[0,1,1]
	v_mul_f32_e32 v134, v113, v167
	v_pk_fma_f32 v[136:137], v[112:113], v[166:167], v[134:135] op_sel_hi:[1,1,0] neg_lo:[0,0,1] neg_hi:[0,0,1]
	v_mul_f32_e32 v134, v113, v166
	v_pk_fma_f32 v[164:165], v[112:113], v[166:167], v[134:135] op_sel:[0,1,0] op_sel_hi:[1,0,0]
	v_mul_f32_e32 v134, v109, v171
	v_pk_mul_f32 v[198:199], v[106:107], v[168:169]
	v_pk_fma_f32 v[166:167], v[106:107], v[168:169], v[200:201] op_sel_hi:[0,1,1]
	v_pk_fma_f32 v[168:169], v[108:109], v[170:171], v[134:135] op_sel_hi:[1,1,0] neg_lo:[0,0,1] neg_hi:[0,0,1]
	v_mul_f32_e32 v134, v109, v170
	v_pk_fma_f32 v[170:171], v[108:109], v[170:171], v[134:135] op_sel:[0,1,0] op_sel_hi:[1,0,0]
	v_sub_f32_e32 v134, v172, v196
	v_sub_f32_e32 v137, v198, v200
.LBB0_482:
	v_cvt_pk_bf16_f32 v134, v134, v135
	v_cvt_pk_bf16_f32 v135, v136, v164
	v_cvt_pk_bf16_f32 v136, v137, v167
	v_cvt_pk_bf16_f32 v137, v168, v170
	global_store_dwordx4 v[132:133], v[134:137], off offset:2048 nt
	s_and_b64 vcc, exec, s[14:15]
	v_mov_b32_e32 v132, v94
	v_mov_b32_e32 v133, v95
	v_mov_b32_e32 v134, v96
	v_mov_b32_e32 v136, v97
	v_mov_b32_e32 v135, v90
	v_mov_b32_e32 v165, v91
	v_mov_b32_e32 v166, v92
	v_mov_b32_e32 v168, v93
	s_cbranch_vccnz .LBB0_484
	v_readlane_b32 s68, v254, 23
	v_mov_b32_e32 v132, s17
	v_readlane_b32 s69, v254, 24
	s_nop 1
	v_cndmask_b32_e64 v132, v175, v132, s[68:69]
	v_lshl_or_b32 v132, v132, 5, v151
	v_readlane_b32 s68, v254, 21
	v_ashrrev_i32_e32 v133, 31, v132
	v_readlane_b32 s69, v254, 22
	s_nop 1
	v_lshl_add_u64 v[132:133], v[132:133], 2, s[68:69]
	global_load_dwordx4 v[166:169], v[132:133], off offset:16
	global_load_dwordx4 v[134:137], v[132:133], off
	s_waitcnt vmcnt(0)
	v_pk_mul_f32 v[198:199], v[90:91], v[166:167] op_sel:[1,1] op_sel_hi:[1,0]
	v_pk_mul_f32 v[172:173], v[94:95], v[134:135] op_sel:[1,1] op_sel_hi:[1,0]
	v_pk_mul_f32 v[170:171], v[94:95], v[134:135]
	v_pk_fma_f32 v[132:133], v[94:95], v[134:135], v[172:173] op_sel_hi:[0,1,1]
	v_mul_f32_e32 v132, v97, v137
	v_pk_fma_f32 v[134:135], v[96:97], v[136:137], v[132:133] op_sel_hi:[1,1,0] neg_lo:[0,0,1] neg_hi:[0,0,1]
	v_mul_f32_e32 v132, v97, v136
	v_pk_fma_f32 v[136:137], v[96:97], v[136:137], v[132:133] op_sel:[0,1,0] op_sel_hi:[1,0,0]
	v_mul_f32_e32 v132, v93, v169
	v_pk_mul_f32 v[196:197], v[90:91], v[166:167]
	v_pk_fma_f32 v[164:165], v[90:91], v[166:167], v[198:199] op_sel_hi:[0,1,1]
	v_pk_fma_f32 v[166:167], v[92:93], v[168:169], v[132:133] op_sel_hi:[1,1,0] neg_lo:[0,0,1] neg_hi:[0,0,1]
	v_mul_f32_e32 v132, v93, v168
	v_pk_fma_f32 v[168:169], v[92:93], v[168:169], v[132:133] op_sel:[0,1,0] op_sel_hi:[1,0,0]
	v_sub_f32_e32 v132, v170, v172
	v_sub_f32_e32 v135, v196, v198
.LBB0_484:
	v_cvt_pk_bf16_f32 v170, v132, v133
	v_lshl_add_u64 v[132:133], v[130:131], 0, v[146:147]
	v_cvt_pk_bf16_f32 v171, v134, v136
	v_add_co_u32_e32 v134, vcc, 0x1000, v132
	v_cvt_pk_bf16_f32 v172, v135, v165
	v_cvt_pk_bf16_f32 v173, v166, v168
	v_mov_b32_e32 v136, v80
	s_nop 0
	v_addc_co_u32_e32 v135, vcc, 0, v133, vcc
	global_store_dwordx4 v[134:135], v[170:173], off nt
	s_and_b64 vcc, exec, s[14:15]
	v_mov_b32_e32 v134, v78
	v_mov_b32_e32 v135, v79
	v_mov_b32_e32 v164, v81
	v_mov_b32_e32 v137, v74
	v_mov_b32_e32 v167, v75
	v_mov_b32_e32 v168, v76
	v_mov_b32_e32 v170, v77
	s_cbranch_vccnz .LBB0_486
	v_readlane_b32 s68, v254, 23
	v_mov_b32_e32 v134, s17
	v_readlane_b32 s69, v254, 24
	s_nop 1
	v_cndmask_b32_e64 v134, v176, v134, s[68:69]
	v_lshl_or_b32 v134, v134, 5, v151
	v_readlane_b32 s68, v254, 21
	v_ashrrev_i32_e32 v135, 31, v134
	v_readlane_b32 s69, v254, 22
	s_nop 1
	v_lshl_add_u64 v[134:135], v[134:135], 2, s[68:69]
	global_load_dwordx4 v[168:171], v[134:135], off offset:16
	global_load_dwordx4 v[164:167], v[134:135], off
	s_waitcnt vmcnt(0)
	v_pk_mul_f32 v[200:201], v[74:75], v[168:169] op_sel:[1,1] op_sel_hi:[1,0]
	v_pk_mul_f32 v[196:197], v[78:79], v[164:165] op_sel:[1,1] op_sel_hi:[1,0]
	v_pk_mul_f32 v[172:173], v[78:79], v[164:165]
	v_pk_fma_f32 v[134:135], v[78:79], v[164:165], v[196:197] op_sel_hi:[0,1,1]
	v_mul_f32_e32 v134, v81, v167
	v_pk_fma_f32 v[136:137], v[80:81], v[166:167], v[134:135] op_sel_hi:[1,1,0] neg_lo:[0,0,1] neg_hi:[0,0,1]
	v_mul_f32_e32 v134, v81, v166
	v_pk_fma_f32 v[164:165], v[80:81], v[166:167], v[134:135] op_sel:[0,1,0] op_sel_hi:[1,0,0]
	v_mul_f32_e32 v134, v77, v171
	v_pk_mul_f32 v[198:199], v[74:75], v[168:169]
	v_pk_fma_f32 v[166:167], v[74:75], v[168:169], v[200:201] op_sel_hi:[0,1,1]
	v_pk_fma_f32 v[168:169], v[76:77], v[170:171], v[134:135] op_sel_hi:[1,1,0] neg_lo:[0,0,1] neg_hi:[0,0,1]
	v_mul_f32_e32 v134, v77, v170
	v_pk_fma_f32 v[170:171], v[76:77], v[170:171], v[134:135] op_sel:[0,1,0] op_sel_hi:[1,0,0]
	v_sub_f32_e32 v134, v172, v196
	v_sub_f32_e32 v137, v198, v200
.LBB0_486:
	v_add_co_u32_e32 v132, vcc, 0x1000, v132
	v_cvt_pk_bf16_f32 v134, v134, v135
	v_cvt_pk_bf16_f32 v135, v136, v164
	v_cvt_pk_bf16_f32 v136, v137, v167
	v_cvt_pk_bf16_f32 v137, v168, v170
	s_nop 1
	v_addc_co_u32_e32 v133, vcc, 0, v133, vcc
	global_store_dwordx4 v[132:133], v[134:137], off offset:2048 nt
	s_add_i32 s17, s17, 2
	s_and_b64 vcc, exec, s[14:15]
	v_mov_b32_e32 v132, v62
	v_mov_b32_e32 v133, v63
	v_mov_b32_e32 v134, v64
	v_mov_b32_e32 v136, v65
	v_mov_b32_e32 v135, v58
	v_mov_b32_e32 v165, v59
	v_mov_b32_e32 v166, v60
	v_mov_b32_e32 v168, v61
	s_cbranch_vccnz .LBB0_488
	v_readlane_b32 s68, v254, 23
	v_mov_b32_e32 v132, s17
	v_readlane_b32 s69, v254, 24
	s_nop 1
	v_cndmask_b32_e64 v132, v1, v132, s[68:69]
	v_lshl_or_b32 v132, v132, 5, v151
	v_readlane_b32 s68, v254, 21
	v_ashrrev_i32_e32 v133, 31, v132
	v_readlane_b32 s69, v254, 22
	s_nop 1
	v_lshl_add_u64 v[132:133], v[132:133], 2, s[68:69]
	global_load_dwordx4 v[166:169], v[132:133], off offset:16
	global_load_dwordx4 v[134:137], v[132:133], off
	s_waitcnt vmcnt(0)
	v_pk_mul_f32 v[198:199], v[58:59], v[166:167] op_sel:[1,1] op_sel_hi:[1,0]
	v_pk_mul_f32 v[172:173], v[62:63], v[134:135] op_sel:[1,1] op_sel_hi:[1,0]
	v_pk_mul_f32 v[170:171], v[62:63], v[134:135]
	v_pk_fma_f32 v[132:133], v[62:63], v[134:135], v[172:173] op_sel_hi:[0,1,1]
	v_mul_f32_e32 v132, v65, v137
	v_pk_fma_f32 v[134:135], v[64:65], v[136:137], v[132:133] op_sel_hi:[1,1,0] neg_lo:[0,0,1] neg_hi:[0,0,1]
	v_mul_f32_e32 v132, v65, v136
	v_pk_fma_f32 v[136:137], v[64:65], v[136:137], v[132:133] op_sel:[0,1,0] op_sel_hi:[1,0,0]
	v_mul_f32_e32 v132, v61, v169
	v_pk_mul_f32 v[196:197], v[58:59], v[166:167]
	v_pk_fma_f32 v[164:165], v[58:59], v[166:167], v[198:199] op_sel_hi:[0,1,1]
	v_pk_fma_f32 v[166:167], v[60:61], v[168:169], v[132:133] op_sel_hi:[1,1,0] neg_lo:[0,0,1] neg_hi:[0,0,1]
	v_mul_f32_e32 v132, v61, v168
	v_pk_fma_f32 v[168:169], v[60:61], v[168:169], v[132:133] op_sel:[0,1,0] op_sel_hi:[1,0,0]
	v_sub_f32_e32 v132, v170, v172
	v_sub_f32_e32 v135, v196, v198
.LBB0_488:
	v_cvt_pk_bf16_f32 v170, v132, v133
	v_lshl_add_u64 v[132:133], v[130:131], 0, v[146:147]
	v_cvt_pk_bf16_f32 v171, v134, v136
	v_add_co_u32_e32 v134, vcc, 0x4000, v132
	v_cvt_pk_bf16_f32 v172, v135, v165
	v_cvt_pk_bf16_f32 v173, v166, v168
	v_mov_b32_e32 v136, v48
	s_nop 0
	v_addc_co_u32_e32 v135, vcc, 0, v133, vcc
	global_store_dwordx4 v[134:135], v[170:173], off nt
	s_and_b64 vcc, exec, s[14:15]
	v_mov_b32_e32 v134, v46
	v_mov_b32_e32 v135, v47
	v_mov_b32_e32 v164, v49
	v_mov_b32_e32 v137, v42
	v_mov_b32_e32 v167, v43
	v_mov_b32_e32 v168, v44
	v_mov_b32_e32 v170, v45
	s_cbranch_vccnz .LBB0_490
	v_readlane_b32 s68, v254, 23
	v_mov_b32_e32 v134, s17
	v_readlane_b32 s69, v254, 24
	s_nop 1
	v_cndmask_b32_e64 v134, v174, v134, s[68:69]
	v_lshl_or_b32 v134, v134, 5, v151
	v_readlane_b32 s68, v254, 21
	v_ashrrev_i32_e32 v135, 31, v134
	v_readlane_b32 s69, v254, 22
	s_nop 1
	v_lshl_add_u64 v[134:135], v[134:135], 2, s[68:69]
	global_load_dwordx4 v[168:171], v[134:135], off offset:16
	global_load_dwordx4 v[164:167], v[134:135], off
	s_waitcnt vmcnt(0)
	v_pk_mul_f32 v[200:201], v[42:43], v[168:169] op_sel:[1,1] op_sel_hi:[1,0]
	v_pk_mul_f32 v[196:197], v[46:47], v[164:165] op_sel:[1,1] op_sel_hi:[1,0]
	v_pk_mul_f32 v[172:173], v[46:47], v[164:165]
	v_pk_fma_f32 v[134:135], v[46:47], v[164:165], v[196:197] op_sel_hi:[0,1,1]
	v_mul_f32_e32 v134, v49, v167
	v_pk_fma_f32 v[136:137], v[48:49], v[166:167], v[134:135] op_sel_hi:[1,1,0] neg_lo:[0,0,1] neg_hi:[0,0,1]
	v_mul_f32_e32 v134, v49, v166
	v_pk_fma_f32 v[164:165], v[48:49], v[166:167], v[134:135] op_sel:[0,1,0] op_sel_hi:[1,0,0]
	v_mul_f32_e32 v134, v45, v171
	v_pk_mul_f32 v[198:199], v[42:43], v[168:169]
	v_pk_fma_f32 v[166:167], v[42:43], v[168:169], v[200:201] op_sel_hi:[0,1,1]
	v_pk_fma_f32 v[168:169], v[44:45], v[170:171], v[134:135] op_sel_hi:[1,1,0] neg_lo:[0,0,1] neg_hi:[0,0,1]
	v_mul_f32_e32 v134, v45, v170
	v_pk_fma_f32 v[170:171], v[44:45], v[170:171], v[134:135] op_sel:[0,1,0] op_sel_hi:[1,0,0]
	v_sub_f32_e32 v134, v172, v196
	v_sub_f32_e32 v137, v198, v200
.LBB0_490:
	v_add_co_u32_e32 v132, vcc, 0x4000, v132
	v_cvt_pk_bf16_f32 v134, v134, v135
	v_cvt_pk_bf16_f32 v135, v136, v164
	v_cvt_pk_bf16_f32 v136, v137, v167
	v_cvt_pk_bf16_f32 v137, v168, v170
	s_nop 1
	v_addc_co_u32_e32 v133, vcc, 0, v133, vcc
	global_store_dwordx4 v[132:133], v[134:137], off offset:2048 nt
	s_and_b64 vcc, exec, s[14:15]
	v_mov_b32_e32 v132, v30
	v_mov_b32_e32 v133, v31
	v_mov_b32_e32 v134, v32
	v_mov_b32_e32 v136, v33
	v_mov_b32_e32 v135, v26
	v_mov_b32_e32 v165, v27
	v_mov_b32_e32 v166, v28
	v_mov_b32_e32 v168, v29
	s_cbranch_vccnz .LBB0_492
	v_readlane_b32 s68, v254, 23
	v_mov_b32_e32 v132, s17
	v_readlane_b32 s69, v254, 24
	s_nop 1
	v_cndmask_b32_e64 v132, v175, v132, s[68:69]
	v_lshl_or_b32 v132, v132, 5, v151
	v_readlane_b32 s68, v254, 21
	v_ashrrev_i32_e32 v133, 31, v132
	v_readlane_b32 s69, v254, 22
	s_nop 1
	v_lshl_add_u64 v[132:133], v[132:133], 2, s[68:69]
	global_load_dwordx4 v[166:169], v[132:133], off offset:16
	global_load_dwordx4 v[134:137], v[132:133], off
	s_waitcnt vmcnt(0)
	v_pk_mul_f32 v[198:199], v[26:27], v[166:167] op_sel:[1,1] op_sel_hi:[1,0]
	v_pk_mul_f32 v[172:173], v[30:31], v[134:135] op_sel:[1,1] op_sel_hi:[1,0]
	v_pk_mul_f32 v[170:171], v[30:31], v[134:135]
	v_pk_fma_f32 v[132:133], v[30:31], v[134:135], v[172:173] op_sel_hi:[0,1,1]
	v_mul_f32_e32 v132, v33, v137
	v_pk_fma_f32 v[134:135], v[32:33], v[136:137], v[132:133] op_sel_hi:[1,1,0] neg_lo:[0,0,1] neg_hi:[0,0,1]
	v_mul_f32_e32 v132, v33, v136
	v_pk_fma_f32 v[136:137], v[32:33], v[136:137], v[132:133] op_sel:[0,1,0] op_sel_hi:[1,0,0]
	v_mul_f32_e32 v132, v29, v169
	v_pk_mul_f32 v[196:197], v[26:27], v[166:167]
	v_pk_fma_f32 v[164:165], v[26:27], v[166:167], v[198:199] op_sel_hi:[0,1,1]
	v_pk_fma_f32 v[166:167], v[28:29], v[168:169], v[132:133] op_sel_hi:[1,1,0] neg_lo:[0,0,1] neg_hi:[0,0,1]
	v_mul_f32_e32 v132, v29, v168
	v_pk_fma_f32 v[168:169], v[28:29], v[168:169], v[132:133] op_sel:[0,1,0] op_sel_hi:[1,0,0]
	v_sub_f32_e32 v132, v170, v172
	v_sub_f32_e32 v135, v196, v198
.LBB0_492:
	v_lshl_add_u64 v[130:131], v[130:131], 0, v[146:147]
	v_cvt_pk_bf16_f32 v132, v132, v133
	v_cvt_pk_bf16_f32 v133, v134, v136
	v_add_co_u32_e32 v136, vcc, 0x5000, v130
	v_cvt_pk_bf16_f32 v134, v135, v165
	v_cvt_pk_bf16_f32 v135, v166, v168
	v_mov_b32_e32 v165, v11
	s_nop 0
	v_addc_co_u32_e32 v137, vcc, 0, v131, vcc
	global_store_dwordx4 v[136:137], v[132:135], off nt
	s_and_b64 vcc, exec, s[14:15]
	v_mov_b32_e32 v136, v17
	v_mov_b32_e32 v132, v14
	v_mov_b32_e32 v133, v15
	v_mov_b32_e32 v134, v16
	v_mov_b32_e32 v135, v10
	v_mov_b32_e32 v166, v12
	v_mov_b32_e32 v168, v13
	s_cbranch_vccnz .LBB0_494
	v_readlane_b32 s14, v254, 23
	v_mov_b32_e32 v132, s17
	v_readlane_b32 s15, v254, 24
	s_nop 1
	v_cndmask_b32_e64 v132, v176, v132, s[14:15]
	v_lshl_or_b32 v132, v132, 5, v151
	v_readlane_b32 s14, v254, 21
	v_ashrrev_i32_e32 v133, 31, v132
	v_readlane_b32 s15, v254, 22
	s_nop 1
	v_lshl_add_u64 v[132:133], v[132:133], 2, s[14:15]
	global_load_dwordx4 v[166:169], v[132:133], off offset:16
	global_load_dwordx4 v[134:137], v[132:133], off
	s_waitcnt vmcnt(0)
	v_pk_mul_f32 v[198:199], v[10:11], v[166:167] op_sel:[1,1] op_sel_hi:[1,0]
	v_pk_mul_f32 v[172:173], v[14:15], v[134:135] op_sel:[1,1] op_sel_hi:[1,0]
	v_pk_mul_f32 v[170:171], v[14:15], v[134:135]
	v_pk_fma_f32 v[132:133], v[14:15], v[134:135], v[172:173] op_sel_hi:[0,1,1]
	v_mul_f32_e32 v132, v17, v137
	v_pk_fma_f32 v[134:135], v[16:17], v[136:137], v[132:133] op_sel_hi:[1,1,0] neg_lo:[0,0,1] neg_hi:[0,0,1]
	v_mul_f32_e32 v132, v17, v136
	v_pk_fma_f32 v[136:137], v[16:17], v[136:137], v[132:133] op_sel:[0,1,0] op_sel_hi:[1,0,0]
	v_mul_f32_e32 v132, v13, v169
	v_pk_mul_f32 v[196:197], v[10:11], v[166:167]
	v_pk_fma_f32 v[164:165], v[10:11], v[166:167], v[198:199] op_sel_hi:[0,1,1]
	v_pk_fma_f32 v[166:167], v[12:13], v[168:169], v[132:133] op_sel_hi:[1,1,0] neg_lo:[0,0,1] neg_hi:[0,0,1]
	v_mul_f32_e32 v132, v13, v168
	v_pk_fma_f32 v[168:169], v[12:13], v[168:169], v[132:133] op_sel:[0,1,0] op_sel_hi:[1,0,0]
	v_sub_f32_e32 v132, v170, v172
	v_sub_f32_e32 v135, v196, v198
.LBB0_494:
	v_add_co_u32_e32 v130, vcc, 0x5000, v130
	v_cvt_pk_bf16_f32 v132, v132, v133
	v_cvt_pk_bf16_f32 v133, v134, v136
	v_cvt_pk_bf16_f32 v134, v135, v165
	v_cvt_pk_bf16_f32 v135, v166, v168
	s_nop 1
	v_addc_co_u32_e32 v131, vcc, 0, v131, vcc
	global_store_dwordx4 v[130:131], v[132:135], off offset:2048 nt

.LBB0_496:
	s_andn2_b64 vcc, exec, s[14:15]
	s_cbranch_vccnz .LBB0_498
	v_mul_f32_e32 v133, 0xbfb8aa3b, v122
	v_mul_f32_e32 v134, 0xbfb8aa3b, v127
	v_exp_f32_e32 v133, v133
	v_exp_f32_e32 v134, v134
	v_mul_f32_e32 v135, 0xbfb8aa3b, v123
	v_exp_f32_e32 v135, v135
	v_add_f32_e32 v133, 1.0, v133
	v_add_f32_e32 v134, 1.0, v134
	v_rcp_f32_e32 v133, v133
	v_rcp_f32_e32 v134, v134
	v_mul_f32_e32 v130, 0xbfb8aa3b, v126
	v_mul_f32_e32 v146, 0xbfb8aa3b, v129
	v_exp_f32_e32 v132, v130
	v_mul_f32_e32 v136, v122, v133
	v_mul_f32_e32 v133, v127, v134
	v_add_f32_e32 v134, 1.0, v135
	v_mul_f32_e32 v135, 0xbfb8aa3b, v128
	v_exp_f32_e32 v146, v146
	v_exp_f32_e32 v135, v135
	v_mul_f32_e32 v137, 0xbfb8aa3b, v124
	v_exp_f32_e32 v137, v137
	v_mul_f32_e32 v164, 0xbfb8aa3b, v125
	v_add_f32_e32 v132, 1.0, v132
	v_exp_f32_e32 v164, v164
	v_add_f32_e32 v146, 1.0, v146
	v_rcp_f32_e32 v132, v132
	v_add_f32_e32 v135, 1.0, v135
	v_rcp_f32_e32 v146, v146
	v_rcp_f32_e32 v134, v134
	v_rcp_f32_e32 v135, v135
	v_add_f32_e32 v137, 1.0, v137
	v_readlane_b32 s14, v254, 13
	v_lshlrev_b64 v[130:131], 13, v[160:161]
	v_rcp_f32_e32 v137, v137
	v_add_f32_e32 v164, 1.0, v164
	v_readlane_b32 s15, v254, 14
	v_mul_f32_e32 v132, v126, v132
	v_rcp_f32_e32 v164, v164
	v_mul_f32_e32 v146, v129, v146
	v_lshl_add_u64 v[130:131], s[14:15], 0, v[130:131]
	s_lshl_b32 s24, s16, 9
	v_mul_f32_e32 v134, v123, v134
	v_mul_f32_e32 v135, v128, v135
	v_cvt_pk_bf16_f32 v132, v132, v133
	v_cvt_pk_bf16_f32 v133, v135, v146
	v_lshl_add_u64 v[130:131], v[130:131], 0, s[24:25]
	v_lshlrev_b32_e32 v146, 1, v150
	v_cvt_pk_bf16_f32 v134, v136, v134
	v_lshl_add_u64 v[130:131], v[130:131], 0, v[146:147]
	v_mul_f32_e32 v136, 0xbfb8aa3b, v118
	s_movk_i32 s10, 0xe000
	v_mul_f32_e32 v137, v124, v137
	v_exp_f32_e32 v146, v136
	v_add_co_u32_e32 v136, vcc, s10, v130
	v_mul_f32_e32 v164, v125, v164
	v_cvt_pk_bf16_f32 v135, v137, v164
	s_nop 0
	v_addc_co_u32_e32 v137, vcc, -1, v131, vcc
	global_store_dwordx4 v[136:137], v[132:135], off offset:-1024 nt
	v_mul_f32_e32 v165, 0xbfb8aa3b, v121
	v_mul_f32_e32 v164, 0xbfb8aa3b, v116
	v_mul_f32_e32 v133, 0xbfb8aa3b, v114
	v_mul_f32_e32 v134, 0xbfb8aa3b, v119
	v_exp_f32_e32 v133, v133
	v_exp_f32_e32 v134, v134
	v_mul_f32_e32 v135, 0xbfb8aa3b, v115
	v_exp_f32_e32 v135, v135
	v_add_f32_e32 v133, 1.0, v133
	v_add_f32_e32 v134, 1.0, v134
	v_rcp_f32_e32 v133, v133
	v_rcp_f32_e32 v134, v134
	v_add_f32_e32 v132, 1.0, v146
	v_exp_f32_e32 v165, v165
	v_mul_f32_e32 v146, v114, v133
	v_mul_f32_e32 v133, v119, v134
	v_add_f32_e32 v134, 1.0, v135
	v_mul_f32_e32 v135, 0xbfb8aa3b, v120
	v_exp_f32_e32 v135, v135
	v_mul_f32_e32 v166, 0xbfb8aa3b, v117
	v_exp_f32_e32 v164, v164
	v_exp_f32_e32 v166, v166
	v_add_f32_e32 v135, 1.0, v135
	v_rcp_f32_e32 v132, v132
	v_rcp_f32_e32 v134, v134
	v_rcp_f32_e32 v135, v135
	v_add_f32_e32 v165, 1.0, v165
	v_add_f32_e32 v164, 1.0, v164
	v_rcp_f32_e32 v165, v165
	v_add_f32_e32 v166, 1.0, v166
	v_rcp_f32_e32 v164, v164
	v_rcp_f32_e32 v166, v166
	v_mul_f32_e32 v132, v118, v132
	v_mul_f32_e32 v134, v115, v134
	v_mul_f32_e32 v135, v120, v135
	v_mul_f32_e32 v165, v121, v165
	v_cvt_pk_bf16_f32 v132, v132, v133
	v_cvt_pk_bf16_f32 v133, v135, v165
	v_mul_f32_e32 v135, 0xbfb8aa3b, v110
	v_cvt_pk_bf16_f32 v134, v146, v134
	v_mul_f32_e32 v164, v116, v164
	v_mul_f32_e32 v166, v117, v166
	v_exp_f32_e32 v165, v135
	v_cvt_pk_bf16_f32 v135, v164, v166
	global_store_dwordx4 v[136:137], v[132:135], off offset:-768 nt
	v_mul_f32_e32 v146, 0xbfb8aa3b, v113
	v_mul_f32_e32 v137, 0xbfb8aa3b, v108
	v_mul_f32_e32 v133, 0xbfb8aa3b, v106
	v_mul_f32_e32 v134, 0xbfb8aa3b, v111
	v_exp_f32_e32 v133, v133
	v_exp_f32_e32 v134, v134
	v_mul_f32_e32 v135, 0xbfb8aa3b, v107
	v_exp_f32_e32 v135, v135
	v_add_f32_e32 v133, 1.0, v133
	v_add_f32_e32 v134, 1.0, v134
	v_rcp_f32_e32 v133, v133
	v_rcp_f32_e32 v134, v134
	v_exp_f32_e32 v146, v146
	v_exp_f32_e32 v137, v137
	v_mul_f32_e32 v136, v106, v133
	v_mul_f32_e32 v133, v111, v134
	v_add_f32_e32 v134, 1.0, v135
	v_mul_f32_e32 v135, 0xbfb8aa3b, v112
	v_exp_f32_e32 v135, v135
	v_mul_f32_e32 v164, 0xbfb8aa3b, v109
	v_exp_f32_e32 v164, v164
	v_add_f32_e32 v132, 1.0, v165
	v_rcp_f32_e32 v132, v132
	v_rcp_f32_e32 v134, v134
	v_add_f32_e32 v135, 1.0, v135
	v_add_f32_e32 v146, 1.0, v146
	v_rcp_f32_e32 v135, v135
	v_add_f32_e32 v137, 1.0, v137
	v_rcp_f32_e32 v146, v146
	v_rcp_f32_e32 v137, v137
	v_add_f32_e32 v164, 1.0, v164
	v_rcp_f32_e32 v164, v164
	v_mul_f32_e32 v132, v110, v132
	v_mul_f32_e32 v134, v107, v134
	v_mul_f32_e32 v135, v112, v135
	v_mul_f32_e32 v146, v113, v146
	v_cvt_pk_bf16_f32 v132, v132, v133
	v_cvt_pk_bf16_f32 v133, v135, v146
	v_cvt_pk_bf16_f32 v134, v136, v134
	v_mul_f32_e32 v136, 0xbfb8aa3b, v102
	s_mov_b32 s10, 0x1d000
	v_mul_f32_e32 v137, v108, v137
	v_exp_f32_e32 v146, v136
	v_add_co_u32_e32 v136, vcc, s10, v130
	v_mul_f32_e32 v164, v109, v164
	v_cvt_pk_bf16_f32 v135, v137, v164
	s_nop 0
	v_addc_co_u32_e32 v137, vcc, 0, v131, vcc
	global_store_dwordx4 v[136:137], v[132:135], off offset:3072 nt
	v_mul_f32_e32 v165, 0xbfb8aa3b, v105
	v_mul_f32_e32 v164, 0xbfb8aa3b, v100
	v_mul_f32_e32 v133, 0xbfb8aa3b, v98
	v_mul_f32_e32 v134, 0xbfb8aa3b, v103
	v_exp_f32_e32 v133, v133
	v_exp_f32_e32 v134, v134
	v_mul_f32_e32 v135, 0xbfb8aa3b, v99
	v_exp_f32_e32 v135, v135
	v_add_f32_e32 v133, 1.0, v133
	v_add_f32_e32 v134, 1.0, v134
	v_rcp_f32_e32 v133, v133
	v_rcp_f32_e32 v134, v134
	v_add_f32_e32 v132, 1.0, v146
	v_exp_f32_e32 v165, v165
	v_mul_f32_e32 v146, v98, v133
	v_mul_f32_e32 v133, v103, v134
	v_add_f32_e32 v134, 1.0, v135
	v_mul_f32_e32 v135, 0xbfb8aa3b, v104
	v_exp_f32_e32 v135, v135
	v_mul_f32_e32 v166, 0xbfb8aa3b, v101
	v_exp_f32_e32 v164, v164
	v_exp_f32_e32 v166, v166
	v_add_f32_e32 v135, 1.0, v135
	v_rcp_f32_e32 v132, v132
	v_rcp_f32_e32 v134, v134
	v_rcp_f32_e32 v135, v135
	v_add_f32_e32 v165, 1.0, v165
	v_add_f32_e32 v164, 1.0, v164
	v_rcp_f32_e32 v165, v165
	v_add_f32_e32 v166, 1.0, v166
	v_rcp_f32_e32 v164, v164
	v_rcp_f32_e32 v166, v166
	v_mul_f32_e32 v132, v102, v132
	v_mul_f32_e32 v134, v99, v134
	v_mul_f32_e32 v135, v104, v135
	v_mul_f32_e32 v165, v105, v165
	v_cvt_pk_bf16_f32 v132, v132, v133
	v_cvt_pk_bf16_f32 v133, v135, v165
	v_mul_f32_e32 v135, 0xbfb8aa3b, v94
	v_cvt_pk_bf16_f32 v134, v146, v134
	v_mul_f32_e32 v164, v100, v164
	v_mul_f32_e32 v166, v101, v166
	v_exp_f32_e32 v165, v135
	v_cvt_pk_bf16_f32 v135, v164, v166
	global_store_dwordx4 v[136:137], v[132:135], off offset:3328 nt
	v_mul_f32_e32 v146, 0xbfb8aa3b, v97
	v_mul_f32_e32 v137, 0xbfb8aa3b, v92
	v_mul_f32_e32 v133, 0xbfb8aa3b, v90
	v_mul_f32_e32 v134, 0xbfb8aa3b, v95
	v_exp_f32_e32 v133, v133
	v_exp_f32_e32 v134, v134
	v_mul_f32_e32 v135, 0xbfb8aa3b, v91
	v_exp_f32_e32 v135, v135
	v_add_f32_e32 v133, 1.0, v133
	v_add_f32_e32 v134, 1.0, v134
	v_rcp_f32_e32 v133, v133
	v_rcp_f32_e32 v134, v134
	v_exp_f32_e32 v146, v146
	v_exp_f32_e32 v137, v137
	v_mul_f32_e32 v136, v90, v133
	v_mul_f32_e32 v133, v95, v134
	v_add_f32_e32 v134, 1.0, v135
	v_mul_f32_e32 v135, 0xbfb8aa3b, v96
	v_exp_f32_e32 v135, v135
	v_mul_f32_e32 v164, 0xbfb8aa3b, v93
	v_exp_f32_e32 v164, v164
	v_add_f32_e32 v132, 1.0, v165
	v_rcp_f32_e32 v132, v132
	v_rcp_f32_e32 v134, v134
	v_add_f32_e32 v135, 1.0, v135
	v_add_f32_e32 v146, 1.0, v146
	v_rcp_f32_e32 v135, v135
	v_add_f32_e32 v137, 1.0, v137
	v_rcp_f32_e32 v146, v146
	v_rcp_f32_e32 v137, v137
	v_add_f32_e32 v164, 1.0, v164
	v_rcp_f32_e32 v164, v164
	v_mul_f32_e32 v132, v94, v132
	v_mul_f32_e32 v134, v91, v134
	v_mul_f32_e32 v135, v96, v135
	v_mul_f32_e32 v146, v97, v146
	v_cvt_pk_bf16_f32 v132, v132, v133
	v_cvt_pk_bf16_f32 v133, v135, v146
	v_cvt_pk_bf16_f32 v134, v136, v134
	v_mul_f32_e32 v136, 0xbfb8aa3b, v86
	s_mov_b32 s10, 0x3d000
	v_mul_f32_e32 v137, v92, v137
	v_exp_f32_e32 v146, v136
	v_add_co_u32_e32 v136, vcc, s10, v130
	v_mul_f32_e32 v164, v93, v164
	v_cvt_pk_bf16_f32 v135, v137, v164
	s_nop 0
	v_addc_co_u32_e32 v137, vcc, 0, v131, vcc
	global_store_dwordx4 v[136:137], v[132:135], off offset:3072 nt
	v_mul_f32_e32 v165, 0xbfb8aa3b, v89
	v_mul_f32_e32 v164, 0xbfb8aa3b, v84
	v_mul_f32_e32 v133, 0xbfb8aa3b, v82
	v_mul_f32_e32 v134, 0xbfb8aa3b, v87
	v_exp_f32_e32 v133, v133
	v_exp_f32_e32 v134, v134
	v_mul_f32_e32 v135, 0xbfb8aa3b, v83
	v_exp_f32_e32 v135, v135
	v_add_f32_e32 v133, 1.0, v133
	v_add_f32_e32 v134, 1.0, v134
	v_rcp_f32_e32 v133, v133
	v_rcp_f32_e32 v134, v134
	v_add_f32_e32 v132, 1.0, v146
	v_exp_f32_e32 v165, v165
	v_mul_f32_e32 v146, v82, v133
	v_mul_f32_e32 v133, v87, v134
	v_add_f32_e32 v134, 1.0, v135
	v_mul_f32_e32 v135, 0xbfb8aa3b, v88
	v_exp_f32_e32 v135, v135
	v_mul_f32_e32 v166, 0xbfb8aa3b, v85
	v_exp_f32_e32 v164, v164
	v_exp_f32_e32 v166, v166
	v_add_f32_e32 v135, 1.0, v135
	v_rcp_f32_e32 v132, v132
	v_rcp_f32_e32 v134, v134
	v_rcp_f32_e32 v135, v135
	v_add_f32_e32 v165, 1.0, v165
	v_add_f32_e32 v164, 1.0, v164
	v_rcp_f32_e32 v165, v165
	v_add_f32_e32 v166, 1.0, v166
	v_rcp_f32_e32 v164, v164
	v_rcp_f32_e32 v166, v166
	v_mul_f32_e32 v132, v86, v132
	v_mul_f32_e32 v134, v83, v134
	v_mul_f32_e32 v135, v88, v135
	v_mul_f32_e32 v165, v89, v165
	v_cvt_pk_bf16_f32 v132, v132, v133
	v_cvt_pk_bf16_f32 v133, v135, v165
	v_mul_f32_e32 v135, 0xbfb8aa3b, v78
	v_cvt_pk_bf16_f32 v134, v146, v134
	v_mul_f32_e32 v164, v84, v164
	v_mul_f32_e32 v166, v85, v166
	v_exp_f32_e32 v165, v135
	v_cvt_pk_bf16_f32 v135, v164, v166
	global_store_dwordx4 v[136:137], v[132:135], off offset:3328 nt
	v_mul_f32_e32 v146, 0xbfb8aa3b, v81
	v_mul_f32_e32 v137, 0xbfb8aa3b, v76
	v_mul_f32_e32 v133, 0xbfb8aa3b, v74
	v_mul_f32_e32 v134, 0xbfb8aa3b, v79
	v_exp_f32_e32 v133, v133
	v_exp_f32_e32 v134, v134
	v_mul_f32_e32 v135, 0xbfb8aa3b, v75
	v_exp_f32_e32 v135, v135
	v_add_f32_e32 v133, 1.0, v133
	v_add_f32_e32 v134, 1.0, v134
	v_rcp_f32_e32 v133, v133
	v_rcp_f32_e32 v134, v134
	v_exp_f32_e32 v146, v146
	v_exp_f32_e32 v137, v137
	v_mul_f32_e32 v136, v74, v133
	v_mul_f32_e32 v133, v79, v134
	v_add_f32_e32 v134, 1.0, v135
	v_mul_f32_e32 v135, 0xbfb8aa3b, v80
	v_exp_f32_e32 v135, v135
	v_mul_f32_e32 v164, 0xbfb8aa3b, v77
	v_exp_f32_e32 v164, v164
	v_add_f32_e32 v132, 1.0, v165
	v_rcp_f32_e32 v132, v132
	v_rcp_f32_e32 v134, v134
	v_add_f32_e32 v135, 1.0, v135
	v_add_f32_e32 v146, 1.0, v146
	v_rcp_f32_e32 v135, v135
	v_add_f32_e32 v137, 1.0, v137
	v_rcp_f32_e32 v146, v146
	v_rcp_f32_e32 v137, v137
	v_add_f32_e32 v164, 1.0, v164
	v_rcp_f32_e32 v164, v164
	v_mul_f32_e32 v132, v78, v132
	v_mul_f32_e32 v134, v75, v134
	v_mul_f32_e32 v135, v80, v135
	v_mul_f32_e32 v146, v81, v146
	v_cvt_pk_bf16_f32 v132, v132, v133
	v_cvt_pk_bf16_f32 v133, v135, v146
	v_cvt_pk_bf16_f32 v134, v136, v134
	v_mul_f32_e32 v136, 0xbfb8aa3b, v70
	s_mov_b32 s10, 0x5d000
	v_mul_f32_e32 v137, v76, v137
	v_exp_f32_e32 v146, v136
	v_add_co_u32_e32 v136, vcc, s10, v130
	v_mul_f32_e32 v164, v77, v164
	v_cvt_pk_bf16_f32 v135, v137, v164
	s_nop 0
	v_addc_co_u32_e32 v137, vcc, 0, v131, vcc
	global_store_dwordx4 v[136:137], v[132:135], off offset:3072 nt
	v_mul_f32_e32 v165, 0xbfb8aa3b, v73
	v_mul_f32_e32 v164, 0xbfb8aa3b, v68
	v_mul_f32_e32 v133, 0xbfb8aa3b, v66
	v_mul_f32_e32 v134, 0xbfb8aa3b, v71
	v_exp_f32_e32 v133, v133
	v_exp_f32_e32 v134, v134
	v_mul_f32_e32 v135, 0xbfb8aa3b, v67
	v_exp_f32_e32 v135, v135
	v_add_f32_e32 v133, 1.0, v133
	v_add_f32_e32 v134, 1.0, v134
	v_rcp_f32_e32 v133, v133
	v_rcp_f32_e32 v134, v134
	v_add_f32_e32 v132, 1.0, v146
	v_exp_f32_e32 v165, v165
	v_mul_f32_e32 v146, v66, v133
	v_mul_f32_e32 v133, v71, v134
	v_add_f32_e32 v134, 1.0, v135
	v_mul_f32_e32 v135, 0xbfb8aa3b, v72
	v_exp_f32_e32 v135, v135
	v_mul_f32_e32 v166, 0xbfb8aa3b, v69
	v_exp_f32_e32 v164, v164
	v_exp_f32_e32 v166, v166
	v_add_f32_e32 v135, 1.0, v135
	v_rcp_f32_e32 v132, v132
	v_rcp_f32_e32 v134, v134
	v_rcp_f32_e32 v135, v135
	v_add_f32_e32 v165, 1.0, v165
	v_add_f32_e32 v164, 1.0, v164
	v_rcp_f32_e32 v165, v165
	v_add_f32_e32 v166, 1.0, v166
	v_rcp_f32_e32 v164, v164
	v_rcp_f32_e32 v166, v166
	v_mul_f32_e32 v132, v70, v132
	v_mul_f32_e32 v134, v67, v134
	v_mul_f32_e32 v135, v72, v135
	v_mul_f32_e32 v165, v73, v165
	v_cvt_pk_bf16_f32 v132, v132, v133
	v_cvt_pk_bf16_f32 v133, v135, v165
	v_mul_f32_e32 v135, 0xbfb8aa3b, v62
	v_cvt_pk_bf16_f32 v134, v146, v134
	v_mul_f32_e32 v164, v68, v164
	v_mul_f32_e32 v166, v69, v166
	v_exp_f32_e32 v165, v135
	v_cvt_pk_bf16_f32 v135, v164, v166
	global_store_dwordx4 v[136:137], v[132:135], off offset:3328 nt
	v_mul_f32_e32 v146, 0xbfb8aa3b, v65
	v_mul_f32_e32 v137, 0xbfb8aa3b, v60
	v_mul_f32_e32 v133, 0xbfb8aa3b, v58
	v_mul_f32_e32 v134, 0xbfb8aa3b, v63
	v_exp_f32_e32 v133, v133
	v_exp_f32_e32 v134, v134
	v_mul_f32_e32 v135, 0xbfb8aa3b, v59
	v_exp_f32_e32 v135, v135
	v_add_f32_e32 v133, 1.0, v133
	v_add_f32_e32 v134, 1.0, v134
	v_rcp_f32_e32 v133, v133
	v_rcp_f32_e32 v134, v134
	v_exp_f32_e32 v146, v146
	v_exp_f32_e32 v137, v137
	v_mul_f32_e32 v136, v58, v133
	v_mul_f32_e32 v133, v63, v134
	v_add_f32_e32 v134, 1.0, v135
	v_mul_f32_e32 v135, 0xbfb8aa3b, v64
	v_exp_f32_e32 v135, v135
	v_mul_f32_e32 v164, 0xbfb8aa3b, v61
	v_exp_f32_e32 v164, v164
	v_add_f32_e32 v132, 1.0, v165
	v_rcp_f32_e32 v132, v132
	v_rcp_f32_e32 v134, v134
	v_add_f32_e32 v135, 1.0, v135
	v_add_f32_e32 v146, 1.0, v146
	v_rcp_f32_e32 v135, v135
	v_add_f32_e32 v137, 1.0, v137
	v_rcp_f32_e32 v146, v146
	v_rcp_f32_e32 v137, v137
	v_add_f32_e32 v164, 1.0, v164
	v_rcp_f32_e32 v164, v164
	v_mul_f32_e32 v132, v62, v132
	v_mul_f32_e32 v134, v59, v134
	v_mul_f32_e32 v135, v64, v135
	v_mul_f32_e32 v146, v65, v146
	v_cvt_pk_bf16_f32 v132, v132, v133
	v_cvt_pk_bf16_f32 v133, v135, v146
	v_cvt_pk_bf16_f32 v134, v136, v134
	v_mul_f32_e32 v136, 0xbfb8aa3b, v54
	s_mov_b32 s10, 0xfd000
	v_mul_f32_e32 v137, v60, v137
	v_exp_f32_e32 v146, v136
	v_add_co_u32_e32 v136, vcc, s10, v130
	v_mul_f32_e32 v164, v61, v164
	v_cvt_pk_bf16_f32 v135, v137, v164
	s_nop 0
	v_addc_co_u32_e32 v137, vcc, 0, v131, vcc
	global_store_dwordx4 v[136:137], v[132:135], off offset:3072 nt
	v_mul_f32_e32 v165, 0xbfb8aa3b, v57
	v_mul_f32_e32 v164, 0xbfb8aa3b, v52
	v_mul_f32_e32 v133, 0xbfb8aa3b, v50
	v_mul_f32_e32 v134, 0xbfb8aa3b, v55
	v_exp_f32_e32 v133, v133
	v_exp_f32_e32 v134, v134
	v_mul_f32_e32 v135, 0xbfb8aa3b, v51
	v_exp_f32_e32 v135, v135
	v_add_f32_e32 v133, 1.0, v133
	v_add_f32_e32 v134, 1.0, v134
	v_rcp_f32_e32 v133, v133
	v_rcp_f32_e32 v134, v134
	v_add_f32_e32 v132, 1.0, v146
	v_exp_f32_e32 v165, v165
	v_mul_f32_e32 v146, v50, v133
	v_mul_f32_e32 v133, v55, v134
	v_add_f32_e32 v134, 1.0, v135
	v_mul_f32_e32 v135, 0xbfb8aa3b, v56
	v_exp_f32_e32 v135, v135
	v_mul_f32_e32 v166, 0xbfb8aa3b, v53
	v_exp_f32_e32 v164, v164
	v_exp_f32_e32 v166, v166
	v_add_f32_e32 v135, 1.0, v135
	v_rcp_f32_e32 v132, v132
	v_rcp_f32_e32 v134, v134
	v_rcp_f32_e32 v135, v135
	v_add_f32_e32 v165, 1.0, v165
	v_add_f32_e32 v164, 1.0, v164
	v_rcp_f32_e32 v165, v165
	v_add_f32_e32 v166, 1.0, v166
	v_rcp_f32_e32 v164, v164
	v_rcp_f32_e32 v166, v166
	v_mul_f32_e32 v132, v54, v132
	v_mul_f32_e32 v134, v51, v134
	v_mul_f32_e32 v135, v56, v135
	v_mul_f32_e32 v165, v57, v165
	v_cvt_pk_bf16_f32 v132, v132, v133
	v_cvt_pk_bf16_f32 v133, v135, v165
	v_mul_f32_e32 v135, 0xbfb8aa3b, v46
	v_cvt_pk_bf16_f32 v134, v146, v134
	v_mul_f32_e32 v164, v52, v164
	v_mul_f32_e32 v166, v53, v166
	v_exp_f32_e32 v165, v135
	v_cvt_pk_bf16_f32 v135, v164, v166
	global_store_dwordx4 v[136:137], v[132:135], off offset:3328 nt
	v_mul_f32_e32 v146, 0xbfb8aa3b, v49
	v_mul_f32_e32 v137, 0xbfb8aa3b, v44
	v_mul_f32_e32 v133, 0xbfb8aa3b, v42
	v_mul_f32_e32 v134, 0xbfb8aa3b, v47
	v_exp_f32_e32 v133, v133
	v_exp_f32_e32 v134, v134
	v_mul_f32_e32 v135, 0xbfb8aa3b, v43
	v_exp_f32_e32 v135, v135
	v_add_f32_e32 v133, 1.0, v133
	v_add_f32_e32 v134, 1.0, v134
	v_rcp_f32_e32 v133, v133
	v_rcp_f32_e32 v134, v134
	v_exp_f32_e32 v146, v146
	v_exp_f32_e32 v137, v137
	v_mul_f32_e32 v136, v42, v133
	v_mul_f32_e32 v133, v47, v134
	v_add_f32_e32 v134, 1.0, v135
	v_mul_f32_e32 v135, 0xbfb8aa3b, v48
	v_exp_f32_e32 v135, v135
	v_mul_f32_e32 v164, 0xbfb8aa3b, v45
	v_exp_f32_e32 v164, v164
	v_add_f32_e32 v132, 1.0, v165
	v_rcp_f32_e32 v132, v132
	v_rcp_f32_e32 v134, v134
	v_add_f32_e32 v135, 1.0, v135
	v_add_f32_e32 v146, 1.0, v146
	v_rcp_f32_e32 v135, v135
	v_add_f32_e32 v137, 1.0, v137
	v_rcp_f32_e32 v146, v146
	v_rcp_f32_e32 v137, v137
	v_add_f32_e32 v164, 1.0, v164
	v_rcp_f32_e32 v164, v164
	v_mul_f32_e32 v132, v46, v132
	v_mul_f32_e32 v134, v43, v134
	v_mul_f32_e32 v135, v48, v135
	v_mul_f32_e32 v146, v49, v146
	v_cvt_pk_bf16_f32 v132, v132, v133
	v_cvt_pk_bf16_f32 v133, v135, v146
	v_cvt_pk_bf16_f32 v134, v136, v134
	v_mul_f32_e32 v136, 0xbfb8aa3b, v38
	s_mov_b32 s10, 0x11d000
	v_mul_f32_e32 v137, v44, v137
	v_exp_f32_e32 v146, v136
	v_add_co_u32_e32 v136, vcc, s10, v130
	v_mul_f32_e32 v164, v45, v164
	v_cvt_pk_bf16_f32 v135, v137, v164
	s_nop 0
	v_addc_co_u32_e32 v137, vcc, 0, v131, vcc
	global_store_dwordx4 v[136:137], v[132:135], off offset:3072 nt
	v_mul_f32_e32 v165, 0xbfb8aa3b, v41
	v_mul_f32_e32 v164, 0xbfb8aa3b, v36
	v_mul_f32_e32 v133, 0xbfb8aa3b, v34
	v_mul_f32_e32 v134, 0xbfb8aa3b, v39
	v_exp_f32_e32 v133, v133
	v_exp_f32_e32 v134, v134
	v_mul_f32_e32 v135, 0xbfb8aa3b, v35
	v_exp_f32_e32 v135, v135
	v_add_f32_e32 v133, 1.0, v133
	v_add_f32_e32 v134, 1.0, v134
	v_rcp_f32_e32 v133, v133
	v_rcp_f32_e32 v134, v134
	v_add_f32_e32 v132, 1.0, v146
	v_exp_f32_e32 v165, v165
	v_mul_f32_e32 v146, v34, v133
	v_mul_f32_e32 v133, v39, v134
	v_add_f32_e32 v134, 1.0, v135
	v_mul_f32_e32 v135, 0xbfb8aa3b, v40
	v_exp_f32_e32 v135, v135
	v_mul_f32_e32 v166, 0xbfb8aa3b, v37
	v_exp_f32_e32 v164, v164
	v_exp_f32_e32 v166, v166
	v_add_f32_e32 v135, 1.0, v135
	v_rcp_f32_e32 v132, v132
	v_rcp_f32_e32 v134, v134
	v_rcp_f32_e32 v135, v135
	v_add_f32_e32 v165, 1.0, v165
	v_add_f32_e32 v164, 1.0, v164
	v_rcp_f32_e32 v165, v165
	v_add_f32_e32 v166, 1.0, v166
	v_rcp_f32_e32 v164, v164
	v_rcp_f32_e32 v166, v166
	v_mul_f32_e32 v132, v38, v132
	v_mul_f32_e32 v134, v35, v134
	v_mul_f32_e32 v135, v40, v135
	v_mul_f32_e32 v165, v41, v165
	v_cvt_pk_bf16_f32 v132, v132, v133
	v_cvt_pk_bf16_f32 v133, v135, v165
	v_mul_f32_e32 v135, 0xbfb8aa3b, v30
	v_cvt_pk_bf16_f32 v134, v146, v134
	v_mul_f32_e32 v164, v36, v164
	v_mul_f32_e32 v166, v37, v166
	v_exp_f32_e32 v165, v135
	v_cvt_pk_bf16_f32 v135, v164, v166
	global_store_dwordx4 v[136:137], v[132:135], off offset:3328 nt
	v_mul_f32_e32 v146, 0xbfb8aa3b, v33
	v_mul_f32_e32 v137, 0xbfb8aa3b, v28
	v_mul_f32_e32 v133, 0xbfb8aa3b, v26
	v_mul_f32_e32 v134, 0xbfb8aa3b, v31
	v_exp_f32_e32 v133, v133
	v_exp_f32_e32 v134, v134
	v_mul_f32_e32 v135, 0xbfb8aa3b, v27
	v_exp_f32_e32 v135, v135
	v_add_f32_e32 v133, 1.0, v133
	v_add_f32_e32 v134, 1.0, v134
	v_rcp_f32_e32 v133, v133
	v_rcp_f32_e32 v134, v134
	v_exp_f32_e32 v146, v146
	v_exp_f32_e32 v137, v137
	v_mul_f32_e32 v136, v26, v133
	v_mul_f32_e32 v133, v31, v134
	v_add_f32_e32 v134, 1.0, v135
	v_mul_f32_e32 v135, 0xbfb8aa3b, v32
	v_exp_f32_e32 v135, v135
	v_mul_f32_e32 v164, 0xbfb8aa3b, v29
	v_exp_f32_e32 v164, v164
	v_add_f32_e32 v132, 1.0, v165
	v_rcp_f32_e32 v132, v132
	v_rcp_f32_e32 v134, v134
	v_add_f32_e32 v135, 1.0, v135
	v_add_f32_e32 v146, 1.0, v146
	v_rcp_f32_e32 v135, v135
	v_add_f32_e32 v137, 1.0, v137
	v_rcp_f32_e32 v146, v146
	v_rcp_f32_e32 v137, v137
	v_add_f32_e32 v164, 1.0, v164
	v_rcp_f32_e32 v164, v164
	v_mul_f32_e32 v132, v30, v132
	v_mul_f32_e32 v134, v27, v134
	v_mul_f32_e32 v135, v32, v135
	v_mul_f32_e32 v146, v33, v146
	v_cvt_pk_bf16_f32 v132, v132, v133
	v_cvt_pk_bf16_f32 v133, v135, v146
	v_cvt_pk_bf16_f32 v134, v136, v134
	v_mul_f32_e32 v136, 0xbfb8aa3b, v22
	s_mov_b32 s10, 0x13d000
	v_mul_f32_e32 v137, v28, v137
	v_exp_f32_e32 v146, v136
	v_add_co_u32_e32 v136, vcc, s10, v130
	v_mul_f32_e32 v164, v29, v164
	v_cvt_pk_bf16_f32 v135, v137, v164
	s_nop 0
	v_addc_co_u32_e32 v137, vcc, 0, v131, vcc
	global_store_dwordx4 v[136:137], v[132:135], off offset:3072 nt
	v_mul_f32_e32 v165, 0xbfb8aa3b, v25
	v_mul_f32_e32 v164, 0xbfb8aa3b, v20
	v_mul_f32_e32 v133, 0xbfb8aa3b, v18
	v_mul_f32_e32 v134, 0xbfb8aa3b, v23
	v_exp_f32_e32 v133, v133
	v_exp_f32_e32 v134, v134
	v_mul_f32_e32 v135, 0xbfb8aa3b, v19
	v_exp_f32_e32 v135, v135
	v_add_f32_e32 v133, 1.0, v133
	v_add_f32_e32 v134, 1.0, v134
	v_rcp_f32_e32 v133, v133
	v_rcp_f32_e32 v134, v134
	v_add_f32_e32 v132, 1.0, v146
	v_exp_f32_e32 v165, v165
	v_mul_f32_e32 v146, v18, v133
	v_mul_f32_e32 v133, v23, v134
	v_add_f32_e32 v134, 1.0, v135
	v_mul_f32_e32 v135, 0xbfb8aa3b, v24
	v_exp_f32_e32 v135, v135
	v_mul_f32_e32 v166, 0xbfb8aa3b, v21
	v_exp_f32_e32 v164, v164
	v_exp_f32_e32 v166, v166
	v_add_f32_e32 v135, 1.0, v135
	v_rcp_f32_e32 v132, v132
	v_rcp_f32_e32 v134, v134
	v_rcp_f32_e32 v135, v135
	v_add_f32_e32 v165, 1.0, v165
	v_add_f32_e32 v164, 1.0, v164
	v_rcp_f32_e32 v165, v165
	v_add_f32_e32 v166, 1.0, v166
	v_rcp_f32_e32 v164, v164
	v_rcp_f32_e32 v166, v166
	v_mul_f32_e32 v132, v22, v132
	v_mul_f32_e32 v134, v19, v134
	v_mul_f32_e32 v135, v24, v135
	v_mul_f32_e32 v165, v25, v165
	v_cvt_pk_bf16_f32 v132, v132, v133
	v_cvt_pk_bf16_f32 v133, v135, v165
	v_mul_f32_e32 v135, 0xbfb8aa3b, v14
	v_cvt_pk_bf16_f32 v134, v146, v134
	v_mul_f32_e32 v164, v20, v164
	v_mul_f32_e32 v166, v21, v166
	v_exp_f32_e32 v165, v135
	v_cvt_pk_bf16_f32 v135, v164, v166
	global_store_dwordx4 v[136:137], v[132:135], off offset:3328 nt
	v_mul_f32_e32 v146, 0xbfb8aa3b, v17
	v_mul_f32_e32 v137, 0xbfb8aa3b, v12
	v_mul_f32_e32 v133, 0xbfb8aa3b, v10
	v_mul_f32_e32 v134, 0xbfb8aa3b, v15
	v_exp_f32_e32 v133, v133
	v_exp_f32_e32 v134, v134
	v_mul_f32_e32 v135, 0xbfb8aa3b, v11
	v_exp_f32_e32 v135, v135
	v_add_f32_e32 v133, 1.0, v133
	v_add_f32_e32 v134, 1.0, v134
	v_rcp_f32_e32 v133, v133
	v_rcp_f32_e32 v134, v134
	v_exp_f32_e32 v146, v146
	v_exp_f32_e32 v137, v137
	v_mul_f32_e32 v136, v10, v133
	v_mul_f32_e32 v133, v15, v134
	v_add_f32_e32 v134, 1.0, v135
	v_mul_f32_e32 v135, 0xbfb8aa3b, v16
	v_exp_f32_e32 v135, v135
	v_mul_f32_e32 v164, 0xbfb8aa3b, v13
	v_exp_f32_e32 v164, v164
	v_add_f32_e32 v132, 1.0, v165
	v_rcp_f32_e32 v132, v132
	v_rcp_f32_e32 v134, v134
	v_add_f32_e32 v135, 1.0, v135
	v_add_f32_e32 v146, 1.0, v146
	v_rcp_f32_e32 v135, v135
	v_add_f32_e32 v137, 1.0, v137
	v_rcp_f32_e32 v146, v146
	v_rcp_f32_e32 v137, v137
	v_add_f32_e32 v164, 1.0, v164
	v_rcp_f32_e32 v164, v164
	v_mul_f32_e32 v132, v14, v132
	v_mul_f32_e32 v134, v11, v134
	v_mul_f32_e32 v135, v16, v135
	v_mul_f32_e32 v146, v17, v146
	v_cvt_pk_bf16_f32 v132, v132, v133
	v_cvt_pk_bf16_f32 v133, v135, v146
	v_cvt_pk_bf16_f32 v134, v136, v134
	v_mul_f32_e32 v136, 0xbfb8aa3b, v6
	s_mov_b32 s10, 0x15d000
	v_mul_f32_e32 v137, v12, v137
	v_exp_f32_e32 v146, v136
	v_add_co_u32_e32 v136, vcc, s10, v130
	v_mul_f32_e32 v164, v13, v164
	v_cvt_pk_bf16_f32 v135, v137, v164
	s_nop 0
	v_addc_co_u32_e32 v137, vcc, 0, v131, vcc
	global_store_dwordx4 v[136:137], v[132:135], off offset:3072 nt
	v_mul_f32_e32 v131, 0xbfb8aa3b, v2
	v_exp_f32_e32 v131, v131
	v_mul_f32_e32 v132, 0xbfb8aa3b, v7
	v_exp_f32_e32 v132, v132
	v_mul_f32_e32 v133, 0xbfb8aa3b, v3
	v_add_f32_e32 v131, 1.0, v131
	v_rcp_f32_e32 v131, v131
	v_add_f32_e32 v132, 1.0, v132
	v_rcp_f32_e32 v132, v132
	v_exp_f32_e32 v133, v133
	v_mul_f32_e32 v134, v2, v131
	v_add_f32_e32 v130, 1.0, v146
	v_mul_f32_e32 v131, v7, v132
	v_add_f32_e32 v132, 1.0, v133
	v_mul_f32_e32 v133, 0xbfb8aa3b, v8
	v_exp_f32_e32 v133, v133
	v_mul_f32_e32 v135, 0xbfb8aa3b, v4
	v_mul_f32_e32 v146, 0xbfb8aa3b, v9
	v_mul_f32_e32 v164, 0xbfb8aa3b, v5
	v_exp_f32_e32 v135, v135
	v_exp_f32_e32 v146, v146
	v_exp_f32_e32 v164, v164
	v_add_f32_e32 v133, 1.0, v133
	v_rcp_f32_e32 v130, v130
	v_rcp_f32_e32 v132, v132
	v_rcp_f32_e32 v133, v133
	v_add_f32_e32 v135, 1.0, v135
	v_add_f32_e32 v146, 1.0, v146
	v_add_f32_e32 v164, 1.0, v164
	v_rcp_f32_e32 v135, v135
	v_rcp_f32_e32 v146, v146
	v_rcp_f32_e32 v164, v164
	v_mul_f32_e32 v130, v6, v130
	v_mul_f32_e32 v132, v3, v132
	v_mul_f32_e32 v133, v8, v133
	v_mul_f32_e32 v135, v4, v135
	v_mul_f32_e32 v146, v9, v146
	v_mul_f32_e32 v164, v5, v164
	v_cvt_pk_bf16_f32 v130, v130, v131
	v_cvt_pk_bf16_f32 v131, v133, v146
	v_cvt_pk_bf16_f32 v132, v134, v132
	v_cvt_pk_bf16_f32 v133, v135, v164
	global_store_dwordx4 v[136:137], v[130:133], off offset:3328 nt

.LBB0_499:
	s_andn2_b64 vcc, exec, s[14:15]
	s_cbranch_vccnz .LBB0_519
	v_mul_f32_e32 v130, v127, v127
	v_mul_f32_e32 v131, v129, v129
	v_fmac_f32_e32 v130, v126, v126
	v_fmac_f32_e32 v131, v128, v128
	v_add_f32_e32 v130, v130, v131
	v_mul_f32_e32 v131, v123, v123
	v_fmac_f32_e32 v131, v122, v122
	v_add_f32_e32 v130, v130, v131
	v_mul_f32_e32 v131, v125, v125
	v_readlane_b32 s14, v254, 11
	v_fmac_f32_e32 v131, v124, v124
	v_readlane_b32 s15, v254, 12
	v_add_f32_e32 v164, v131, v130
	s_movk_i32 s10, 0xc00
	v_mov_b64_e32 v[130:131], s[14:15]
	v_mad_u64_u32 v[130:131], s[14:15], v160, s10, v[130:131]
	v_mad_i32_i24 v131, v161, s10, v131
	s_lshl_b32 s24, s16, 9
	v_lshl_add_u64 v[136:137], v[130:131], 0, s[24:25]
	v_lshlrev_b32_e32 v146, 1, v150
	v_lshl_add_u64 v[136:137], v[136:137], 0, v[146:147]
	v_add_co_u32_e32 v136, vcc, s1, v136
	v_cvt_pk_bf16_f32 v132, v126, v127
	v_cvt_pk_bf16_f32 v133, v128, v129
	v_cvt_pk_bf16_f32 v134, v122, v123
	v_cvt_pk_bf16_f32 v135, v124, v125
	s_nop 1
	v_addc_co_u32_e32 v137, vcc, -1, v137, vcc
	global_store_dwordx4 v[136:137], v[132:135], off offset:-2048 nt
	s_nop 1
	v_mul_f32_e32 v132, v119, v119
	v_mul_f32_e32 v133, v121, v121
	v_fmac_f32_e32 v132, v118, v118
	v_fmac_f32_e32 v133, v120, v120
	v_add_f32_e32 v132, v132, v133
	v_mul_f32_e32 v133, v115, v115
	v_fmac_f32_e32 v133, v114, v114
	v_add_f32_e32 v132, v132, v133
	v_mul_f32_e32 v133, v117, v117
	v_fmac_f32_e32 v133, v116, v116
	v_add_f32_e32 v132, v133, v132
	v_add_f32_e32 v164, v164, v132
	v_cvt_pk_bf16_f32 v132, v118, v119
	v_cvt_pk_bf16_f32 v133, v120, v121
	v_cvt_pk_bf16_f32 v134, v114, v115
	v_cvt_pk_bf16_f32 v135, v116, v117
	global_store_dwordx4 v[136:137], v[132:135], off offset:-1792 nt
	s_nop 1
	v_and_b32_e32 v133, 64, v194
	v_xor_b32_e32 v132, 16, v194
	v_add_u32_e32 v133, 64, v133
	v_cmp_lt_i32_e32 vcc, v132, v133
	v_xor_b32_e32 v135, 32, v194
	s_nop 0
	v_cndmask_b32_e32 v132, v194, v132, vcc
	v_lshlrev_b32_e32 v132, 2, v132
	ds_bpermute_b32 v134, v132, v164
	v_cmp_lt_i32_e32 vcc, v135, v133
	s_waitcnt lgkmcnt(0)
	v_add_f32_e32 v134, v164, v134
	v_cndmask_b32_e32 v133, v194, v135, vcc
	v_lshlrev_b32_e32 v133, 2, v133
	ds_bpermute_b32 v135, v133, v134
	s_and_saveexec_b64 s[14:15], s[8:9]
	s_cbranch_execz .LBB0_502
	s_waitcnt lgkmcnt(0)
	v_add_f32_e32 v134, v134, v135
	ds_write_b32 v180, v134
.LBB0_502:
	s_or_b64 exec, exec, s[14:15]
	v_mul_f32_e32 v134, v111, v111
	s_waitcnt lgkmcnt(0)
	v_mul_f32_e32 v135, v113, v113
	s_lshl_b32 s10, s16, 8
	v_fmac_f32_e32 v134, v110, v110
	v_fmac_f32_e32 v135, v112, v112
	s_mov_b64 s[14:15], 0xc000
	v_add_f32_e32 v134, v134, v135
	v_mul_f32_e32 v135, v107, v107
	v_lshl_add_u64 v[130:131], v[130:131], 0, s[14:15]
	s_lshl_b32 s24, s10, 1
	v_fmac_f32_e32 v135, v106, v106
	v_lshl_add_u64 v[164:165], v[130:131], 0, s[24:25]
	v_add_f32_e32 v134, v134, v135
	v_mul_f32_e32 v135, v109, v109
	v_lshl_add_u64 v[164:165], v[164:165], 0, v[146:147]
	v_fmac_f32_e32 v135, v108, v108
	v_add_co_u32_e32 v164, vcc, s1, v164
	v_add_f32_e32 v166, v135, v134
	v_cvt_pk_bf16_f32 v134, v110, v111
	v_cvt_pk_bf16_f32 v135, v112, v113
	s_nop 0
	v_addc_co_u32_e32 v165, vcc, -1, v165, vcc
	v_cvt_pk_bf16_f32 v136, v106, v107
	v_cvt_pk_bf16_f32 v137, v108, v109
	global_store_dwordx4 v[164:165], v[134:137], off offset:-2048 nt
	s_nop 1
	v_mul_f32_e32 v134, v103, v103
	v_mul_f32_e32 v135, v105, v105
	v_fmac_f32_e32 v134, v102, v102
	v_fmac_f32_e32 v135, v104, v104
	v_add_f32_e32 v134, v134, v135
	v_mul_f32_e32 v135, v99, v99
	v_fmac_f32_e32 v135, v98, v98
	v_add_f32_e32 v134, v134, v135
	v_mul_f32_e32 v135, v101, v101
	v_fmac_f32_e32 v135, v100, v100
	v_add_f32_e32 v134, v135, v134
	v_add_f32_e32 v166, v166, v134
	v_cvt_pk_bf16_f32 v134, v102, v103
	v_cvt_pk_bf16_f32 v135, v104, v105
	v_cvt_pk_bf16_f32 v136, v98, v99
	v_cvt_pk_bf16_f32 v137, v100, v101
	global_store_dwordx4 v[164:165], v[134:137], off offset:-1792 nt
	ds_bpermute_b32 v134, v132, v166
	s_waitcnt lgkmcnt(0)
	v_add_f32_e32 v134, v166, v134
	ds_bpermute_b32 v135, v133, v134
	s_and_saveexec_b64 s[14:15], s[8:9]
	s_cbranch_execz .LBB0_504
	s_waitcnt lgkmcnt(0)
	v_add_f32_e32 v134, v134, v135
	ds_write_b32 v181, v134
.LBB0_504:
	s_or_b64 exec, exec, s[14:15]
	v_mul_f32_e32 v134, v95, v95
	s_waitcnt lgkmcnt(0)
	v_mul_f32_e32 v135, v97, v97
	v_fmac_f32_e32 v134, v94, v94
	v_fmac_f32_e32 v135, v96, v96
	s_mov_b64 s[14:15], 0xc000
	v_add_f32_e32 v134, v134, v135
	v_mul_f32_e32 v135, v91, v91
	v_lshl_add_u64 v[130:131], v[130:131], 0, s[14:15]
	v_fmac_f32_e32 v135, v90, v90
	v_lshl_add_u64 v[164:165], v[130:131], 0, s[24:25]
	v_add_f32_e32 v134, v134, v135
	v_mul_f32_e32 v135, v93, v93
	v_lshl_add_u64 v[164:165], v[164:165], 0, v[146:147]
	v_fmac_f32_e32 v135, v92, v92
	v_add_co_u32_e32 v164, vcc, s1, v164
	v_add_f32_e32 v166, v135, v134
	v_cvt_pk_bf16_f32 v134, v94, v95
	v_cvt_pk_bf16_f32 v135, v96, v97
	s_nop 0
	v_addc_co_u32_e32 v165, vcc, -1, v165, vcc
	v_cvt_pk_bf16_f32 v136, v90, v91
	v_cvt_pk_bf16_f32 v137, v92, v93
	global_store_dwordx4 v[164:165], v[134:137], off offset:-2048 nt
	s_nop 1
	v_mul_f32_e32 v134, v87, v87
	v_mul_f32_e32 v135, v89, v89
	v_fmac_f32_e32 v134, v86, v86
	v_fmac_f32_e32 v135, v88, v88
	v_add_f32_e32 v134, v134, v135
	v_mul_f32_e32 v135, v83, v83
	v_fmac_f32_e32 v135, v82, v82
	v_add_f32_e32 v134, v134, v135
	v_mul_f32_e32 v135, v85, v85
	v_fmac_f32_e32 v135, v84, v84
	v_add_f32_e32 v134, v135, v134
	v_add_f32_e32 v166, v166, v134
	v_cvt_pk_bf16_f32 v134, v86, v87
	v_cvt_pk_bf16_f32 v135, v88, v89
	v_cvt_pk_bf16_f32 v136, v82, v83
	v_cvt_pk_bf16_f32 v137, v84, v85
	global_store_dwordx4 v[164:165], v[134:137], off offset:-1792 nt
	ds_bpermute_b32 v134, v132, v166
	s_waitcnt lgkmcnt(0)
	v_add_f32_e32 v134, v166, v134
	ds_bpermute_b32 v135, v133, v134
	s_and_saveexec_b64 s[14:15], s[8:9]
	s_cbranch_execz .LBB0_506
	s_waitcnt lgkmcnt(0)
	v_add_f32_e32 v134, v134, v135
	ds_write_b32 v182, v134
.LBB0_506:
	s_or_b64 exec, exec, s[14:15]
	v_mul_f32_e32 v134, v79, v79
	s_waitcnt lgkmcnt(0)
	v_mul_f32_e32 v135, v81, v81
	v_fmac_f32_e32 v134, v78, v78
	v_fmac_f32_e32 v135, v80, v80
	s_mov_b64 s[14:15], 0xc000
	v_add_f32_e32 v134, v134, v135
	v_mul_f32_e32 v135, v75, v75
	v_lshl_add_u64 v[130:131], v[130:131], 0, s[14:15]
	v_fmac_f32_e32 v135, v74, v74
	v_lshl_add_u64 v[164:165], v[130:131], 0, s[24:25]
	v_add_f32_e32 v134, v134, v135
	v_mul_f32_e32 v135, v77, v77
	v_lshl_add_u64 v[164:165], v[164:165], 0, v[146:147]
	v_fmac_f32_e32 v135, v76, v76
	v_add_co_u32_e32 v164, vcc, s1, v164
	v_add_f32_e32 v166, v135, v134
	v_cvt_pk_bf16_f32 v134, v78, v79
	v_cvt_pk_bf16_f32 v135, v80, v81
	s_nop 0
	v_addc_co_u32_e32 v165, vcc, -1, v165, vcc
	v_cvt_pk_bf16_f32 v136, v74, v75
	v_cvt_pk_bf16_f32 v137, v76, v77
	global_store_dwordx4 v[164:165], v[134:137], off offset:-2048 nt
	s_nop 1
	v_mul_f32_e32 v134, v71, v71
	v_mul_f32_e32 v135, v73, v73
	v_fmac_f32_e32 v134, v70, v70
	v_fmac_f32_e32 v135, v72, v72
	v_add_f32_e32 v134, v134, v135
	v_mul_f32_e32 v135, v67, v67
	v_fmac_f32_e32 v135, v66, v66
	v_add_f32_e32 v134, v134, v135
	v_mul_f32_e32 v135, v69, v69
	v_fmac_f32_e32 v135, v68, v68
	v_add_f32_e32 v134, v135, v134
	v_add_f32_e32 v166, v166, v134
	v_cvt_pk_bf16_f32 v134, v70, v71
	v_cvt_pk_bf16_f32 v135, v72, v73
	v_cvt_pk_bf16_f32 v136, v66, v67
	v_cvt_pk_bf16_f32 v137, v68, v69
	global_store_dwordx4 v[164:165], v[134:137], off offset:-1792 nt
	ds_bpermute_b32 v134, v132, v166
	s_waitcnt lgkmcnt(0)
	v_add_f32_e32 v134, v166, v134
	ds_bpermute_b32 v135, v133, v134
	s_and_saveexec_b64 s[14:15], s[8:9]
	s_cbranch_execz .LBB0_508
	s_waitcnt lgkmcnt(0)
	v_add_f32_e32 v134, v134, v135
	ds_write_b32 v183, v134
.LBB0_508:
	s_or_b64 exec, exec, s[14:15]
	v_mul_f32_e32 v134, v63, v63
	s_waitcnt lgkmcnt(0)
	v_mul_f32_e32 v135, v65, v65
	v_fmac_f32_e32 v134, v62, v62
	v_fmac_f32_e32 v135, v64, v64
	s_mov_b64 s[14:15], 0x3c000
	v_add_f32_e32 v134, v134, v135
	v_mul_f32_e32 v135, v59, v59
	v_lshl_add_u64 v[130:131], v[130:131], 0, s[14:15]
	v_fmac_f32_e32 v135, v58, v58
	v_lshl_add_u64 v[164:165], v[130:131], 0, s[24:25]
	v_add_f32_e32 v134, v134, v135
	v_mul_f32_e32 v135, v61, v61
	v_lshl_add_u64 v[164:165], v[164:165], 0, v[146:147]
	v_fmac_f32_e32 v135, v60, v60
	v_add_co_u32_e32 v164, vcc, s1, v164
	v_add_f32_e32 v166, v135, v134
	v_cvt_pk_bf16_f32 v134, v62, v63
	v_cvt_pk_bf16_f32 v135, v64, v65
	s_nop 0
	v_addc_co_u32_e32 v165, vcc, -1, v165, vcc
	v_cvt_pk_bf16_f32 v136, v58, v59
	v_cvt_pk_bf16_f32 v137, v60, v61
	global_store_dwordx4 v[164:165], v[134:137], off offset:-2048 nt
	s_nop 1
	v_mul_f32_e32 v134, v55, v55
	v_mul_f32_e32 v135, v57, v57
	v_fmac_f32_e32 v134, v54, v54
	v_fmac_f32_e32 v135, v56, v56
	v_add_f32_e32 v134, v134, v135
	v_mul_f32_e32 v135, v51, v51
	v_fmac_f32_e32 v135, v50, v50
	v_add_f32_e32 v134, v134, v135
	v_mul_f32_e32 v135, v53, v53
	v_fmac_f32_e32 v135, v52, v52
	v_add_f32_e32 v134, v135, v134
	v_add_f32_e32 v166, v166, v134
	v_cvt_pk_bf16_f32 v134, v54, v55
	v_cvt_pk_bf16_f32 v135, v56, v57
	v_cvt_pk_bf16_f32 v136, v50, v51
	v_cvt_pk_bf16_f32 v137, v52, v53
	global_store_dwordx4 v[164:165], v[134:137], off offset:-1792 nt
	ds_bpermute_b32 v134, v132, v166
	s_waitcnt lgkmcnt(0)
	v_add_f32_e32 v134, v166, v134
	ds_bpermute_b32 v135, v133, v134
	s_and_saveexec_b64 s[14:15], s[8:9]
	s_cbranch_execz .LBB0_510
	s_waitcnt lgkmcnt(0)
	v_add_f32_e32 v134, v134, v135
	ds_write_b32 v184, v134
.LBB0_510:
	s_or_b64 exec, exec, s[14:15]
	v_mul_f32_e32 v134, v47, v47
	s_waitcnt lgkmcnt(0)
	v_mul_f32_e32 v135, v49, v49
	v_fmac_f32_e32 v134, v46, v46
	v_fmac_f32_e32 v135, v48, v48
	s_mov_b64 s[14:15], 0xc000
	v_add_f32_e32 v134, v134, v135
	v_mul_f32_e32 v135, v43, v43
	v_lshl_add_u64 v[130:131], v[130:131], 0, s[14:15]
	v_fmac_f32_e32 v135, v42, v42
	v_lshl_add_u64 v[164:165], v[130:131], 0, s[24:25]
	v_add_f32_e32 v134, v134, v135
	v_mul_f32_e32 v135, v45, v45
	v_lshl_add_u64 v[164:165], v[164:165], 0, v[146:147]
	v_fmac_f32_e32 v135, v44, v44
	v_add_co_u32_e32 v164, vcc, s1, v164
	v_add_f32_e32 v166, v135, v134
	v_cvt_pk_bf16_f32 v134, v46, v47
	v_cvt_pk_bf16_f32 v135, v48, v49
	s_nop 0
	v_addc_co_u32_e32 v165, vcc, -1, v165, vcc
	v_cvt_pk_bf16_f32 v136, v42, v43
	v_cvt_pk_bf16_f32 v137, v44, v45
	global_store_dwordx4 v[164:165], v[134:137], off offset:-2048 nt
	s_nop 1
	v_mul_f32_e32 v134, v39, v39
	v_mul_f32_e32 v135, v41, v41
	v_fmac_f32_e32 v134, v38, v38
	v_fmac_f32_e32 v135, v40, v40
	v_add_f32_e32 v134, v134, v135
	v_mul_f32_e32 v135, v35, v35
	v_fmac_f32_e32 v135, v34, v34
	v_add_f32_e32 v134, v134, v135
	v_mul_f32_e32 v135, v37, v37
	v_fmac_f32_e32 v135, v36, v36
	v_add_f32_e32 v134, v135, v134
	v_add_f32_e32 v166, v166, v134
	v_cvt_pk_bf16_f32 v134, v38, v39
	v_cvt_pk_bf16_f32 v135, v40, v41
	v_cvt_pk_bf16_f32 v136, v34, v35
	v_cvt_pk_bf16_f32 v137, v36, v37
	global_store_dwordx4 v[164:165], v[134:137], off offset:-1792 nt
	ds_bpermute_b32 v134, v132, v166
	s_waitcnt lgkmcnt(0)
	v_add_f32_e32 v134, v166, v134
	ds_bpermute_b32 v135, v133, v134
	s_and_saveexec_b64 s[14:15], s[8:9]
	s_cbranch_execz .LBB0_512
	s_waitcnt lgkmcnt(0)
	v_add_f32_e32 v134, v134, v135
	ds_write_b32 v185, v134
.LBB0_512:
	s_or_b64 exec, exec, s[14:15]
	v_mul_f32_e32 v134, v31, v31
	s_waitcnt lgkmcnt(0)
	v_mul_f32_e32 v135, v33, v33
	v_fmac_f32_e32 v134, v30, v30
	v_fmac_f32_e32 v135, v32, v32
	s_mov_b64 s[14:15], 0xc000
	v_add_f32_e32 v134, v134, v135
	v_mul_f32_e32 v135, v27, v27
	v_lshl_add_u64 v[130:131], v[130:131], 0, s[14:15]
	v_fmac_f32_e32 v135, v26, v26
	v_lshl_add_u64 v[164:165], v[130:131], 0, s[24:25]
	v_add_f32_e32 v134, v134, v135
	v_mul_f32_e32 v135, v29, v29
	v_lshl_add_u64 v[164:165], v[164:165], 0, v[146:147]
	v_fmac_f32_e32 v135, v28, v28
	v_add_co_u32_e32 v164, vcc, s1, v164
	v_add_f32_e32 v166, v135, v134
	v_cvt_pk_bf16_f32 v134, v30, v31
	v_cvt_pk_bf16_f32 v135, v32, v33
	s_nop 0
	v_addc_co_u32_e32 v165, vcc, -1, v165, vcc
	v_cvt_pk_bf16_f32 v136, v26, v27
	v_cvt_pk_bf16_f32 v137, v28, v29
	global_store_dwordx4 v[164:165], v[134:137], off offset:-2048 nt
	s_nop 1
	v_mul_f32_e32 v134, v23, v23
	v_mul_f32_e32 v135, v25, v25
	v_fmac_f32_e32 v134, v22, v22
	v_fmac_f32_e32 v135, v24, v24
	v_add_f32_e32 v134, v134, v135
	v_mul_f32_e32 v135, v19, v19
	v_fmac_f32_e32 v135, v18, v18
	v_add_f32_e32 v134, v134, v135
	v_mul_f32_e32 v135, v21, v21
	v_fmac_f32_e32 v135, v20, v20
	v_add_f32_e32 v134, v135, v134
	v_add_f32_e32 v166, v166, v134
	v_cvt_pk_bf16_f32 v134, v22, v23
	v_cvt_pk_bf16_f32 v135, v24, v25
	v_cvt_pk_bf16_f32 v136, v18, v19
	v_cvt_pk_bf16_f32 v137, v20, v21
	global_store_dwordx4 v[164:165], v[134:137], off offset:-1792 nt
	ds_bpermute_b32 v134, v132, v166
	s_waitcnt lgkmcnt(0)
	v_add_f32_e32 v134, v166, v134
	ds_bpermute_b32 v135, v133, v134
	s_and_saveexec_b64 s[14:15], s[8:9]
	s_cbranch_execz .LBB0_514
	s_waitcnt lgkmcnt(0)
	v_add_f32_e32 v134, v134, v135
	ds_write_b32 v186, v134
.LBB0_514:
	s_or_b64 exec, exec, s[14:15]
	v_lshl_add_u64 v[130:131], v[130:131], 0, s[24:25]
	v_mul_f32_e32 v134, v15, v15
	s_waitcnt lgkmcnt(0)
	v_mul_f32_e32 v135, v17, v17
	v_lshl_add_u64 v[130:131], v[130:131], 0, v[146:147]
	v_mul_f32_e32 v146, v7, v7
	v_mul_f32_e32 v165, v9, v9
	v_fmac_f32_e32 v134, v14, v14
	v_fmac_f32_e32 v135, v16, v16
	v_fmac_f32_e32 v146, v6, v6
	v_fmac_f32_e32 v165, v8, v8
	v_add_f32_e32 v134, v134, v135
	v_mul_f32_e32 v135, v11, v11
	v_add_f32_e32 v146, v146, v165
	v_mul_f32_e32 v165, v3, v3
	v_fmac_f32_e32 v135, v10, v10
	v_fmac_f32_e32 v165, v2, v2
	v_add_f32_e32 v134, v134, v135
	v_mul_f32_e32 v135, v13, v13
	v_add_f32_e32 v146, v146, v165
	v_mul_f32_e32 v165, v5, v5
	v_fmac_f32_e32 v135, v12, v12
	v_fmac_f32_e32 v165, v4, v4
	v_add_f32_e32 v164, v135, v134
	v_add_f32_e32 v146, v165, v146
	v_add_f32_e32 v146, v164, v146
	ds_bpermute_b32 v166, v132, v146
	s_mov_b32 s10, 0xa000
	v_add_co_u32_e32 v164, vcc, s10, v130
	v_cvt_pk_bf16_f32 v134, v14, v15
	s_waitcnt lgkmcnt(0)
	v_add_f32_e32 v130, v146, v166
	v_addc_co_u32_e32 v165, vcc, 0, v131, vcc
	ds_bpermute_b32 v131, v133, v130
	v_cvt_pk_bf16_f32 v135, v16, v17
	v_cvt_pk_bf16_f32 v136, v10, v11
	v_cvt_pk_bf16_f32 v137, v12, v13
	global_store_dwordx4 v[164:165], v[134:137], off offset:2048 nt
	v_cvt_pk_bf16_f32 v132, v6, v7
	v_cvt_pk_bf16_f32 v133, v8, v9
	s_nop 1
	v_cvt_pk_bf16_f32 v134, v2, v3
	v_cvt_pk_bf16_f32 v135, v4, v5
	global_store_dwordx4 v[164:165], v[132:135], off offset:2304 nt
	s_and_saveexec_b64 s[14:15], s[8:9]
	s_cbranch_execz .LBB0_516
	s_waitcnt lgkmcnt(0)
	v_add_f32_e32 v130, v130, v131
	ds_write_b32 v187, v130

.LBB0_520:
	s_andn2_b64 vcc, exec, s[14:15]
	s_cbranch_vccnz .LBB0_522
	s_waitcnt lgkmcnt(0)
	v_mov_b64_e32 v[130:131], s[28:29]
	v_mad_u64_u32 v[130:131], s[14:15], v160, s22, v[130:131]
	v_mad_i32_i24 v131, v161, s22, v131
	s_lshl_b32 s24, s16, 9
	v_lshl_add_u64 v[130:131], v[130:131], 0, s[24:25]
	v_lshlrev_b32_e32 v146, 1, v150
	v_cvt_pk_bf16_f32 v132, v126, v127
	v_cvt_pk_bf16_f32 v133, v128, v129
	v_cvt_pk_bf16_f32 v134, v122, v123
	v_cvt_pk_bf16_f32 v135, v124, v125
	v_lshl_add_u64 v[130:131], v[130:131], 0, v[146:147]
	s_mov_b32 s10, 0x18000
	global_store_dwordx4 v[130:131], v[132:135], off nt
	v_add_co_u32_e32 v164, vcc, s10, v130
	s_nop 0
	v_cvt_pk_bf16_f32 v132, v118, v119
	v_cvt_pk_bf16_f32 v133, v120, v121
	v_cvt_pk_bf16_f32 v134, v114, v115
	v_cvt_pk_bf16_f32 v135, v116, v117
	global_store_dwordx4 v[130:131], v[132:135], off offset:256 nt
	s_mov_b64 s[14:15], 0x18000
	v_addc_co_u32_e32 v165, vcc, 0, v131, vcc
	v_cvt_pk_bf16_f32 v132, v110, v111
	v_cvt_pk_bf16_f32 v133, v112, v113
	v_cvt_pk_bf16_f32 v134, v106, v107
	v_cvt_pk_bf16_f32 v135, v108, v109
	s_mov_b32 s10, 0x30000
	v_lshl_add_u64 v[136:137], v[130:131], 0, s[14:15]
	global_store_dwordx4 v[164:165], v[132:135], off nt
	v_add_co_u32_e32 v164, vcc, s10, v130
	s_nop 0
	v_cvt_pk_bf16_f32 v132, v102, v103
	v_cvt_pk_bf16_f32 v133, v104, v105
	v_cvt_pk_bf16_f32 v134, v98, v99
	v_cvt_pk_bf16_f32 v135, v100, v101
	global_store_dwordx4 v[136:137], v[132:135], off offset:256 nt
	s_mov_b64 s[14:15], 0x30000
	v_addc_co_u32_e32 v165, vcc, 0, v131, vcc
	v_cvt_pk_bf16_f32 v132, v94, v95
	v_cvt_pk_bf16_f32 v133, v96, v97
	v_cvt_pk_bf16_f32 v134, v90, v91
	v_cvt_pk_bf16_f32 v135, v92, v93
	s_mov_b32 s10, 0x48000
	v_lshl_add_u64 v[136:137], v[130:131], 0, s[14:15]
	global_store_dwordx4 v[164:165], v[132:135], off nt
	v_add_co_u32_e32 v164, vcc, s10, v130
	s_nop 0
	v_cvt_pk_bf16_f32 v132, v86, v87
	v_cvt_pk_bf16_f32 v133, v88, v89
	v_cvt_pk_bf16_f32 v134, v82, v83
	v_cvt_pk_bf16_f32 v135, v84, v85
	global_store_dwordx4 v[136:137], v[132:135], off offset:256 nt
	s_mov_b64 s[14:15], 0x48000
	v_addc_co_u32_e32 v165, vcc, 0, v131, vcc
	v_cvt_pk_bf16_f32 v132, v78, v79
	v_cvt_pk_bf16_f32 v133, v80, v81
	v_cvt_pk_bf16_f32 v134, v74, v75
	v_cvt_pk_bf16_f32 v135, v76, v77
	v_lshl_add_u64 v[136:137], v[130:131], 0, s[14:15]
	global_store_dwordx4 v[164:165], v[132:135], off nt
	v_add_co_u32_e32 v164, vcc, s58, v130
	s_nop 0
	v_cvt_pk_bf16_f32 v132, v70, v71
	v_cvt_pk_bf16_f32 v133, v72, v73
	v_cvt_pk_bf16_f32 v134, v66, v67
	v_cvt_pk_bf16_f32 v135, v68, v69
	global_store_dwordx4 v[136:137], v[132:135], off offset:256 nt
	s_mov_b64 s[14:15], 0xc0000
	v_addc_co_u32_e32 v165, vcc, 0, v131, vcc
	v_cvt_pk_bf16_f32 v132, v62, v63
	v_cvt_pk_bf16_f32 v133, v64, v65
	v_cvt_pk_bf16_f32 v134, v58, v59
	v_cvt_pk_bf16_f32 v135, v60, v61
	v_lshl_add_u64 v[136:137], v[130:131], 0, s[14:15]
	global_store_dwordx4 v[164:165], v[132:135], off nt
	v_add_co_u32_e32 v164, vcc, s59, v130
	s_nop 0
	v_cvt_pk_bf16_f32 v132, v54, v55
	v_cvt_pk_bf16_f32 v133, v56, v57
	v_cvt_pk_bf16_f32 v134, v50, v51
	v_cvt_pk_bf16_f32 v135, v52, v53
	global_store_dwordx4 v[136:137], v[132:135], off offset:256 nt
	v_addc_co_u32_e32 v165, vcc, 0, v131, vcc
	s_nop 0
	v_cvt_pk_bf16_f32 v132, v46, v47
	v_cvt_pk_bf16_f32 v133, v48, v49
	v_cvt_pk_bf16_f32 v134, v42, v43
	v_cvt_pk_bf16_f32 v135, v44, v45
	v_lshl_add_u64 v[136:137], v[130:131], 0, s[70:71]
	global_store_dwordx4 v[164:165], v[132:135], off nt
	v_add_co_u32_e32 v164, vcc, s60, v130
	s_nop 0
	v_cvt_pk_bf16_f32 v132, v38, v39
	v_cvt_pk_bf16_f32 v133, v40, v41
	v_cvt_pk_bf16_f32 v134, v34, v35
	v_cvt_pk_bf16_f32 v135, v36, v37
	global_store_dwordx4 v[136:137], v[132:135], off offset:256 nt
	v_lshl_add_u64 v[136:137], v[130:131], 0, s[72:73]
	v_addc_co_u32_e32 v165, vcc, 0, v131, vcc
	v_cvt_pk_bf16_f32 v132, v30, v31
	v_cvt_pk_bf16_f32 v133, v32, v33
	v_cvt_pk_bf16_f32 v134, v26, v27
	v_cvt_pk_bf16_f32 v135, v28, v29
	global_store_dwordx4 v[164:165], v[132:135], off nt
	s_nop 1
	v_cvt_pk_bf16_f32 v132, v22, v23
	v_cvt_pk_bf16_f32 v133, v24, v25
	v_cvt_pk_bf16_f32 v134, v18, v19
	v_cvt_pk_bf16_f32 v135, v20, v21
	global_store_dwordx4 v[136:137], v[132:135], off offset:256 nt
	v_lshl_add_u64 v[136:137], v[130:131], 0, s[74:75]
	v_add_co_u32_e32 v130, vcc, s61, v130
	v_cvt_pk_bf16_f32 v132, v14, v15
	v_cvt_pk_bf16_f32 v133, v16, v17
	v_cvt_pk_bf16_f32 v134, v10, v11
	v_cvt_pk_bf16_f32 v135, v12, v13
	s_nop 1
	v_addc_co_u32_e32 v131, vcc, 0, v131, vcc
	global_store_dwordx4 v[130:131], v[132:135], off nt
	v_cvt_pk_bf16_f32 v130, v6, v7
	v_cvt_pk_bf16_f32 v131, v8, v9
	s_nop 1
	v_cvt_pk_bf16_f32 v132, v2, v3
	v_cvt_pk_bf16_f32 v133, v4, v5
	global_store_dwordx4 v[136:137], v[130:133], off offset:256 nt

.LBB0_559:
	v_mov_b32_e32 v124, v134
	v_add_u32_e32 v134, s31, v177
	v_cvt_pk_bf16_f32 v196, v126, v127
	v_cvt_pk_bf16_f32 v197, v172, v173
	v_cvt_pk_bf16_f32 v198, v168, v169
	v_cvt_pk_bf16_f32 v199, v170, v171
	ds_read_b128 v[168:171], v134 offset:16
	v_mov_b32_e32 v125, v130
	v_mov_b32_e32 v123, v132
	v_mov_b64_e32 v[126:127], s[28:29]
	v_mov_b32_e32 v122, v136
	s_waitcnt lgkmcnt(0)
	v_mov_b32_e32 v172, v169
	v_mov_b32_e32 v173, v170
	v_mov_b32_e32 v169, v171
	v_pk_add_f32 v[168:169], v[172:173], v[168:169]
	s_lshl_b32 s16, s16, 8
	v_add_f32_e32 v130, v168, v169
	v_fmamk_f32 v130, v130, 0x3c000000, v192
	v_cmp_gt_f32_e32 vcc, s23, v130
	v_mul_f32_e32 v132, 0x4f800000, v130
	v_mad_u64_u32 v[126:127], s[18:19], v160, s22, v[126:127]
	v_cndmask_b32_e32 v130, v130, v132, vcc
	v_sqrt_f32_e32 v132, v130
	s_ashr_i32 s17, s16, 31
	v_mad_i32_i24 v127, v161, s22, v127
	v_lshl_add_u64 v[126:127], s[16:17], 1, v[126:127]
	v_add_u32_e32 v136, -1, v132
	v_fma_f32 v168, -v136, v132, v130
	v_cmp_ge_f32_e64 s[16:17], 0, v168
	v_add_u32_e32 v168, 1, v132
	v_lshlrev_b32_e32 v146, 1, v150
	v_cndmask_b32_e64 v136, v132, v136, s[16:17]
	v_fma_f32 v132, -v168, v132, v130
	v_cmp_lt_f32_e64 s[16:17], 0, v132
	v_lshl_add_u64 v[160:161], v[126:127], 0, v[146:147]
	global_store_dwordx4 v[160:161], v[196:199], off nt
	v_cndmask_b32_e64 v132, v136, v168, s[16:17]
	v_mul_f32_e32 v136, 0x37800000, v132
	v_cndmask_b32_e32 v132, v132, v136, vcc
	v_cmp_class_f32_e32 vcc, v130, v193
	s_nop 1
	v_cndmask_b32_e32 v130, v132, v130, vcc
	v_div_scale_f32 v132, s[16:17], v130, v130, 1.0
	v_rcp_f32_e32 v136, v132
	s_nop 0
	v_fma_f32 v168, -v132, v136, 1.0
	v_fmac_f32_e32 v136, v168, v136
	v_div_scale_f32 v168, vcc, 1.0, v130, 1.0
	v_mul_f32_e32 v169, v168, v136
	v_fma_f32 v170, -v132, v169, v168
	v_fmac_f32_e32 v169, v170, v136
	v_fma_f32 v132, -v132, v169, v168
	v_div_fmas_f32 v132, v132, v136, v169
	v_div_fixup_f32 v130, v132, v130, 1.0
	v_pk_mul_f32 v[118:119], v[118:119], v[130:131] op_sel_hi:[1,0]
	v_pk_mul_f32 v[120:121], v[120:121], v[130:131] op_sel_hi:[1,0]
	v_pk_mul_f32 v[114:115], v[114:115], v[130:131] op_sel_hi:[1,0]
	v_pk_mul_f32 v[116:117], v[116:117], v[130:131] op_sel_hi:[1,0]
	v_pk_mul_f32 v[120:121], v[164:165], v[120:121]
	v_pk_mul_f32 v[118:119], v[124:125], v[118:119]
	v_pk_mul_f32 v[116:117], v[166:167], v[116:117]
	v_pk_mul_f32 v[114:115], v[122:123], v[114:115]
	s_and_b64 vcc, exec, s[14:15]
	s_cbranch_vccnz .LBB0_561
	global_load_dwordx4 v[164:167], v[128:129], off offset:16
	global_load_dwordx4 v[168:171], v[128:129], off
	s_waitcnt vmcnt(1)
	v_pk_mul_f32 v[196:197], v[114:115], v[164:165] op_sel:[1,1] op_sel_hi:[1,0]
	s_waitcnt vmcnt(0)
	v_pk_mul_f32 v[172:173], v[118:119], v[168:169] op_sel:[1,1] op_sel_hi:[1,0]
	v_pk_mul_f32 v[128:129], v[118:119], v[168:169]
	v_pk_fma_f32 v[118:119], v[118:119], v[168:169], v[172:173] op_sel_hi:[0,1,1]
	v_mul_f32_e32 v118, v121, v171
	v_pk_fma_f32 v[168:169], v[120:121], v[170:171], v[118:119] op_sel_hi:[1,1,0] neg_lo:[0,0,1] neg_hi:[0,0,1]
	v_mul_f32_e32 v118, v121, v170
	v_pk_fma_f32 v[170:171], v[120:121], v[170:171], v[118:119] op_sel:[0,1,0] op_sel_hi:[1,0,0]
	v_pk_mul_f32 v[120:121], v[114:115], v[164:165]
	v_pk_fma_f32 v[114:115], v[114:115], v[164:165], v[196:197] op_sel_hi:[0,1,1]
	v_mul_f32_e32 v114, v117, v167
	v_pk_fma_f32 v[164:165], v[116:117], v[166:167], v[114:115] op_sel_hi:[1,1,0] neg_lo:[0,0,1] neg_hi:[0,0,1]
	v_mul_f32_e32 v114, v117, v166
	v_pk_fma_f32 v[166:167], v[116:117], v[166:167], v[114:115] op_sel:[0,1,0] op_sel_hi:[1,0,0]
	v_sub_f32_e32 v114, v120, v196
	v_sub_f32_e32 v118, v128, v172
	v_mov_b32_e32 v116, v164
	v_mov_b32_e32 v117, v166
	v_mov_b32_e32 v120, v168
	v_mov_b32_e32 v121, v170
.LBB0_561:
	v_cvt_pk_bf16_f32 v118, v118, v119
	v_cvt_pk_bf16_f32 v119, v120, v121
	v_cvt_pk_bf16_f32 v120, v114, v115
	v_mov_b32_e32 v114, s24
	v_cndmask_b32_e64 v114, v174, v114, s[4:5]
	v_cvt_pk_bf16_f32 v121, v116, v117
	global_store_dwordx4 v[160:161], v[118:121], off offset:256 nt
	v_mov_b32_e32 v130, v135
	v_mov_b32_e32 v132, v137
	v_lshl_or_b32 v118, v114, 6, v178
	ds_read_b128 v[114:117], v134 offset:512
	v_ashrrev_i32_e32 v119, 31, v118
	s_waitcnt lgkmcnt(0)
	v_mov_b32_e32 v120, v115
	v_mov_b32_e32 v121, v116
	v_mov_b32_e32 v115, v117
	v_pk_add_f32 v[114:115], v[120:121], v[114:115]
	s_nop 0
	v_add_f32_e32 v114, v114, v115
	v_fmamk_f32 v114, v114, 0x3c000000, v192
	v_cmp_gt_f32_e32 vcc, s23, v114
	v_mul_f32_e32 v115, 0x4f800000, v114
	s_nop 0
	v_cndmask_b32_e32 v114, v114, v115, vcc
	v_sqrt_f32_e32 v115, v114
	s_nop 0
	v_add_u32_e32 v116, -1, v115
	v_fma_f32 v117, -v116, v115, v114
	v_cmp_ge_f32_e64 s[16:17], 0, v117
	v_add_u32_e32 v117, 1, v115
	s_nop 0
	v_cndmask_b32_e64 v116, v115, v116, s[16:17]
	v_fma_f32 v115, -v117, v115, v114
	v_cmp_lt_f32_e64 s[16:17], 0, v115
	s_nop 1
	v_cndmask_b32_e64 v115, v116, v117, s[16:17]
	v_mul_f32_e32 v116, 0x37800000, v115
	v_cndmask_b32_e32 v115, v115, v116, vcc
	v_cmp_class_f32_e32 vcc, v114, v193
	s_nop 1
	v_cndmask_b32_e32 v114, v115, v114, vcc
	v_div_scale_f32 v115, s[16:17], v114, v114, 1.0
	v_rcp_f32_e32 v116, v115
	s_nop 0
	v_fma_f32 v117, -v115, v116, 1.0
	v_fmac_f32_e32 v116, v117, v116
	v_div_scale_f32 v117, vcc, 1.0, v114, 1.0
	v_mul_f32_e32 v120, v117, v116
	v_fma_f32 v121, -v115, v120, v117
	v_fmac_f32_e32 v120, v121, v116
	v_fma_f32 v115, -v115, v120, v117
	v_div_fmas_f32 v115, v115, v116, v120
	v_div_fixup_f32 v116, v115, v114, 1.0
	v_pk_mul_f32 v[110:111], v[110:111], v[116:117] op_sel_hi:[1,0]
	v_pk_mul_f32 v[112:113], v[112:113], v[116:117] op_sel_hi:[1,0]
	v_pk_mul_f32 v[106:107], v[106:107], v[116:117] op_sel_hi:[1,0]
	v_pk_mul_f32 v[108:109], v[108:109], v[116:117] op_sel_hi:[1,0]
	v_pk_mul_f32 v[114:115], v[130:131], v[112:113]
	v_pk_mul_f32 v[110:111], v[124:125], v[110:111]
	v_pk_mul_f32 v[112:113], v[132:133], v[108:109]
	v_pk_mul_f32 v[106:107], v[122:123], v[106:107]
	s_and_b64 vcc, exec, s[14:15]
	v_lshl_add_u64 v[108:109], v[118:119], 2, s[42:43]
	s_cbranch_vccnz .LBB0_563
	global_load_dwordx4 v[116:119], v[108:109], off offset:16
	global_load_dwordx4 v[164:167], v[108:109], off
	s_waitcnt vmcnt(0)
	v_pk_mul_f32 v[128:129], v[110:111], v[164:165] op_sel:[1,1] op_sel_hi:[1,0]
	v_pk_mul_f32 v[120:121], v[110:111], v[164:165]
	v_pk_fma_f32 v[110:111], v[110:111], v[164:165], v[128:129] op_sel_hi:[0,1,1]
	v_mul_f32_e32 v110, v115, v167
	v_pk_fma_f32 v[160:161], v[114:115], v[166:167], v[110:111] op_sel_hi:[1,1,0] neg_lo:[0,0,1] neg_hi:[0,0,1]
	v_mul_f32_e32 v110, v115, v166
	v_pk_fma_f32 v[164:165], v[114:115], v[166:167], v[110:111] op_sel:[0,1,0] op_sel_hi:[1,0,0]
	v_pk_mul_f32 v[166:167], v[106:107], v[116:117] op_sel:[1,1] op_sel_hi:[1,0]
	v_pk_mul_f32 v[114:115], v[106:107], v[116:117]
	v_pk_fma_f32 v[106:107], v[106:107], v[116:117], v[166:167] op_sel_hi:[0,1,1]
	v_mul_f32_e32 v106, v113, v119
	v_pk_fma_f32 v[116:117], v[112:113], v[118:119], v[106:107] op_sel_hi:[1,1,0] neg_lo:[0,0,1] neg_hi:[0,0,1]
	v_mul_f32_e32 v106, v113, v118
	v_pk_fma_f32 v[118:119], v[112:113], v[118:119], v[106:107] op_sel:[0,1,0] op_sel_hi:[1,0,0]
	v_sub_f32_e32 v106, v114, v166
	v_sub_f32_e32 v110, v120, v128
	v_mov_b32_e32 v112, v116
	v_mov_b32_e32 v113, v118
	v_mov_b32_e32 v114, v160
	v_mov_b32_e32 v115, v164
.LBB0_563:
	v_cvt_pk_bf16_f32 v116, v110, v111
	v_cvt_pk_bf16_f32 v117, v114, v115
	v_cvt_pk_bf16_f32 v118, v106, v107
	v_lshl_add_u64 v[106:107], v[126:127], 0, v[146:147]
	s_mov_b32 s10, 0x18000
	v_add_co_u32_e32 v110, vcc, s10, v106
	v_cvt_pk_bf16_f32 v119, v112, v113
	s_nop 1
	v_addc_co_u32_e32 v111, vcc, 0, v107, vcc
	global_store_dwordx4 v[110:111], v[116:119], off nt
	ds_read_b128 v[110:113], v134 offset:528
	s_waitcnt lgkmcnt(0)
	v_mov_b32_e32 v114, v111
	v_mov_b32_e32 v115, v112
	v_mov_b32_e32 v111, v113
	v_pk_add_f32 v[110:111], v[114:115], v[110:111]
	s_nop 0
	v_add_f32_e32 v110, v110, v111
	v_fmamk_f32 v110, v110, 0x3c000000, v192
	v_cmp_gt_f32_e32 vcc, s23, v110
	v_mul_f32_e32 v111, 0x4f800000, v110
	s_nop 0
	v_cndmask_b32_e32 v110, v110, v111, vcc
	v_sqrt_f32_e32 v111, v110
	s_nop 0
	v_add_u32_e32 v112, -1, v111
	v_fma_f32 v113, -v112, v111, v110
	v_cmp_ge_f32_e64 s[16:17], 0, v113
	v_add_u32_e32 v113, 1, v111
	s_nop 0
	v_cndmask_b32_e64 v112, v111, v112, s[16:17]
	v_fma_f32 v111, -v113, v111, v110
	v_cmp_lt_f32_e64 s[16:17], 0, v111
	s_nop 1
	v_cndmask_b32_e64 v111, v112, v113, s[16:17]
	v_mul_f32_e32 v112, 0x37800000, v111
	v_cndmask_b32_e32 v111, v111, v112, vcc
	v_cmp_class_f32_e32 vcc, v110, v193
	s_nop 1
	v_cndmask_b32_e32 v110, v111, v110, vcc
	v_div_scale_f32 v111, s[16:17], v110, v110, 1.0
	v_rcp_f32_e32 v112, v111
	s_nop 0
	v_fma_f32 v113, -v111, v112, 1.0
	v_fmac_f32_e32 v112, v113, v112
	v_div_scale_f32 v113, vcc, 1.0, v110, 1.0
	v_mul_f32_e32 v114, v113, v112
	v_fma_f32 v115, -v111, v114, v113
	v_fmac_f32_e32 v114, v115, v112
	v_fma_f32 v111, -v111, v114, v113
	v_div_fmas_f32 v111, v111, v112, v114
	v_div_fixup_f32 v110, v111, v110, 1.0
	v_pk_mul_f32 v[102:103], v[102:103], v[110:111] op_sel_hi:[1,0]
	v_pk_mul_f32 v[104:105], v[104:105], v[110:111] op_sel_hi:[1,0]
	v_pk_mul_f32 v[98:99], v[98:99], v[110:111] op_sel_hi:[1,0]
	v_pk_mul_f32 v[100:101], v[100:101], v[110:111] op_sel_hi:[1,0]
	v_pk_mul_f32 v[104:105], v[130:131], v[104:105]
	v_pk_mul_f32 v[102:103], v[124:125], v[102:103]
	v_pk_mul_f32 v[100:101], v[132:133], v[100:101]
	v_pk_mul_f32 v[98:99], v[122:123], v[98:99]
	s_and_b64 vcc, exec, s[14:15]
	s_cbranch_vccnz .LBB0_565
	global_load_dwordx4 v[110:113], v[108:109], off offset:16
	global_load_dwordx4 v[114:117], v[108:109], off
	s_waitcnt vmcnt(1)
	v_pk_mul_f32 v[120:121], v[98:99], v[110:111] op_sel:[1,1] op_sel_hi:[1,0]
	s_waitcnt vmcnt(0)
	v_pk_mul_f32 v[118:119], v[102:103], v[114:115] op_sel:[1,1] op_sel_hi:[1,0]
	v_pk_mul_f32 v[108:109], v[102:103], v[114:115]
	v_pk_fma_f32 v[102:103], v[102:103], v[114:115], v[118:119] op_sel_hi:[0,1,1]
	v_mul_f32_e32 v102, v105, v117
	v_pk_fma_f32 v[114:115], v[104:105], v[116:117], v[102:103] op_sel_hi:[1,1,0] neg_lo:[0,0,1] neg_hi:[0,0,1]
	v_mul_f32_e32 v102, v105, v116
	v_pk_fma_f32 v[116:117], v[104:105], v[116:117], v[102:103] op_sel:[0,1,0] op_sel_hi:[1,0,0]
	v_pk_mul_f32 v[104:105], v[98:99], v[110:111]
	v_pk_fma_f32 v[98:99], v[98:99], v[110:111], v[120:121] op_sel_hi:[0,1,1]
	v_mul_f32_e32 v98, v101, v113
	v_pk_fma_f32 v[110:111], v[100:101], v[112:113], v[98:99] op_sel_hi:[1,1,0] neg_lo:[0,0,1] neg_hi:[0,0,1]
	v_mul_f32_e32 v98, v101, v112
	v_pk_fma_f32 v[112:113], v[100:101], v[112:113], v[98:99] op_sel:[0,1,0] op_sel_hi:[1,0,0]
	v_sub_f32_e32 v98, v104, v120
	v_sub_f32_e32 v102, v108, v118
	v_mov_b32_e32 v100, v110
	v_mov_b32_e32 v101, v112
	v_mov_b32_e32 v104, v114
	v_mov_b32_e32 v105, v116
.LBB0_565:
	v_cvt_pk_bf16_f32 v102, v102, v103
	v_cvt_pk_bf16_f32 v103, v104, v105
	v_cvt_pk_bf16_f32 v104, v98, v99
	v_cvt_pk_bf16_f32 v105, v100, v101
	ds_read_b128 v[98:101], v134 offset:1024
	s_mov_b64 s[16:17], 0x18000
	v_mov_b32_e32 v130, v135
	v_mov_b32_e32 v132, v137
	s_waitcnt lgkmcnt(0)
	v_mov_b32_e32 v108, v99
	v_mov_b32_e32 v109, v100
	v_mov_b32_e32 v99, v101
	v_pk_add_f32 v[98:99], v[108:109], v[98:99]
	s_nop 0
	v_add_f32_e32 v98, v98, v99
	v_fmamk_f32 v98, v98, 0x3c000000, v192
	v_mul_f32_e32 v99, 0x4f800000, v98
	v_cmp_gt_f32_e32 vcc, s23, v98
	s_nop 1
	v_cndmask_b32_e32 v100, v98, v99, vcc
	v_sqrt_f32_e32 v101, v100
	v_lshl_add_u64 v[98:99], v[106:107], 0, s[16:17]
	global_store_dwordx4 v[98:99], v[102:105], off offset:256 nt
	v_mov_b32_e32 v98, s24
	v_add_u32_e32 v99, -1, v101
	v_fma_f32 v102, -v99, v101, v100
	v_cmp_ge_f32_e64 s[16:17], 0, v102
	v_add_u32_e32 v102, 1, v101
	v_cndmask_b32_e64 v98, v175, v98, s[4:5]
	v_cndmask_b32_e64 v99, v101, v99, s[16:17]
	v_fma_f32 v101, -v102, v101, v100
	v_cmp_lt_f32_e64 s[16:17], 0, v101
	s_nop 1
	v_cndmask_b32_e64 v99, v99, v102, s[16:17]
	v_mul_f32_e32 v101, 0x37800000, v99
	v_cndmask_b32_e32 v99, v99, v101, vcc
	v_cmp_class_f32_e32 vcc, v100, v193
	s_nop 1
	v_cndmask_b32_e32 v99, v99, v100, vcc
	v_div_scale_f32 v102, s[16:17], v99, v99, 1.0
	v_rcp_f32_e32 v103, v102
	v_lshl_or_b32 v100, v98, 6, v178
	v_ashrrev_i32_e32 v101, 31, v100
	v_fma_f32 v98, -v102, v103, 1.0
	v_fmac_f32_e32 v103, v98, v103
	v_div_scale_f32 v98, vcc, 1.0, v99, 1.0
	v_mul_f32_e32 v104, v98, v103
	v_fma_f32 v105, -v102, v104, v98
	v_fmac_f32_e32 v104, v105, v103
	v_fma_f32 v98, -v102, v104, v98
	v_div_fmas_f32 v98, v98, v103, v104
	v_div_fixup_f32 v102, v98, v99, 1.0
	v_pk_mul_f32 v[94:95], v[94:95], v[102:103] op_sel_hi:[1,0]
	v_pk_mul_f32 v[96:97], v[96:97], v[102:103] op_sel_hi:[1,0]
	v_pk_mul_f32 v[90:91], v[90:91], v[102:103] op_sel_hi:[1,0]
	v_pk_mul_f32 v[92:93], v[92:93], v[102:103] op_sel_hi:[1,0]
	v_pk_mul_f32 v[98:99], v[130:131], v[96:97]
	v_pk_mul_f32 v[94:95], v[124:125], v[94:95]
	v_pk_mul_f32 v[96:97], v[132:133], v[92:93]
	v_pk_mul_f32 v[90:91], v[122:123], v[90:91]
	s_and_b64 vcc, exec, s[14:15]
	v_lshl_add_u64 v[92:93], v[100:101], 2, s[42:43]
	s_cbranch_vccnz .LBB0_567
	global_load_dwordx4 v[100:103], v[92:93], off offset:16
	global_load_dwordx4 v[104:107], v[92:93], off
	s_waitcnt vmcnt(1)
	v_pk_mul_f32 v[112:113], v[90:91], v[100:101] op_sel:[1,1] op_sel_hi:[1,0]
	s_waitcnt vmcnt(0)
	v_pk_mul_f32 v[110:111], v[94:95], v[104:105] op_sel:[1,1] op_sel_hi:[1,0]
	v_pk_mul_f32 v[108:109], v[94:95], v[104:105]
	v_pk_fma_f32 v[94:95], v[94:95], v[104:105], v[110:111] op_sel_hi:[0,1,1]
	v_mul_f32_e32 v94, v99, v107
	v_pk_fma_f32 v[104:105], v[98:99], v[106:107], v[94:95] op_sel_hi:[1,1,0] neg_lo:[0,0,1] neg_hi:[0,0,1]
	v_mul_f32_e32 v94, v99, v106
	v_pk_fma_f32 v[106:107], v[98:99], v[106:107], v[94:95] op_sel:[0,1,0] op_sel_hi:[1,0,0]
	v_pk_mul_f32 v[98:99], v[90:91], v[100:101]
	v_pk_fma_f32 v[90:91], v[90:91], v[100:101], v[112:113] op_sel_hi:[0,1,1]
	v_mul_f32_e32 v90, v97, v103
	v_pk_fma_f32 v[100:101], v[96:97], v[102:103], v[90:91] op_sel_hi:[1,1,0] neg_lo:[0,0,1] neg_hi:[0,0,1]
	v_mul_f32_e32 v90, v97, v102
	v_pk_fma_f32 v[102:103], v[96:97], v[102:103], v[90:91] op_sel:[0,1,0] op_sel_hi:[1,0,0]
	v_sub_f32_e32 v90, v98, v112
	v_sub_f32_e32 v94, v108, v110
	v_mov_b32_e32 v96, v100
	v_mov_b32_e32 v97, v102
	v_mov_b32_e32 v98, v104
	v_mov_b32_e32 v99, v106
.LBB0_567:
	v_cvt_pk_bf16_f32 v100, v94, v95
	v_cvt_pk_bf16_f32 v101, v98, v99
	v_cvt_pk_bf16_f32 v102, v90, v91
	v_lshl_add_u64 v[90:91], v[126:127], 0, v[146:147]
	s_mov_b32 s10, 0x30000
	v_add_co_u32_e32 v94, vcc, s10, v90
	v_cvt_pk_bf16_f32 v103, v96, v97
	s_nop 1
	v_addc_co_u32_e32 v95, vcc, 0, v91, vcc
	global_store_dwordx4 v[94:95], v[100:103], off nt
	ds_read_b128 v[94:97], v134 offset:1040
	s_waitcnt lgkmcnt(0)
	v_mov_b32_e32 v98, v95
	v_mov_b32_e32 v99, v96
	v_mov_b32_e32 v95, v97
	v_pk_add_f32 v[94:95], v[98:99], v[94:95]
	s_nop 0
	v_add_f32_e32 v94, v94, v95
	v_fmamk_f32 v94, v94, 0x3c000000, v192
	v_cmp_gt_f32_e32 vcc, s23, v94
	v_mul_f32_e32 v95, 0x4f800000, v94
	s_nop 0
	v_cndmask_b32_e32 v94, v94, v95, vcc
	v_sqrt_f32_e32 v95, v94
	s_nop 0
	v_add_u32_e32 v96, -1, v95
	v_fma_f32 v97, -v96, v95, v94
	v_cmp_ge_f32_e64 s[16:17], 0, v97
	v_add_u32_e32 v97, 1, v95
	s_nop 0
	v_cndmask_b32_e64 v96, v95, v96, s[16:17]
	v_fma_f32 v95, -v97, v95, v94
	v_cmp_lt_f32_e64 s[16:17], 0, v95
	s_nop 1
	v_cndmask_b32_e64 v95, v96, v97, s[16:17]
	v_mul_f32_e32 v96, 0x37800000, v95
	v_cndmask_b32_e32 v95, v95, v96, vcc
	v_cmp_class_f32_e32 vcc, v94, v193
	s_nop 1
	v_cndmask_b32_e32 v94, v95, v94, vcc
	v_div_scale_f32 v95, s[16:17], v94, v94, 1.0
	v_rcp_f32_e32 v96, v95
	s_nop 0
	v_fma_f32 v97, -v95, v96, 1.0
	v_fmac_f32_e32 v96, v97, v96
	v_div_scale_f32 v97, vcc, 1.0, v94, 1.0
	v_mul_f32_e32 v98, v97, v96
	v_fma_f32 v99, -v95, v98, v97
	v_fmac_f32_e32 v98, v99, v96
	v_fma_f32 v95, -v95, v98, v97
	v_div_fmas_f32 v95, v95, v96, v98
	v_div_fixup_f32 v94, v95, v94, 1.0
	v_pk_mul_f32 v[86:87], v[86:87], v[94:95] op_sel_hi:[1,0]
	v_pk_mul_f32 v[88:89], v[88:89], v[94:95] op_sel_hi:[1,0]
	v_pk_mul_f32 v[82:83], v[82:83], v[94:95] op_sel_hi:[1,0]
	v_pk_mul_f32 v[84:85], v[84:85], v[94:95] op_sel_hi:[1,0]
	v_pk_mul_f32 v[88:89], v[130:131], v[88:89]
	v_pk_mul_f32 v[86:87], v[124:125], v[86:87]
	v_pk_mul_f32 v[84:85], v[132:133], v[84:85]
	v_pk_mul_f32 v[82:83], v[122:123], v[82:83]
	s_and_b64 vcc, exec, s[14:15]
	s_cbranch_vccnz .LBB0_569
	global_load_dwordx4 v[94:97], v[92:93], off offset:16
	global_load_dwordx4 v[98:101], v[92:93], off
	s_waitcnt vmcnt(1)
	v_pk_mul_f32 v[104:105], v[82:83], v[94:95] op_sel:[1,1] op_sel_hi:[1,0]
	s_waitcnt vmcnt(0)
	v_pk_mul_f32 v[102:103], v[86:87], v[98:99] op_sel:[1,1] op_sel_hi:[1,0]
	v_pk_mul_f32 v[92:93], v[86:87], v[98:99]
	v_pk_fma_f32 v[86:87], v[86:87], v[98:99], v[102:103] op_sel_hi:[0,1,1]
	v_mul_f32_e32 v86, v89, v101
	v_pk_fma_f32 v[98:99], v[88:89], v[100:101], v[86:87] op_sel_hi:[1,1,0] neg_lo:[0,0,1] neg_hi:[0,0,1]
	v_mul_f32_e32 v86, v89, v100
	v_pk_fma_f32 v[100:101], v[88:89], v[100:101], v[86:87] op_sel:[0,1,0] op_sel_hi:[1,0,0]
	v_pk_mul_f32 v[88:89], v[82:83], v[94:95]
	v_pk_fma_f32 v[82:83], v[82:83], v[94:95], v[104:105] op_sel_hi:[0,1,1]
	v_mul_f32_e32 v82, v85, v97
	v_pk_fma_f32 v[94:95], v[84:85], v[96:97], v[82:83] op_sel_hi:[1,1,0] neg_lo:[0,0,1] neg_hi:[0,0,1]
	v_mul_f32_e32 v82, v85, v96
	v_pk_fma_f32 v[96:97], v[84:85], v[96:97], v[82:83] op_sel:[0,1,0] op_sel_hi:[1,0,0]
	v_sub_f32_e32 v82, v88, v104
	v_sub_f32_e32 v86, v92, v102
	v_mov_b32_e32 v84, v94
	v_mov_b32_e32 v85, v96
	v_mov_b32_e32 v88, v98
	v_mov_b32_e32 v89, v100
.LBB0_569:
	v_cvt_pk_bf16_f32 v86, v86, v87
	v_cvt_pk_bf16_f32 v87, v88, v89
	v_cvt_pk_bf16_f32 v88, v82, v83
	v_cvt_pk_bf16_f32 v89, v84, v85
	ds_read_b128 v[82:85], v134 offset:1536
	s_mov_b64 s[16:17], 0x30000
	v_mov_b32_e32 v130, v135
	v_mov_b32_e32 v132, v137
	s_waitcnt lgkmcnt(0)
	v_mov_b32_e32 v92, v83
	v_mov_b32_e32 v93, v84
	v_mov_b32_e32 v83, v85
	v_pk_add_f32 v[82:83], v[92:93], v[82:83]
	s_nop 0
	v_add_f32_e32 v82, v82, v83
	v_fmamk_f32 v82, v82, 0x3c000000, v192
	v_mul_f32_e32 v83, 0x4f800000, v82
	v_cmp_gt_f32_e32 vcc, s23, v82
	s_nop 1
	v_cndmask_b32_e32 v84, v82, v83, vcc
	v_sqrt_f32_e32 v85, v84
	v_lshl_add_u64 v[82:83], v[90:91], 0, s[16:17]
	global_store_dwordx4 v[82:83], v[86:89], off offset:256 nt
	v_mov_b32_e32 v82, s24
	v_add_u32_e32 v83, -1, v85
	v_fma_f32 v86, -v83, v85, v84
	v_cmp_ge_f32_e64 s[16:17], 0, v86
	v_add_u32_e32 v86, 1, v85
	v_cndmask_b32_e64 v82, v176, v82, s[4:5]
	v_cndmask_b32_e64 v83, v85, v83, s[16:17]
	v_fma_f32 v85, -v86, v85, v84
	v_cmp_lt_f32_e64 s[16:17], 0, v85
	s_nop 1
	v_cndmask_b32_e64 v83, v83, v86, s[16:17]
	v_mul_f32_e32 v85, 0x37800000, v83
	v_cndmask_b32_e32 v83, v83, v85, vcc
	v_cmp_class_f32_e32 vcc, v84, v193
	s_nop 1
	v_cndmask_b32_e32 v83, v83, v84, vcc
	v_div_scale_f32 v86, s[16:17], v83, v83, 1.0
	v_rcp_f32_e32 v87, v86
	v_lshl_or_b32 v84, v82, 6, v178
	v_ashrrev_i32_e32 v85, 31, v84
	v_fma_f32 v82, -v86, v87, 1.0
	v_fmac_f32_e32 v87, v82, v87
	v_div_scale_f32 v82, vcc, 1.0, v83, 1.0
	v_mul_f32_e32 v88, v82, v87
	v_fma_f32 v89, -v86, v88, v82
	v_fmac_f32_e32 v88, v89, v87
	v_fma_f32 v82, -v86, v88, v82
	v_div_fmas_f32 v82, v82, v87, v88
	v_div_fixup_f32 v86, v82, v83, 1.0
	v_pk_mul_f32 v[78:79], v[78:79], v[86:87] op_sel_hi:[1,0]
	v_pk_mul_f32 v[80:81], v[80:81], v[86:87] op_sel_hi:[1,0]
	v_pk_mul_f32 v[74:75], v[74:75], v[86:87] op_sel_hi:[1,0]
	v_pk_mul_f32 v[76:77], v[76:77], v[86:87] op_sel_hi:[1,0]
	v_pk_mul_f32 v[82:83], v[130:131], v[80:81]
	v_pk_mul_f32 v[78:79], v[124:125], v[78:79]
	v_pk_mul_f32 v[80:81], v[132:133], v[76:77]
	v_pk_mul_f32 v[76:77], v[122:123], v[74:75]
	s_and_b64 vcc, exec, s[14:15]
	v_lshl_add_u64 v[74:75], v[84:85], 2, s[42:43]
	s_cbranch_vccnz .LBB0_571
	global_load_dwordx4 v[84:87], v[74:75], off offset:16
	global_load_dwordx4 v[88:91], v[74:75], off
	s_waitcnt vmcnt(1)
	v_pk_mul_f32 v[96:97], v[76:77], v[84:85] op_sel:[1,1] op_sel_hi:[1,0]
	s_waitcnt vmcnt(0)
	v_pk_mul_f32 v[94:95], v[78:79], v[88:89] op_sel:[1,1] op_sel_hi:[1,0]
	v_pk_mul_f32 v[92:93], v[78:79], v[88:89]
	v_pk_fma_f32 v[78:79], v[78:79], v[88:89], v[94:95] op_sel_hi:[0,1,1]
	v_mul_f32_e32 v78, v83, v91
	v_pk_fma_f32 v[88:89], v[82:83], v[90:91], v[78:79] op_sel_hi:[1,1,0] neg_lo:[0,0,1] neg_hi:[0,0,1]
	v_mul_f32_e32 v78, v83, v90
	v_pk_fma_f32 v[90:91], v[82:83], v[90:91], v[78:79] op_sel:[0,1,0] op_sel_hi:[1,0,0]
	v_pk_mul_f32 v[82:83], v[76:77], v[84:85]
	v_pk_fma_f32 v[76:77], v[76:77], v[84:85], v[96:97] op_sel_hi:[0,1,1]
	v_mul_f32_e32 v76, v81, v87
	v_pk_fma_f32 v[84:85], v[80:81], v[86:87], v[76:77] op_sel_hi:[1,1,0] neg_lo:[0,0,1] neg_hi:[0,0,1]
	v_mul_f32_e32 v76, v81, v86
	v_pk_fma_f32 v[86:87], v[80:81], v[86:87], v[76:77] op_sel:[0,1,0] op_sel_hi:[1,0,0]
	v_sub_f32_e32 v76, v82, v96
	v_sub_f32_e32 v78, v92, v94
	v_mov_b32_e32 v80, v84
	v_mov_b32_e32 v81, v86
	v_mov_b32_e32 v82, v88
	v_mov_b32_e32 v83, v90
.LBB0_571:
	v_cvt_pk_bf16_f32 v84, v78, v79
	v_cvt_pk_bf16_f32 v85, v82, v83
	v_cvt_pk_bf16_f32 v86, v76, v77
	v_lshl_add_u64 v[76:77], v[126:127], 0, v[146:147]
	s_mov_b32 s10, 0x48000
	v_add_co_u32_e32 v78, vcc, s10, v76
	v_cvt_pk_bf16_f32 v87, v80, v81
	s_nop 1
	v_addc_co_u32_e32 v79, vcc, 0, v77, vcc
	global_store_dwordx4 v[78:79], v[84:87], off nt
	ds_read_b128 v[78:81], v134 offset:1552
	s_waitcnt lgkmcnt(0)
	v_mov_b32_e32 v82, v79
	v_mov_b32_e32 v83, v80
	v_mov_b32_e32 v79, v81
	v_pk_add_f32 v[78:79], v[82:83], v[78:79]
	s_nop 0
	v_add_f32_e32 v78, v78, v79
	v_fmamk_f32 v78, v78, 0x3c000000, v192
	v_cmp_gt_f32_e32 vcc, s23, v78
	v_mul_f32_e32 v79, 0x4f800000, v78
	s_nop 0
	v_cndmask_b32_e32 v78, v78, v79, vcc
	v_sqrt_f32_e32 v79, v78
	s_nop 0
	v_add_u32_e32 v80, -1, v79
	v_fma_f32 v81, -v80, v79, v78
	v_cmp_ge_f32_e64 s[16:17], 0, v81
	v_add_u32_e32 v81, 1, v79
	s_nop 0
	v_cndmask_b32_e64 v80, v79, v80, s[16:17]
	v_fma_f32 v79, -v81, v79, v78
	v_cmp_lt_f32_e64 s[16:17], 0, v79
	s_nop 1
	v_cndmask_b32_e64 v79, v80, v81, s[16:17]
	v_mul_f32_e32 v80, 0x37800000, v79
	v_cndmask_b32_e32 v79, v79, v80, vcc
	v_cmp_class_f32_e32 vcc, v78, v193
	s_nop 1
	v_cndmask_b32_e32 v78, v79, v78, vcc
	v_div_scale_f32 v79, s[16:17], v78, v78, 1.0
	v_rcp_f32_e32 v80, v79
	s_nop 0
	v_fma_f32 v81, -v79, v80, 1.0
	v_fmac_f32_e32 v80, v81, v80
	v_div_scale_f32 v81, vcc, 1.0, v78, 1.0
	v_mul_f32_e32 v82, v81, v80
	v_fma_f32 v83, -v79, v82, v81
	v_fmac_f32_e32 v82, v83, v80
	v_fma_f32 v79, -v79, v82, v81
	v_div_fmas_f32 v79, v79, v80, v82
	v_div_fixup_f32 v78, v79, v78, 1.0
	v_pk_mul_f32 v[70:71], v[70:71], v[78:79] op_sel_hi:[1,0]
	v_pk_mul_f32 v[72:73], v[72:73], v[78:79] op_sel_hi:[1,0]
	v_pk_mul_f32 v[66:67], v[66:67], v[78:79] op_sel_hi:[1,0]
	v_pk_mul_f32 v[68:69], v[68:69], v[78:79] op_sel_hi:[1,0]
	v_pk_mul_f32 v[72:73], v[130:131], v[72:73]
	v_pk_mul_f32 v[70:71], v[124:125], v[70:71]
	v_pk_mul_f32 v[68:69], v[132:133], v[68:69]
	v_pk_mul_f32 v[66:67], v[122:123], v[66:67]
	s_and_b64 vcc, exec, s[14:15]
	s_cbranch_vccnz .LBB0_573
	global_load_dwordx4 v[78:81], v[74:75], off offset:16
	global_load_dwordx4 v[82:85], v[74:75], off
	s_waitcnt vmcnt(1)
	v_pk_mul_f32 v[88:89], v[66:67], v[78:79] op_sel:[1,1] op_sel_hi:[1,0]
	s_waitcnt vmcnt(0)
	v_pk_mul_f32 v[86:87], v[70:71], v[82:83] op_sel:[1,1] op_sel_hi:[1,0]
	v_pk_mul_f32 v[74:75], v[70:71], v[82:83]
	v_pk_fma_f32 v[70:71], v[70:71], v[82:83], v[86:87] op_sel_hi:[0,1,1]
	v_mul_f32_e32 v70, v73, v85
	v_pk_fma_f32 v[82:83], v[72:73], v[84:85], v[70:71] op_sel_hi:[1,1,0] neg_lo:[0,0,1] neg_hi:[0,0,1]
	v_mul_f32_e32 v70, v73, v84
	v_pk_fma_f32 v[84:85], v[72:73], v[84:85], v[70:71] op_sel:[0,1,0] op_sel_hi:[1,0,0]
	v_pk_mul_f32 v[72:73], v[66:67], v[78:79]
	v_pk_fma_f32 v[66:67], v[66:67], v[78:79], v[88:89] op_sel_hi:[0,1,1]
	v_mul_f32_e32 v66, v69, v81
	v_pk_fma_f32 v[78:79], v[68:69], v[80:81], v[66:67] op_sel_hi:[1,1,0] neg_lo:[0,0,1] neg_hi:[0,0,1]
	v_mul_f32_e32 v66, v69, v80
	v_pk_fma_f32 v[80:81], v[68:69], v[80:81], v[66:67] op_sel:[0,1,0] op_sel_hi:[1,0,0]
	v_sub_f32_e32 v66, v72, v88
	v_sub_f32_e32 v70, v74, v86
	v_mov_b32_e32 v68, v78
	v_mov_b32_e32 v69, v80
	v_mov_b32_e32 v72, v82
	v_mov_b32_e32 v73, v84
.LBB0_573:
	v_cvt_pk_bf16_f32 v70, v70, v71
	v_cvt_pk_bf16_f32 v71, v72, v73
	v_cvt_pk_bf16_f32 v72, v66, v67
	v_cvt_pk_bf16_f32 v73, v68, v69
	ds_read_b128 v[66:69], v134 offset:4096
	s_mov_b64 s[16:17], 0x48000
	v_lshl_add_u64 v[74:75], v[76:77], 0, s[16:17]
	global_store_dwordx4 v[74:75], v[70:73], off offset:256 nt
	s_add_i32 s18, s24, 2
	s_waitcnt lgkmcnt(0)
	v_mov_b32_e32 v76, v67
	v_mov_b32_e32 v77, v68
	v_mov_b32_e32 v67, v69
	v_pk_add_f32 v[66:67], v[76:77], v[66:67]
	v_mov_b32_e32 v68, s18
	v_add_f32_e32 v66, v66, v67
	v_fmamk_f32 v66, v66, 0x3c000000, v192
	v_mul_f32_e32 v67, 0x4f800000, v66
	v_cmp_gt_f32_e32 vcc, s23, v66
	v_cndmask_b32_e64 v68, v1, v68, s[4:5]
	v_lshl_or_b32 v68, v68, 6, v178
	v_cndmask_b32_e32 v66, v66, v67, vcc
	v_sqrt_f32_e32 v67, v66
	v_mov_b32_e32 v130, v135
	v_mov_b32_e32 v132, v137
	v_add_u32_e32 v69, -1, v67
	v_fma_f32 v70, -v69, v67, v66
	v_cmp_ge_f32_e64 s[16:17], 0, v70
	v_add_u32_e32 v70, 1, v67
	s_nop 0
	v_cndmask_b32_e64 v69, v67, v69, s[16:17]
	v_fma_f32 v67, -v70, v67, v66
	v_cmp_lt_f32_e64 s[16:17], 0, v67
	s_nop 1
	v_cndmask_b32_e64 v67, v69, v70, s[16:17]
	v_mul_f32_e32 v69, 0x37800000, v67
	v_cndmask_b32_e32 v67, v67, v69, vcc
	v_cmp_class_f32_e32 vcc, v66, v193
	v_ashrrev_i32_e32 v69, 31, v68
	s_nop 0
	v_cndmask_b32_e32 v66, v67, v66, vcc
	v_div_scale_f32 v67, s[16:17], v66, v66, 1.0
	v_rcp_f32_e32 v70, v67
	s_nop 0
	v_fma_f32 v71, -v67, v70, 1.0
	v_fmac_f32_e32 v70, v71, v70
	v_div_scale_f32 v71, vcc, 1.0, v66, 1.0
	v_mul_f32_e32 v72, v71, v70
	v_fma_f32 v73, -v67, v72, v71
	v_fmac_f32_e32 v72, v73, v70
	v_fma_f32 v67, -v67, v72, v71
	v_div_fmas_f32 v67, v67, v70, v72
	v_div_fixup_f32 v70, v67, v66, 1.0
	v_pk_mul_f32 v[62:63], v[62:63], v[70:71] op_sel_hi:[1,0]
	v_pk_mul_f32 v[64:65], v[64:65], v[70:71] op_sel_hi:[1,0]
	v_pk_mul_f32 v[58:59], v[58:59], v[70:71] op_sel_hi:[1,0]
	v_pk_mul_f32 v[60:61], v[60:61], v[70:71] op_sel_hi:[1,0]
	v_pk_mul_f32 v[66:67], v[130:131], v[64:65]
	v_pk_mul_f32 v[62:63], v[124:125], v[62:63]
	v_pk_mul_f32 v[64:65], v[132:133], v[60:61]
	v_pk_mul_f32 v[58:59], v[122:123], v[58:59]
	s_and_b64 vcc, exec, s[14:15]
	v_lshl_add_u64 v[60:61], v[68:69], 2, s[42:43]
	s_cbranch_vccnz .LBB0_575
	global_load_dwordx4 v[68:71], v[60:61], off offset:16
	global_load_dwordx4 v[72:75], v[60:61], off
	s_waitcnt vmcnt(1)
	v_pk_mul_f32 v[80:81], v[58:59], v[68:69] op_sel:[1,1] op_sel_hi:[1,0]
	s_waitcnt vmcnt(0)
	v_pk_mul_f32 v[78:79], v[62:63], v[72:73] op_sel:[1,1] op_sel_hi:[1,0]
	v_pk_mul_f32 v[76:77], v[62:63], v[72:73]
	v_pk_fma_f32 v[62:63], v[62:63], v[72:73], v[78:79] op_sel_hi:[0,1,1]
	v_mul_f32_e32 v62, v67, v75
	v_pk_fma_f32 v[72:73], v[66:67], v[74:75], v[62:63] op_sel_hi:[1,1,0] neg_lo:[0,0,1] neg_hi:[0,0,1]
	v_mul_f32_e32 v62, v67, v74
	v_pk_fma_f32 v[74:75], v[66:67], v[74:75], v[62:63] op_sel:[0,1,0] op_sel_hi:[1,0,0]
	v_pk_mul_f32 v[66:67], v[58:59], v[68:69]
	v_pk_fma_f32 v[58:59], v[58:59], v[68:69], v[80:81] op_sel_hi:[0,1,1]
	v_mul_f32_e32 v58, v65, v71
	v_pk_fma_f32 v[68:69], v[64:65], v[70:71], v[58:59] op_sel_hi:[1,1,0] neg_lo:[0,0,1] neg_hi:[0,0,1]
	v_mul_f32_e32 v58, v65, v70
	v_pk_fma_f32 v[70:71], v[64:65], v[70:71], v[58:59] op_sel:[0,1,0] op_sel_hi:[1,0,0]
	v_sub_f32_e32 v58, v66, v80
	v_sub_f32_e32 v62, v76, v78
	v_mov_b32_e32 v64, v68
	v_mov_b32_e32 v65, v70
	v_mov_b32_e32 v66, v72
	v_mov_b32_e32 v67, v74
.LBB0_575:
	v_cvt_pk_bf16_f32 v68, v62, v63
	v_cvt_pk_bf16_f32 v69, v66, v67
	v_cvt_pk_bf16_f32 v70, v58, v59
	v_lshl_add_u64 v[58:59], v[126:127], 0, v[146:147]
	v_add_co_u32_e32 v62, vcc, s58, v58
	v_cvt_pk_bf16_f32 v71, v64, v65
	s_nop 1
	v_addc_co_u32_e32 v63, vcc, 0, v59, vcc
	global_store_dwordx4 v[62:63], v[68:71], off nt
	ds_read_b128 v[62:65], v134 offset:4112
	s_waitcnt lgkmcnt(0)
	v_mov_b32_e32 v66, v63
	v_mov_b32_e32 v67, v64
	v_mov_b32_e32 v63, v65
	v_pk_add_f32 v[62:63], v[66:67], v[62:63]
	s_nop 0
	v_add_f32_e32 v62, v62, v63
	v_fmamk_f32 v62, v62, 0x3c000000, v192
	v_cmp_gt_f32_e32 vcc, s23, v62
	v_mul_f32_e32 v63, 0x4f800000, v62
	s_nop 0
	v_cndmask_b32_e32 v62, v62, v63, vcc
	v_sqrt_f32_e32 v63, v62
	s_nop 0
	v_add_u32_e32 v64, -1, v63
	v_fma_f32 v65, -v64, v63, v62
	v_cmp_ge_f32_e64 s[16:17], 0, v65
	v_add_u32_e32 v65, 1, v63
	s_nop 0
	v_cndmask_b32_e64 v64, v63, v64, s[16:17]
	v_fma_f32 v63, -v65, v63, v62
	v_cmp_lt_f32_e64 s[16:17], 0, v63
	s_nop 1
	v_cndmask_b32_e64 v63, v64, v65, s[16:17]
	v_mul_f32_e32 v64, 0x37800000, v63
	v_cndmask_b32_e32 v63, v63, v64, vcc
	v_cmp_class_f32_e32 vcc, v62, v193
	s_nop 1
	v_cndmask_b32_e32 v62, v63, v62, vcc
	v_div_scale_f32 v63, s[16:17], v62, v62, 1.0
	v_rcp_f32_e32 v64, v63
	s_nop 0
	v_fma_f32 v65, -v63, v64, 1.0
	v_fmac_f32_e32 v64, v65, v64
	v_div_scale_f32 v65, vcc, 1.0, v62, 1.0
	v_mul_f32_e32 v66, v65, v64
	v_fma_f32 v67, -v63, v66, v65
	v_fmac_f32_e32 v66, v67, v64
	v_fma_f32 v63, -v63, v66, v65
	v_div_fmas_f32 v63, v63, v64, v66
	v_div_fixup_f32 v62, v63, v62, 1.0
	v_pk_mul_f32 v[54:55], v[54:55], v[62:63] op_sel_hi:[1,0]
	v_pk_mul_f32 v[56:57], v[56:57], v[62:63] op_sel_hi:[1,0]
	v_pk_mul_f32 v[50:51], v[50:51], v[62:63] op_sel_hi:[1,0]
	v_pk_mul_f32 v[52:53], v[52:53], v[62:63] op_sel_hi:[1,0]
	v_pk_mul_f32 v[56:57], v[130:131], v[56:57]
	v_pk_mul_f32 v[54:55], v[124:125], v[54:55]
	v_pk_mul_f32 v[52:53], v[132:133], v[52:53]
	v_pk_mul_f32 v[50:51], v[122:123], v[50:51]
	s_and_b64 vcc, exec, s[14:15]
	s_cbranch_vccnz .LBB0_577
	global_load_dwordx4 v[62:65], v[60:61], off offset:16
	global_load_dwordx4 v[66:69], v[60:61], off
	s_waitcnt vmcnt(1)
	v_pk_mul_f32 v[72:73], v[50:51], v[62:63] op_sel:[1,1] op_sel_hi:[1,0]
	s_waitcnt vmcnt(0)
	v_pk_mul_f32 v[70:71], v[54:55], v[66:67] op_sel:[1,1] op_sel_hi:[1,0]
	v_pk_mul_f32 v[60:61], v[54:55], v[66:67]
	v_pk_fma_f32 v[54:55], v[54:55], v[66:67], v[70:71] op_sel_hi:[0,1,1]
	v_mul_f32_e32 v54, v57, v69
	v_pk_fma_f32 v[66:67], v[56:57], v[68:69], v[54:55] op_sel_hi:[1,1,0] neg_lo:[0,0,1] neg_hi:[0,0,1]
	v_mul_f32_e32 v54, v57, v68
	v_pk_fma_f32 v[68:69], v[56:57], v[68:69], v[54:55] op_sel:[0,1,0] op_sel_hi:[1,0,0]
	v_pk_mul_f32 v[56:57], v[50:51], v[62:63]
	v_pk_fma_f32 v[50:51], v[50:51], v[62:63], v[72:73] op_sel_hi:[0,1,1]
	v_mul_f32_e32 v50, v53, v65
	v_pk_fma_f32 v[62:63], v[52:53], v[64:65], v[50:51] op_sel_hi:[1,1,0] neg_lo:[0,0,1] neg_hi:[0,0,1]
	v_mul_f32_e32 v50, v53, v64
	v_pk_fma_f32 v[64:65], v[52:53], v[64:65], v[50:51] op_sel:[0,1,0] op_sel_hi:[1,0,0]
	v_sub_f32_e32 v50, v56, v72
	v_sub_f32_e32 v54, v60, v70
	v_mov_b32_e32 v52, v62
	v_mov_b32_e32 v53, v64
	v_mov_b32_e32 v56, v66
	v_mov_b32_e32 v57, v68
.LBB0_577:
	v_cvt_pk_bf16_f32 v54, v54, v55
	v_cvt_pk_bf16_f32 v55, v56, v57
	v_cvt_pk_bf16_f32 v56, v50, v51
	v_cvt_pk_bf16_f32 v57, v52, v53
	ds_read_b128 v[50:53], v134 offset:4608
	s_mov_b64 s[16:17], 0xc0000
	v_mov_b32_e32 v130, v135
	v_mov_b32_e32 v132, v137
	s_waitcnt lgkmcnt(0)
	v_mov_b32_e32 v60, v51
	v_mov_b32_e32 v61, v52
	v_mov_b32_e32 v51, v53
	v_pk_add_f32 v[50:51], v[60:61], v[50:51]
	s_nop 0
	v_add_f32_e32 v50, v50, v51
	v_fmamk_f32 v50, v50, 0x3c000000, v192
	v_mul_f32_e32 v51, 0x4f800000, v50
	v_cmp_gt_f32_e32 vcc, s23, v50
	s_nop 1
	v_cndmask_b32_e32 v52, v50, v51, vcc
	v_sqrt_f32_e32 v53, v52
	v_lshl_add_u64 v[50:51], v[58:59], 0, s[16:17]
	global_store_dwordx4 v[50:51], v[54:57], off offset:256 nt
	v_mov_b32_e32 v50, s18
	v_add_u32_e32 v51, -1, v53
	v_fma_f32 v54, -v51, v53, v52
	v_cmp_ge_f32_e64 s[16:17], 0, v54
	v_add_u32_e32 v54, 1, v53
	v_cndmask_b32_e64 v50, v174, v50, s[4:5]
	v_cndmask_b32_e64 v51, v53, v51, s[16:17]
	v_fma_f32 v53, -v54, v53, v52
	v_cmp_lt_f32_e64 s[16:17], 0, v53
	s_nop 1
	v_cndmask_b32_e64 v51, v51, v54, s[16:17]
	v_mul_f32_e32 v53, 0x37800000, v51
	v_cndmask_b32_e32 v51, v51, v53, vcc
	v_cmp_class_f32_e32 vcc, v52, v193
	s_nop 1
	v_cndmask_b32_e32 v51, v51, v52, vcc
	v_div_scale_f32 v54, s[16:17], v51, v51, 1.0
	v_rcp_f32_e32 v55, v54
	v_lshl_or_b32 v52, v50, 6, v178
	v_ashrrev_i32_e32 v53, 31, v52
	v_fma_f32 v50, -v54, v55, 1.0
	v_fmac_f32_e32 v55, v50, v55
	v_div_scale_f32 v50, vcc, 1.0, v51, 1.0
	v_mul_f32_e32 v56, v50, v55
	v_fma_f32 v57, -v54, v56, v50
	v_fmac_f32_e32 v56, v57, v55
	v_fma_f32 v50, -v54, v56, v50
	v_div_fmas_f32 v50, v50, v55, v56
	v_div_fixup_f32 v54, v50, v51, 1.0
	v_pk_mul_f32 v[46:47], v[46:47], v[54:55] op_sel_hi:[1,0]
	v_pk_mul_f32 v[48:49], v[48:49], v[54:55] op_sel_hi:[1,0]
	v_pk_mul_f32 v[42:43], v[42:43], v[54:55] op_sel_hi:[1,0]
	v_pk_mul_f32 v[44:45], v[44:45], v[54:55] op_sel_hi:[1,0]
	v_pk_mul_f32 v[50:51], v[130:131], v[48:49]
	v_pk_mul_f32 v[46:47], v[124:125], v[46:47]
	v_pk_mul_f32 v[48:49], v[132:133], v[44:45]
	v_pk_mul_f32 v[42:43], v[122:123], v[42:43]
	s_and_b64 vcc, exec, s[14:15]
	v_lshl_add_u64 v[44:45], v[52:53], 2, s[42:43]
	s_cbranch_vccnz .LBB0_579
	global_load_dwordx4 v[52:55], v[44:45], off offset:16
	global_load_dwordx4 v[56:59], v[44:45], off
	s_waitcnt vmcnt(1)
	v_pk_mul_f32 v[64:65], v[42:43], v[52:53] op_sel:[1,1] op_sel_hi:[1,0]
	s_waitcnt vmcnt(0)
	v_pk_mul_f32 v[62:63], v[46:47], v[56:57] op_sel:[1,1] op_sel_hi:[1,0]
	v_pk_mul_f32 v[60:61], v[46:47], v[56:57]
	v_pk_fma_f32 v[46:47], v[46:47], v[56:57], v[62:63] op_sel_hi:[0,1,1]
	v_mul_f32_e32 v46, v51, v59
	v_pk_fma_f32 v[56:57], v[50:51], v[58:59], v[46:47] op_sel_hi:[1,1,0] neg_lo:[0,0,1] neg_hi:[0,0,1]
	v_mul_f32_e32 v46, v51, v58
	v_pk_fma_f32 v[58:59], v[50:51], v[58:59], v[46:47] op_sel:[0,1,0] op_sel_hi:[1,0,0]
	v_pk_mul_f32 v[50:51], v[42:43], v[52:53]
	v_pk_fma_f32 v[42:43], v[42:43], v[52:53], v[64:65] op_sel_hi:[0,1,1]
	v_mul_f32_e32 v42, v49, v55
	v_pk_fma_f32 v[52:53], v[48:49], v[54:55], v[42:43] op_sel_hi:[1,1,0] neg_lo:[0,0,1] neg_hi:[0,0,1]
	v_mul_f32_e32 v42, v49, v54
	v_pk_fma_f32 v[54:55], v[48:49], v[54:55], v[42:43] op_sel:[0,1,0] op_sel_hi:[1,0,0]
	v_sub_f32_e32 v42, v50, v64
	v_sub_f32_e32 v46, v60, v62
	v_mov_b32_e32 v48, v52
	v_mov_b32_e32 v49, v54
	v_mov_b32_e32 v50, v56
	v_mov_b32_e32 v51, v58
.LBB0_579:
	v_cvt_pk_bf16_f32 v52, v46, v47
	v_cvt_pk_bf16_f32 v53, v50, v51
	v_cvt_pk_bf16_f32 v54, v42, v43
	v_lshl_add_u64 v[42:43], v[126:127], 0, v[146:147]
	v_add_co_u32_e32 v46, vcc, s59, v42
	v_cvt_pk_bf16_f32 v55, v48, v49
	s_nop 1
	v_addc_co_u32_e32 v47, vcc, 0, v43, vcc
	global_store_dwordx4 v[46:47], v[52:55], off nt
	ds_read_b128 v[46:49], v134 offset:4624
	s_waitcnt lgkmcnt(0)
	v_mov_b32_e32 v50, v47
	v_mov_b32_e32 v51, v48
	v_mov_b32_e32 v47, v49
	v_pk_add_f32 v[46:47], v[50:51], v[46:47]
	s_nop 0
	v_add_f32_e32 v46, v46, v47
	v_fmamk_f32 v46, v46, 0x3c000000, v192
	v_cmp_gt_f32_e32 vcc, s23, v46
	v_mul_f32_e32 v47, 0x4f800000, v46
	s_nop 0
	v_cndmask_b32_e32 v46, v46, v47, vcc
	v_sqrt_f32_e32 v47, v46
	s_nop 0
	v_add_u32_e32 v48, -1, v47
	v_fma_f32 v49, -v48, v47, v46
	v_cmp_ge_f32_e64 s[16:17], 0, v49
	v_add_u32_e32 v49, 1, v47
	s_nop 0
	v_cndmask_b32_e64 v48, v47, v48, s[16:17]
	v_fma_f32 v47, -v49, v47, v46
	v_cmp_lt_f32_e64 s[16:17], 0, v47
	s_nop 1
	v_cndmask_b32_e64 v47, v48, v49, s[16:17]
	v_mul_f32_e32 v48, 0x37800000, v47
	v_cndmask_b32_e32 v47, v47, v48, vcc
	v_cmp_class_f32_e32 vcc, v46, v193
	s_nop 1
	v_cndmask_b32_e32 v46, v47, v46, vcc
	v_div_scale_f32 v47, s[16:17], v46, v46, 1.0
	v_rcp_f32_e32 v48, v47
	s_nop 0
	v_fma_f32 v49, -v47, v48, 1.0
	v_fmac_f32_e32 v48, v49, v48
	v_div_scale_f32 v49, vcc, 1.0, v46, 1.0
	v_mul_f32_e32 v50, v49, v48
	v_fma_f32 v51, -v47, v50, v49
	v_fmac_f32_e32 v50, v51, v48
	v_fma_f32 v47, -v47, v50, v49
	v_div_fmas_f32 v47, v47, v48, v50
	v_div_fixup_f32 v46, v47, v46, 1.0
	v_pk_mul_f32 v[38:39], v[38:39], v[46:47] op_sel_hi:[1,0]
	v_pk_mul_f32 v[40:41], v[40:41], v[46:47] op_sel_hi:[1,0]
	v_pk_mul_f32 v[34:35], v[34:35], v[46:47] op_sel_hi:[1,0]
	v_pk_mul_f32 v[36:37], v[36:37], v[46:47] op_sel_hi:[1,0]
	v_pk_mul_f32 v[40:41], v[130:131], v[40:41]
	v_pk_mul_f32 v[38:39], v[124:125], v[38:39]
	v_pk_mul_f32 v[36:37], v[132:133], v[36:37]
	v_pk_mul_f32 v[34:35], v[122:123], v[34:35]
	s_and_b64 vcc, exec, s[14:15]
	s_cbranch_vccnz .LBB0_581
	global_load_dwordx4 v[46:49], v[44:45], off offset:16
	global_load_dwordx4 v[50:53], v[44:45], off
	s_waitcnt vmcnt(1)
	v_pk_mul_f32 v[56:57], v[34:35], v[46:47] op_sel:[1,1] op_sel_hi:[1,0]
	s_waitcnt vmcnt(0)
	v_pk_mul_f32 v[54:55], v[38:39], v[50:51] op_sel:[1,1] op_sel_hi:[1,0]
	v_pk_mul_f32 v[44:45], v[38:39], v[50:51]
	v_pk_fma_f32 v[38:39], v[38:39], v[50:51], v[54:55] op_sel_hi:[0,1,1]
	v_mul_f32_e32 v38, v41, v53
	v_pk_fma_f32 v[50:51], v[40:41], v[52:53], v[38:39] op_sel_hi:[1,1,0] neg_lo:[0,0,1] neg_hi:[0,0,1]
	v_mul_f32_e32 v38, v41, v52
	v_pk_fma_f32 v[52:53], v[40:41], v[52:53], v[38:39] op_sel:[0,1,0] op_sel_hi:[1,0,0]
	v_pk_mul_f32 v[40:41], v[34:35], v[46:47]
	v_pk_fma_f32 v[34:35], v[34:35], v[46:47], v[56:57] op_sel_hi:[0,1,1]
	v_mul_f32_e32 v34, v37, v49
	v_pk_fma_f32 v[46:47], v[36:37], v[48:49], v[34:35] op_sel_hi:[1,1,0] neg_lo:[0,0,1] neg_hi:[0,0,1]
	v_mul_f32_e32 v34, v37, v48
	v_pk_fma_f32 v[48:49], v[36:37], v[48:49], v[34:35] op_sel:[0,1,0] op_sel_hi:[1,0,0]
	v_sub_f32_e32 v34, v40, v56
	v_sub_f32_e32 v38, v44, v54
	v_mov_b32_e32 v36, v46
	v_mov_b32_e32 v37, v48
	v_mov_b32_e32 v40, v50
	v_mov_b32_e32 v41, v52
.LBB0_581:
	v_cvt_pk_bf16_f32 v38, v38, v39
	v_cvt_pk_bf16_f32 v39, v40, v41
	v_cvt_pk_bf16_f32 v40, v34, v35
	v_cvt_pk_bf16_f32 v41, v36, v37
	ds_read_b128 v[34:37], v134 offset:5120
	v_mov_b32_e32 v130, v135
	v_mov_b32_e32 v132, v137
	s_waitcnt lgkmcnt(0)
	v_mov_b32_e32 v44, v35
	v_mov_b32_e32 v45, v36
	v_mov_b32_e32 v35, v37
	v_pk_add_f32 v[34:35], v[44:45], v[34:35]
	s_nop 0
	v_add_f32_e32 v34, v34, v35
	v_fmamk_f32 v34, v34, 0x3c000000, v192
	v_mul_f32_e32 v35, 0x4f800000, v34
	v_cmp_gt_f32_e32 vcc, s23, v34
	s_nop 1
	v_cndmask_b32_e32 v36, v34, v35, vcc
	v_sqrt_f32_e32 v37, v36
	v_lshl_add_u64 v[34:35], v[42:43], 0, s[70:71]
	global_store_dwordx4 v[34:35], v[38:41], off offset:256 nt
	v_mov_b32_e32 v34, s18
	v_add_u32_e32 v35, -1, v37
	v_fma_f32 v38, -v35, v37, v36
	v_cmp_ge_f32_e64 s[16:17], 0, v38
	v_add_u32_e32 v38, 1, v37
	v_cndmask_b32_e64 v34, v175, v34, s[4:5]
	v_cndmask_b32_e64 v35, v37, v35, s[16:17]
	v_fma_f32 v37, -v38, v37, v36
	v_cmp_lt_f32_e64 s[16:17], 0, v37
	s_nop 1
	v_cndmask_b32_e64 v35, v35, v38, s[16:17]
	v_mul_f32_e32 v37, 0x37800000, v35
	v_cndmask_b32_e32 v35, v35, v37, vcc
	v_cmp_class_f32_e32 vcc, v36, v193
	s_nop 1
	v_cndmask_b32_e32 v35, v35, v36, vcc
	v_div_scale_f32 v38, s[16:17], v35, v35, 1.0
	v_rcp_f32_e32 v39, v38
	v_lshl_or_b32 v36, v34, 6, v178
	v_ashrrev_i32_e32 v37, 31, v36
	v_fma_f32 v34, -v38, v39, 1.0
	v_fmac_f32_e32 v39, v34, v39
	v_div_scale_f32 v34, vcc, 1.0, v35, 1.0
	v_mul_f32_e32 v40, v34, v39
	v_fma_f32 v41, -v38, v40, v34
	v_fmac_f32_e32 v40, v41, v39
	v_fma_f32 v34, -v38, v40, v34
	v_div_fmas_f32 v34, v34, v39, v40
	v_div_fixup_f32 v38, v34, v35, 1.0
	v_pk_mul_f32 v[30:31], v[30:31], v[38:39] op_sel_hi:[1,0]
	v_pk_mul_f32 v[32:33], v[32:33], v[38:39] op_sel_hi:[1,0]
	v_pk_mul_f32 v[26:27], v[26:27], v[38:39] op_sel_hi:[1,0]
	v_pk_mul_f32 v[28:29], v[28:29], v[38:39] op_sel_hi:[1,0]
	v_pk_mul_f32 v[34:35], v[130:131], v[32:33]
	v_pk_mul_f32 v[30:31], v[124:125], v[30:31]
	v_pk_mul_f32 v[32:33], v[132:133], v[28:29]
	v_pk_mul_f32 v[26:27], v[122:123], v[26:27]
	s_and_b64 vcc, exec, s[14:15]
	v_lshl_add_u64 v[28:29], v[36:37], 2, s[42:43]
	s_cbranch_vccnz .LBB0_583
	global_load_dwordx4 v[36:39], v[28:29], off offset:16
	global_load_dwordx4 v[40:43], v[28:29], off
	s_waitcnt vmcnt(1)
	v_pk_mul_f32 v[48:49], v[26:27], v[36:37] op_sel:[1,1] op_sel_hi:[1,0]
	s_waitcnt vmcnt(0)
	v_pk_mul_f32 v[46:47], v[30:31], v[40:41] op_sel:[1,1] op_sel_hi:[1,0]
	v_pk_mul_f32 v[44:45], v[30:31], v[40:41]
	v_pk_fma_f32 v[30:31], v[30:31], v[40:41], v[46:47] op_sel_hi:[0,1,1]
	v_mul_f32_e32 v30, v35, v43
	v_pk_fma_f32 v[40:41], v[34:35], v[42:43], v[30:31] op_sel_hi:[1,1,0] neg_lo:[0,0,1] neg_hi:[0,0,1]
	v_mul_f32_e32 v30, v35, v42
	v_pk_fma_f32 v[42:43], v[34:35], v[42:43], v[30:31] op_sel:[0,1,0] op_sel_hi:[1,0,0]
	v_pk_mul_f32 v[34:35], v[26:27], v[36:37]
	v_pk_fma_f32 v[26:27], v[26:27], v[36:37], v[48:49] op_sel_hi:[0,1,1]
	v_mul_f32_e32 v26, v33, v39
	v_pk_fma_f32 v[36:37], v[32:33], v[38:39], v[26:27] op_sel_hi:[1,1,0] neg_lo:[0,0,1] neg_hi:[0,0,1]
	v_mul_f32_e32 v26, v33, v38
	v_pk_fma_f32 v[38:39], v[32:33], v[38:39], v[26:27] op_sel:[0,1,0] op_sel_hi:[1,0,0]
	v_sub_f32_e32 v26, v34, v48
	v_sub_f32_e32 v30, v44, v46
	v_mov_b32_e32 v32, v36
	v_mov_b32_e32 v33, v38
	v_mov_b32_e32 v34, v40
	v_mov_b32_e32 v35, v42
.LBB0_583:
	v_cvt_pk_bf16_f32 v36, v30, v31
	v_cvt_pk_bf16_f32 v37, v34, v35
	v_cvt_pk_bf16_f32 v38, v26, v27
	v_lshl_add_u64 v[26:27], v[126:127], 0, v[146:147]
	v_add_co_u32_e32 v30, vcc, s60, v26
	v_cvt_pk_bf16_f32 v39, v32, v33
	s_nop 1
	v_addc_co_u32_e32 v31, vcc, 0, v27, vcc
	global_store_dwordx4 v[30:31], v[36:39], off nt
	ds_read_b128 v[30:33], v134 offset:5136
	s_waitcnt lgkmcnt(0)
	v_mov_b32_e32 v34, v31
	v_mov_b32_e32 v35, v32
	v_mov_b32_e32 v31, v33
	v_pk_add_f32 v[30:31], v[34:35], v[30:31]
	s_nop 0
	v_add_f32_e32 v30, v30, v31
	v_fmamk_f32 v30, v30, 0x3c000000, v192
	v_cmp_gt_f32_e32 vcc, s23, v30
	v_mul_f32_e32 v31, 0x4f800000, v30
	s_nop 0
	v_cndmask_b32_e32 v30, v30, v31, vcc
	v_sqrt_f32_e32 v31, v30
	s_nop 0
	v_add_u32_e32 v32, -1, v31
	v_fma_f32 v33, -v32, v31, v30
	v_cmp_ge_f32_e64 s[16:17], 0, v33
	v_add_u32_e32 v33, 1, v31
	s_nop 0
	v_cndmask_b32_e64 v32, v31, v32, s[16:17]
	v_fma_f32 v31, -v33, v31, v30
	v_cmp_lt_f32_e64 s[16:17], 0, v31
	s_nop 1
	v_cndmask_b32_e64 v31, v32, v33, s[16:17]
	v_mul_f32_e32 v32, 0x37800000, v31
	v_cndmask_b32_e32 v31, v31, v32, vcc
	v_cmp_class_f32_e32 vcc, v30, v193
	s_nop 1
	v_cndmask_b32_e32 v30, v31, v30, vcc
	v_div_scale_f32 v31, s[16:17], v30, v30, 1.0
	v_rcp_f32_e32 v32, v31
	s_nop 0
	v_fma_f32 v33, -v31, v32, 1.0
	v_fmac_f32_e32 v32, v33, v32
	v_div_scale_f32 v33, vcc, 1.0, v30, 1.0
	v_mul_f32_e32 v34, v33, v32
	v_fma_f32 v35, -v31, v34, v33
	v_fmac_f32_e32 v34, v35, v32
	v_fma_f32 v31, -v31, v34, v33
	v_div_fmas_f32 v31, v31, v32, v34
	v_div_fixup_f32 v30, v31, v30, 1.0
	v_pk_mul_f32 v[22:23], v[22:23], v[30:31] op_sel_hi:[1,0]
	v_pk_mul_f32 v[24:25], v[24:25], v[30:31] op_sel_hi:[1,0]
	v_pk_mul_f32 v[18:19], v[18:19], v[30:31] op_sel_hi:[1,0]
	v_pk_mul_f32 v[20:21], v[20:21], v[30:31] op_sel_hi:[1,0]
	v_pk_mul_f32 v[24:25], v[130:131], v[24:25]
	v_pk_mul_f32 v[22:23], v[124:125], v[22:23]
	v_pk_mul_f32 v[20:21], v[132:133], v[20:21]
	v_pk_mul_f32 v[18:19], v[122:123], v[18:19]
	s_and_b64 vcc, exec, s[14:15]
	s_cbranch_vccnz .LBB0_585
	global_load_dwordx4 v[30:33], v[28:29], off offset:16
	global_load_dwordx4 v[34:37], v[28:29], off
	s_waitcnt vmcnt(1)
	v_pk_mul_f32 v[40:41], v[18:19], v[30:31] op_sel:[1,1] op_sel_hi:[1,0]
	s_waitcnt vmcnt(0)
	v_pk_mul_f32 v[38:39], v[22:23], v[34:35] op_sel:[1,1] op_sel_hi:[1,0]
	v_pk_mul_f32 v[28:29], v[22:23], v[34:35]
	v_pk_fma_f32 v[22:23], v[22:23], v[34:35], v[38:39] op_sel_hi:[0,1,1]
	v_mul_f32_e32 v22, v25, v37
	v_pk_fma_f32 v[34:35], v[24:25], v[36:37], v[22:23] op_sel_hi:[1,1,0] neg_lo:[0,0,1] neg_hi:[0,0,1]
	v_mul_f32_e32 v22, v25, v36
	v_pk_fma_f32 v[36:37], v[24:25], v[36:37], v[22:23] op_sel:[0,1,0] op_sel_hi:[1,0,0]
	v_pk_mul_f32 v[24:25], v[18:19], v[30:31]
	v_pk_fma_f32 v[18:19], v[18:19], v[30:31], v[40:41] op_sel_hi:[0,1,1]
	v_mul_f32_e32 v18, v21, v33
	v_pk_fma_f32 v[30:31], v[20:21], v[32:33], v[18:19] op_sel_hi:[1,1,0] neg_lo:[0,0,1] neg_hi:[0,0,1]
	v_mul_f32_e32 v18, v21, v32
	v_pk_fma_f32 v[32:33], v[20:21], v[32:33], v[18:19] op_sel:[0,1,0] op_sel_hi:[1,0,0]
	v_sub_f32_e32 v18, v24, v40
	v_sub_f32_e32 v22, v28, v38
	v_mov_b32_e32 v20, v30
	v_mov_b32_e32 v21, v32
	v_mov_b32_e32 v24, v34
	v_mov_b32_e32 v25, v36
.LBB0_585:
	v_cvt_pk_bf16_f32 v22, v22, v23
	v_cvt_pk_bf16_f32 v23, v24, v25
	v_cvt_pk_bf16_f32 v24, v18, v19
	v_cvt_pk_bf16_f32 v25, v20, v21
	ds_read_b128 v[18:21], v134 offset:5632
	v_mov_b32_e32 v130, v135
	v_mov_b32_e32 v132, v137
	s_waitcnt lgkmcnt(0)
	v_mov_b32_e32 v28, v19
	v_mov_b32_e32 v29, v20
	v_mov_b32_e32 v19, v21
	v_pk_add_f32 v[18:19], v[28:29], v[18:19]
	s_nop 0
	v_add_f32_e32 v18, v18, v19
	v_fmamk_f32 v18, v18, 0x3c000000, v192
	v_mul_f32_e32 v19, 0x4f800000, v18
	v_cmp_gt_f32_e32 vcc, s23, v18
	s_nop 1
	v_cndmask_b32_e32 v20, v18, v19, vcc
	v_sqrt_f32_e32 v21, v20
	v_lshl_add_u64 v[18:19], v[26:27], 0, s[72:73]
	global_store_dwordx4 v[18:19], v[22:25], off offset:256 nt
	v_mov_b32_e32 v18, s18
	v_add_u32_e32 v19, -1, v21
	v_fma_f32 v22, -v19, v21, v20
	v_cmp_ge_f32_e64 s[16:17], 0, v22
	v_add_u32_e32 v22, 1, v21
	v_cndmask_b32_e64 v18, v176, v18, s[4:5]
	v_cndmask_b32_e64 v19, v21, v19, s[16:17]
	v_fma_f32 v21, -v22, v21, v20
	v_cmp_lt_f32_e64 s[16:17], 0, v21
	s_nop 1
	v_cndmask_b32_e64 v19, v19, v22, s[16:17]
	v_mul_f32_e32 v21, 0x37800000, v19
	v_cndmask_b32_e32 v19, v19, v21, vcc
	v_cmp_class_f32_e32 vcc, v20, v193
	s_nop 1
	v_cndmask_b32_e32 v19, v19, v20, vcc
	v_div_scale_f32 v22, s[16:17], v19, v19, 1.0
	v_rcp_f32_e32 v23, v22
	v_lshl_or_b32 v20, v18, 6, v178
	v_ashrrev_i32_e32 v21, 31, v20
	v_fma_f32 v18, -v22, v23, 1.0
	v_fmac_f32_e32 v23, v18, v23
	v_div_scale_f32 v18, vcc, 1.0, v19, 1.0
	v_mul_f32_e32 v24, v18, v23
	v_fma_f32 v25, -v22, v24, v18
	v_fmac_f32_e32 v24, v25, v23
	v_fma_f32 v18, -v22, v24, v18
	v_div_fmas_f32 v18, v18, v23, v24
	v_div_fixup_f32 v22, v18, v19, 1.0
	v_pk_mul_f32 v[14:15], v[14:15], v[22:23] op_sel_hi:[1,0]
	v_pk_mul_f32 v[16:17], v[16:17], v[22:23] op_sel_hi:[1,0]
	v_pk_mul_f32 v[10:11], v[10:11], v[22:23] op_sel_hi:[1,0]
	v_pk_mul_f32 v[12:13], v[12:13], v[22:23] op_sel_hi:[1,0]
	v_pk_mul_f32 v[18:19], v[130:131], v[16:17]
	v_pk_mul_f32 v[14:15], v[124:125], v[14:15]
	v_pk_mul_f32 v[16:17], v[132:133], v[12:13]
	v_pk_mul_f32 v[12:13], v[122:123], v[10:11]
	s_and_b64 vcc, exec, s[14:15]
	v_lshl_add_u64 v[10:11], v[20:21], 2, s[42:43]
	s_cbranch_vccnz .LBB0_587
	global_load_dwordx4 v[20:23], v[10:11], off offset:16
	global_load_dwordx4 v[24:27], v[10:11], off
	s_waitcnt vmcnt(1)
	v_pk_mul_f32 v[32:33], v[12:13], v[20:21] op_sel:[1,1] op_sel_hi:[1,0]
	s_waitcnt vmcnt(0)
	v_pk_mul_f32 v[30:31], v[14:15], v[24:25] op_sel:[1,1] op_sel_hi:[1,0]
	v_pk_mul_f32 v[28:29], v[14:15], v[24:25]
	v_pk_fma_f32 v[14:15], v[14:15], v[24:25], v[30:31] op_sel_hi:[0,1,1]
	v_mul_f32_e32 v14, v19, v27
	v_pk_fma_f32 v[24:25], v[18:19], v[26:27], v[14:15] op_sel_hi:[1,1,0] neg_lo:[0,0,1] neg_hi:[0,0,1]
	v_mul_f32_e32 v14, v19, v26
	v_pk_fma_f32 v[26:27], v[18:19], v[26:27], v[14:15] op_sel:[0,1,0] op_sel_hi:[1,0,0]
	v_pk_mul_f32 v[18:19], v[12:13], v[20:21]
	v_pk_fma_f32 v[12:13], v[12:13], v[20:21], v[32:33] op_sel_hi:[0,1,1]
	v_mul_f32_e32 v12, v17, v23
	v_pk_fma_f32 v[20:21], v[16:17], v[22:23], v[12:13] op_sel_hi:[1,1,0] neg_lo:[0,0,1] neg_hi:[0,0,1]
	v_mul_f32_e32 v12, v17, v22
	v_pk_fma_f32 v[22:23], v[16:17], v[22:23], v[12:13] op_sel:[0,1,0] op_sel_hi:[1,0,0]
	v_sub_f32_e32 v12, v18, v32
	v_sub_f32_e32 v14, v28, v30
	v_mov_b32_e32 v16, v20
	v_mov_b32_e32 v17, v22
	v_mov_b32_e32 v18, v24
	v_mov_b32_e32 v19, v26
.LBB0_587:
	v_cvt_pk_bf16_f32 v20, v14, v15
	v_cvt_pk_bf16_f32 v21, v18, v19
	v_cvt_pk_bf16_f32 v22, v12, v13
	v_cvt_pk_bf16_f32 v23, v16, v17
	ds_read_b128 v[12:15], v134 offset:5648
	s_waitcnt lgkmcnt(0)
	v_mov_b32_e32 v16, v13
	v_mov_b32_e32 v17, v14
	v_mov_b32_e32 v13, v15
	v_pk_add_f32 v[12:13], v[16:17], v[12:13]
	s_nop 0
	v_add_f32_e32 v12, v12, v13
	v_fmamk_f32 v12, v12, 0x3c000000, v192
	v_mul_f32_e32 v13, 0x4f800000, v12
	v_cmp_gt_f32_e64 s[16:17], s23, v12
	s_nop 1
	v_cndmask_b32_e64 v15, v12, v13, s[16:17]
	v_sqrt_f32_e32 v16, v15
	v_lshl_add_u64 v[12:13], v[126:127], 0, v[146:147]
	v_add_co_u32_e32 v14, vcc, s61, v12
	v_add_u32_e32 v17, -1, v16
	v_fma_f32 v18, -v17, v16, v15
	v_cmp_ge_f32_e64 s[18:19], 0, v18
	v_add_u32_e32 v18, 1, v16
	s_nop 0
	v_cndmask_b32_e64 v17, v16, v17, s[18:19]
	v_fma_f32 v16, -v18, v16, v15
	v_cmp_lt_f32_e64 s[18:19], 0, v16
	s_nop 1
	v_cndmask_b32_e64 v16, v17, v18, s[18:19]
	v_mul_f32_e32 v17, 0x37800000, v16
	v_cndmask_b32_e64 v16, v16, v17, s[16:17]
	v_cmp_class_f32_e64 s[16:17], v15, v193
	s_nop 1
	v_cndmask_b32_e64 v16, v16, v15, s[16:17]
	v_div_scale_f32 v17, s[16:17], v16, v16, 1.0
	v_rcp_f32_e32 v18, v17
	v_addc_co_u32_e32 v15, vcc, 0, v13, vcc
	global_store_dwordx4 v[14:15], v[20:23], off nt
	v_fma_f32 v14, -v17, v18, 1.0
	v_fmac_f32_e32 v18, v14, v18
	v_div_scale_f32 v14, vcc, 1.0, v16, 1.0
	v_mul_f32_e32 v15, v14, v18
	v_fma_f32 v19, -v17, v15, v14
	v_fmac_f32_e32 v15, v19, v18
	v_fma_f32 v14, -v17, v15, v14
	v_div_fmas_f32 v14, v14, v18, v15
	v_div_fixup_f32 v14, v14, v16, 1.0
	v_pk_mul_f32 v[6:7], v[6:7], v[14:15] op_sel_hi:[1,0]
	v_pk_mul_f32 v[8:9], v[8:9], v[14:15] op_sel_hi:[1,0]
	v_pk_mul_f32 v[2:3], v[2:3], v[14:15] op_sel_hi:[1,0]
	v_pk_mul_f32 v[4:5], v[4:5], v[14:15] op_sel_hi:[1,0]
	v_pk_mul_f32 v[8:9], v[130:131], v[8:9]
	v_pk_mul_f32 v[6:7], v[124:125], v[6:7]
	v_pk_mul_f32 v[4:5], v[132:133], v[4:5]
	s_and_b64 vcc, exec, s[14:15]
	v_pk_mul_f32 v[2:3], v[122:123], v[2:3]
	s_cbranch_vccnz .LBB0_589
	global_load_dwordx4 v[14:17], v[10:11], off offset:16
	global_load_dwordx4 v[18:21], v[10:11], off
	s_waitcnt vmcnt(1)
	v_pk_mul_f32 v[24:25], v[2:3], v[14:15] op_sel:[1,1] op_sel_hi:[1,0]
	s_waitcnt vmcnt(0)
	v_pk_mul_f32 v[22:23], v[6:7], v[18:19] op_sel:[1,1] op_sel_hi:[1,0]
	v_pk_mul_f32 v[10:11], v[6:7], v[18:19]
	v_pk_fma_f32 v[6:7], v[6:7], v[18:19], v[22:23] op_sel_hi:[0,1,1]
	v_mul_f32_e32 v6, v9, v21
	v_pk_fma_f32 v[18:19], v[8:9], v[20:21], v[6:7] op_sel_hi:[1,1,0] neg_lo:[0,0,1] neg_hi:[0,0,1]
	v_mul_f32_e32 v6, v9, v20
	v_pk_fma_f32 v[20:21], v[8:9], v[20:21], v[6:7] op_sel:[0,1,0] op_sel_hi:[1,0,0]
	v_pk_mul_f32 v[8:9], v[2:3], v[14:15]
	v_pk_fma_f32 v[2:3], v[2:3], v[14:15], v[24:25] op_sel_hi:[0,1,1]
	v_mul_f32_e32 v2, v5, v17
	v_pk_fma_f32 v[14:15], v[4:5], v[16:17], v[2:3] op_sel_hi:[1,1,0] neg_lo:[0,0,1] neg_hi:[0,0,1]
	v_mul_f32_e32 v2, v5, v16
	v_pk_fma_f32 v[16:17], v[4:5], v[16:17], v[2:3] op_sel:[0,1,0] op_sel_hi:[1,0,0]
	v_sub_f32_e32 v2, v8, v24
	v_sub_f32_e32 v6, v10, v22
	v_mov_b32_e32 v4, v14
	v_mov_b32_e32 v5, v16
	v_mov_b32_e32 v8, v18
	v_mov_b32_e32 v9, v20
.LBB0_589:
	v_lshl_add_u64 v[10:11], v[12:13], 0, s[74:75]
	v_cvt_pk_bf16_f32 v6, v6, v7
	v_cvt_pk_bf16_f32 v7, v8, v9
	v_cvt_pk_bf16_f32 v8, v2, v3
	v_cvt_pk_bf16_f32 v9, v4, v5
	global_store_dwordx4 v[10:11], v[6:9], off offset:256 nt
	s_andn2_b64 vcc, exec, s[12:13]
	s_mov_b64 s[12:13], -1
	s_cbranch_vccnz .LBB0_462

.LBB0_1134:
	s_andn2_b64 vcc, exec, s[20:21]
	s_cbranch_vccnz .LBB0_1149
	s_add_i32 s6, s63, -12
	s_cmp_gt_u32 s6, 11
	s_mov_b64 s[34:35], -1
	s_cbranch_scc0 .LBB0_1147
	s_ashr_i32 s31, s30, 31
	s_lshl_b64 s[34:35], s[30:31], 8
	v_lshl_add_u64 v[156:157], s[34:35], 0, v[140:141]
	s_cmp_gt_i32 s63, 27
	s_mov_b64 s[34:35], -1
	s_cbranch_scc0 .LBB0_1144
	s_cmp_gt_u32 s63, 43
	s_cbranch_scc0 .LBB0_1141
	s_andn2_b64 vcc, exec, s[18:19]
	s_cbranch_vccnz .LBB0_1140
	v_lshlrev_b64 v[158:159], 7, v[156:157]
	v_lshl_add_u64 v[158:159], s[12:13], 0, v[158:159]
	v_mov_b32_e32 v153, v139
	v_lshl_add_u64 v[158:159], v[158:159], 0, v[152:153]
	s_mov_b64 s[34:35], 0x1000
	v_add_co_u32_e32 v168, vcc, 0x1000, v158
	v_lshl_add_u64 v[166:167], v[158:159], 0, s[34:35]
	s_nop 0
	v_addc_co_u32_e32 v169, vcc, 0, v159, vcc
	s_mov_b64 s[34:35], 0x1800
	s_movk_i32 s6, 0x4000
	global_store_dwordx4 v[158:159], v[126:129], off nt
	global_store_dwordx4 v[158:159], v[122:125], off offset:16 nt
	global_store_dwordx4 v[158:159], v[118:121], off offset:2048 nt
	global_store_dwordx4 v[158:159], v[114:117], off offset:2064 nt
	global_store_dwordx4 v[168:169], v[110:113], off nt
	global_store_dwordx4 v[166:167], v[106:109], off offset:16 nt
	v_lshl_add_u64 v[166:167], v[158:159], 0, s[34:35]
	global_store_dwordx4 v[168:169], v[102:105], off offset:2048 nt
	global_store_dwordx4 v[166:167], v[98:101], off offset:16 nt
	s_mov_b64 s[34:35], 0x4000
	v_add_co_u32_e32 v168, vcc, s6, v158
	v_lshl_add_u64 v[166:167], v[158:159], 0, s[34:35]
	s_nop 0
	v_addc_co_u32_e32 v169, vcc, 0, v159, vcc
	s_mov_b64 s[34:35], 0x4800
	global_store_dwordx4 v[168:169], v[62:65], off nt
	global_store_dwordx4 v[166:167], v[58:61], off offset:16 nt
	v_lshl_add_u64 v[166:167], v[158:159], 0, s[34:35]
	global_store_dwordx4 v[168:169], v[54:57], off offset:2048 nt
	global_store_dwordx4 v[166:167], v[50:53], off offset:16 nt
	s_mov_b64 s[34:35], 0x5000
	v_add_co_u32_e32 v168, vcc, 0x5000, v158
	v_lshl_add_u64 v[166:167], v[158:159], 0, s[34:35]
	s_nop 0
	v_addc_co_u32_e32 v169, vcc, 0, v159, vcc
	s_mov_b64 s[34:35], 0x5800
	global_store_dwordx4 v[168:169], v[46:49], off nt
	global_store_dwordx4 v[166:167], v[42:45], off offset:16 nt
	v_lshl_add_u64 v[158:159], v[158:159], 0, s[34:35]
	global_store_dwordx4 v[168:169], v[38:41], off offset:2048 nt
	global_store_dwordx4 v[158:159], v[34:37], off offset:16 nt

.LBB0_1141:
	s_andn2_b64 vcc, exec, s[34:35]
	s_cbranch_vccnz .LBB0_1143
	v_mul_f32_e32 v166, 0xbfb8aa3b, v123
	v_exp_f32_e32 v166, v166
	v_mul_f32_e32 v167, 0xbfb8aa3b, v128
	v_mul_f32_e32 v168, 0xbfb8aa3b, v124
	v_exp_f32_e32 v167, v167
	v_add_f32_e32 v166, 1.0, v166
	v_rcp_f32_e32 v166, v166
	v_exp_f32_e32 v168, v168
	v_mul_f32_e32 v170, 0xbfb8aa3b, v125
	v_mul_f32_e32 v153, 0xbfb8aa3b, v126
	v_mul_f32_e32 v169, v123, v166
	v_add_f32_e32 v166, 1.0, v167
	v_add_f32_e32 v167, 1.0, v168
	v_mul_f32_e32 v168, 0xbfb8aa3b, v129
	v_mul_f32_e32 v155, 0xbfb8aa3b, v122
	v_mul_f32_e32 v165, 0xbfb8aa3b, v127
	v_exp_f32_e32 v168, v168
	v_exp_f32_e32 v170, v170
	v_exp_f32_e32 v153, v153
	v_exp_f32_e32 v155, v155
	v_exp_f32_e32 v165, v165
	v_add_f32_e32 v168, 1.0, v168
	v_add_f32_e32 v170, 1.0, v170
	v_add_f32_e32 v153, 1.0, v153
	v_add_f32_e32 v155, 1.0, v155
	v_add_f32_e32 v165, 1.0, v165
	v_rcp_f32_e32 v166, v166
	v_rcp_f32_e32 v167, v167
	v_rcp_f32_e32 v168, v168
	v_rcp_f32_e32 v170, v170
	v_rcp_f32_e32 v153, v153
	v_rcp_f32_e32 v155, v155
	v_rcp_f32_e32 v165, v165
	v_lshlrev_b64 v[158:159], 13, v[156:157]
	v_mul_f32_e32 v171, v128, v166
	v_mul_f32_e32 v172, v124, v167
	v_mul_f32_e32 v167, v129, v168
	v_mul_f32_e32 v170, v125, v170
	v_lshl_add_u64 v[158:159], s[10:11], 0, v[158:159]
	s_lshl_b32 s6, s63, 9
	v_mul_f32_e32 v153, v126, v153
	v_mul_f32_e32 v155, v122, v155
	v_mul_f32_e32 v165, v127, v165
	v_cvt_pk_bf16_f32 v166, v153, v165
	v_cvt_pk_bf16_f32 v167, v171, v167
	v_cvt_pk_bf16_f32 v168, v155, v169
	v_cvt_pk_bf16_f32 v169, v172, v170
	v_lshl_add_u64 v[158:159], v[158:159], 0, s[6:7]
	v_lshlrev_b32_e32 v170, 1, v142
	v_mov_b32_e32 v171, v139
	v_lshl_add_u64 v[158:159], v[158:159], 0, v[170:171]
	s_movk_i32 s6, 0xd000
	v_add_co_u32_e32 v170, vcc, s6, v158
	v_mul_f32_e32 v153, 0xbfb8aa3b, v94
	s_nop 0
	v_addc_co_u32_e32 v171, vcc, -1, v159, vcc
	global_store_dwordx4 v[170:171], v[166:169], off offset:-2048 nt
	v_mul_f32_e32 v165, 0xbfb8aa3b, v95
	v_exp_f32_e32 v153, v153
	v_mul_f32_e32 v166, 0xbfb8aa3b, v91
	v_exp_f32_e32 v166, v166
	v_mul_f32_e32 v167, 0xbfb8aa3b, v96
	v_mul_f32_e32 v168, 0xbfb8aa3b, v92
	v_exp_f32_e32 v167, v167
	v_add_f32_e32 v166, 1.0, v166
	v_rcp_f32_e32 v166, v166
	v_exp_f32_e32 v168, v168
	v_mul_f32_e32 v155, 0xbfb8aa3b, v90
	v_exp_f32_e32 v165, v165
	v_mul_f32_e32 v169, v91, v166
	v_add_f32_e32 v166, 1.0, v167
	v_add_f32_e32 v167, 1.0, v168
	v_mul_f32_e32 v168, 0xbfb8aa3b, v97
	v_exp_f32_e32 v168, v168
	v_mul_f32_e32 v172, 0xbfb8aa3b, v93
	v_exp_f32_e32 v155, v155
	v_exp_f32_e32 v172, v172
	v_add_f32_e32 v153, 1.0, v153
	v_add_f32_e32 v165, 1.0, v165
	v_add_f32_e32 v168, 1.0, v168
	v_rcp_f32_e32 v153, v153
	v_add_f32_e32 v155, 1.0, v155
	v_rcp_f32_e32 v165, v165
	v_rcp_f32_e32 v166, v166
	v_rcp_f32_e32 v167, v167
	v_rcp_f32_e32 v168, v168
	v_add_f32_e32 v172, 1.0, v172
	v_rcp_f32_e32 v155, v155
	v_rcp_f32_e32 v172, v172
	v_mul_f32_e32 v153, v94, v153
	v_mul_f32_e32 v165, v95, v165
	v_mul_f32_e32 v173, v96, v166
	v_mul_f32_e32 v174, v92, v167
	v_mul_f32_e32 v167, v97, v168
	v_cvt_pk_bf16_f32 v166, v153, v165
	v_mul_f32_e32 v155, v90, v155
	v_mul_f32_e32 v172, v93, v172
	v_cvt_pk_bf16_f32 v167, v173, v167
	v_cvt_pk_bf16_f32 v168, v155, v169
	v_cvt_pk_bf16_f32 v169, v174, v172
	global_store_dwordx4 v[170:171], v[166:169], off offset:-1792 nt
	v_mul_f32_e32 v170, 0xbfb8aa3b, v117
	v_mul_f32_e32 v153, 0xbfb8aa3b, v118
	v_mul_f32_e32 v166, 0xbfb8aa3b, v115
	v_exp_f32_e32 v166, v166
	v_mul_f32_e32 v167, 0xbfb8aa3b, v120
	v_mul_f32_e32 v168, 0xbfb8aa3b, v116
	v_exp_f32_e32 v167, v167
	v_add_f32_e32 v166, 1.0, v166
	v_rcp_f32_e32 v166, v166
	v_exp_f32_e32 v168, v168
	v_mul_f32_e32 v155, 0xbfb8aa3b, v114
	v_mul_f32_e32 v165, 0xbfb8aa3b, v119
	v_mul_f32_e32 v169, v115, v166
	v_add_f32_e32 v166, 1.0, v167
	v_add_f32_e32 v167, 1.0, v168
	v_mul_f32_e32 v168, 0xbfb8aa3b, v121
	v_exp_f32_e32 v168, v168
	v_exp_f32_e32 v170, v170
	v_exp_f32_e32 v153, v153
	v_exp_f32_e32 v155, v155
	v_exp_f32_e32 v165, v165
	v_add_f32_e32 v168, 1.0, v168
	v_add_f32_e32 v170, 1.0, v170
	v_add_f32_e32 v153, 1.0, v153
	v_add_f32_e32 v155, 1.0, v155
	v_add_f32_e32 v165, 1.0, v165
	v_rcp_f32_e32 v167, v167
	v_rcp_f32_e32 v168, v168
	v_rcp_f32_e32 v170, v170
	v_rcp_f32_e32 v153, v153
	v_rcp_f32_e32 v155, v155
	v_rcp_f32_e32 v165, v165
	v_rcp_f32_e32 v166, v166
	v_mul_f32_e32 v172, v116, v167
	v_mul_f32_e32 v167, v121, v168
	v_mul_f32_e32 v170, v117, v170
	s_mov_b32 s6, 0x1c000
	v_mul_f32_e32 v153, v118, v153
	v_mul_f32_e32 v155, v114, v155
	v_mul_f32_e32 v165, v119, v165
	v_mul_f32_e32 v171, v120, v166
	v_cvt_pk_bf16_f32 v166, v153, v165
	v_cvt_pk_bf16_f32 v167, v171, v167
	v_cvt_pk_bf16_f32 v168, v155, v169
	v_cvt_pk_bf16_f32 v169, v172, v170
	v_add_co_u32_e32 v170, vcc, s6, v158
	v_mul_f32_e32 v153, 0xbfb8aa3b, v86
	s_nop 0
	v_addc_co_u32_e32 v171, vcc, 0, v159, vcc
	global_store_dwordx4 v[170:171], v[166:169], off offset:2048 nt
	v_mul_f32_e32 v165, 0xbfb8aa3b, v87
	v_exp_f32_e32 v153, v153
	v_mul_f32_e32 v166, 0xbfb8aa3b, v83
	v_exp_f32_e32 v166, v166
	v_mul_f32_e32 v167, 0xbfb8aa3b, v88
	v_mul_f32_e32 v168, 0xbfb8aa3b, v84
	v_exp_f32_e32 v167, v167
	v_add_f32_e32 v166, 1.0, v166
	v_rcp_f32_e32 v166, v166
	v_exp_f32_e32 v168, v168
	v_mul_f32_e32 v155, 0xbfb8aa3b, v82
	v_exp_f32_e32 v165, v165
	v_mul_f32_e32 v169, v83, v166
	v_add_f32_e32 v166, 1.0, v167
	v_add_f32_e32 v167, 1.0, v168
	v_mul_f32_e32 v168, 0xbfb8aa3b, v89
	v_exp_f32_e32 v168, v168
	v_mul_f32_e32 v172, 0xbfb8aa3b, v85
	v_exp_f32_e32 v155, v155
	v_exp_f32_e32 v172, v172
	v_add_f32_e32 v153, 1.0, v153
	v_add_f32_e32 v165, 1.0, v165
	v_add_f32_e32 v168, 1.0, v168
	v_rcp_f32_e32 v153, v153
	v_add_f32_e32 v155, 1.0, v155
	v_rcp_f32_e32 v165, v165
	v_rcp_f32_e32 v166, v166
	v_rcp_f32_e32 v167, v167
	v_rcp_f32_e32 v168, v168
	v_add_f32_e32 v172, 1.0, v172
	v_rcp_f32_e32 v155, v155
	v_rcp_f32_e32 v172, v172
	v_mul_f32_e32 v153, v86, v153
	v_mul_f32_e32 v165, v87, v165
	v_mul_f32_e32 v173, v88, v166
	v_mul_f32_e32 v174, v84, v167
	v_mul_f32_e32 v167, v89, v168
	v_cvt_pk_bf16_f32 v166, v153, v165
	v_mul_f32_e32 v155, v82, v155
	v_mul_f32_e32 v172, v85, v172
	v_cvt_pk_bf16_f32 v167, v173, v167
	v_cvt_pk_bf16_f32 v168, v155, v169
	v_cvt_pk_bf16_f32 v169, v174, v172
	global_store_dwordx4 v[170:171], v[166:169], off offset:2304 nt
	v_mul_f32_e32 v170, 0xbfb8aa3b, v109
	v_mul_f32_e32 v153, 0xbfb8aa3b, v110
	v_mul_f32_e32 v166, 0xbfb8aa3b, v107
	v_exp_f32_e32 v166, v166
	v_mul_f32_e32 v167, 0xbfb8aa3b, v112
	v_mul_f32_e32 v168, 0xbfb8aa3b, v108
	v_exp_f32_e32 v167, v167
	v_add_f32_e32 v166, 1.0, v166
	v_rcp_f32_e32 v166, v166
	v_exp_f32_e32 v168, v168
	v_mul_f32_e32 v155, 0xbfb8aa3b, v106
	v_mul_f32_e32 v165, 0xbfb8aa3b, v111
	v_mul_f32_e32 v169, v107, v166
	v_add_f32_e32 v166, 1.0, v167
	v_add_f32_e32 v167, 1.0, v168
	v_mul_f32_e32 v168, 0xbfb8aa3b, v113
	v_exp_f32_e32 v168, v168
	v_exp_f32_e32 v170, v170
	v_exp_f32_e32 v153, v153
	v_exp_f32_e32 v155, v155
	v_exp_f32_e32 v165, v165
	v_add_f32_e32 v168, 1.0, v168
	v_add_f32_e32 v170, 1.0, v170
	v_add_f32_e32 v153, 1.0, v153
	v_add_f32_e32 v155, 1.0, v155
	v_add_f32_e32 v165, 1.0, v165
	v_rcp_f32_e32 v167, v167
	v_rcp_f32_e32 v168, v168
	v_rcp_f32_e32 v170, v170
	v_rcp_f32_e32 v153, v153
	v_rcp_f32_e32 v155, v155
	v_rcp_f32_e32 v165, v165
	v_rcp_f32_e32 v166, v166
	v_mul_f32_e32 v172, v108, v167
	v_mul_f32_e32 v167, v113, v168
	v_mul_f32_e32 v170, v109, v170
	s_mov_b32 s6, 0x3c000
	v_mul_f32_e32 v153, v110, v153
	v_mul_f32_e32 v155, v106, v155
	v_mul_f32_e32 v165, v111, v165
	v_mul_f32_e32 v171, v112, v166
	v_cvt_pk_bf16_f32 v166, v153, v165
	v_cvt_pk_bf16_f32 v167, v171, v167
	v_cvt_pk_bf16_f32 v168, v155, v169
	v_cvt_pk_bf16_f32 v169, v172, v170
	v_add_co_u32_e32 v170, vcc, s6, v158
	v_mul_f32_e32 v153, 0xbfb8aa3b, v78
	s_nop 0
	v_addc_co_u32_e32 v171, vcc, 0, v159, vcc
	global_store_dwordx4 v[170:171], v[166:169], off offset:2048 nt
	v_mul_f32_e32 v165, 0xbfb8aa3b, v79
	v_exp_f32_e32 v153, v153
	v_mul_f32_e32 v166, 0xbfb8aa3b, v75
	v_exp_f32_e32 v166, v166
	v_mul_f32_e32 v167, 0xbfb8aa3b, v80
	v_mul_f32_e32 v168, 0xbfb8aa3b, v76
	v_exp_f32_e32 v167, v167
	v_add_f32_e32 v166, 1.0, v166
	v_rcp_f32_e32 v166, v166
	v_exp_f32_e32 v168, v168
	v_mul_f32_e32 v155, 0xbfb8aa3b, v74
	v_exp_f32_e32 v165, v165
	v_mul_f32_e32 v169, v75, v166
	v_add_f32_e32 v166, 1.0, v167
	v_add_f32_e32 v167, 1.0, v168
	v_mul_f32_e32 v168, 0xbfb8aa3b, v81
	v_exp_f32_e32 v168, v168
	v_mul_f32_e32 v172, 0xbfb8aa3b, v77
	v_exp_f32_e32 v155, v155
	v_exp_f32_e32 v172, v172
	v_add_f32_e32 v153, 1.0, v153
	v_add_f32_e32 v165, 1.0, v165
	v_add_f32_e32 v168, 1.0, v168
	v_rcp_f32_e32 v153, v153
	v_add_f32_e32 v155, 1.0, v155
	v_rcp_f32_e32 v165, v165
	v_rcp_f32_e32 v166, v166
	v_rcp_f32_e32 v167, v167
	v_rcp_f32_e32 v168, v168
	v_add_f32_e32 v172, 1.0, v172
	v_rcp_f32_e32 v155, v155
	v_rcp_f32_e32 v172, v172
	v_mul_f32_e32 v153, v78, v153
	v_mul_f32_e32 v165, v79, v165
	v_mul_f32_e32 v173, v80, v166
	v_mul_f32_e32 v174, v76, v167
	v_mul_f32_e32 v167, v81, v168
	v_cvt_pk_bf16_f32 v166, v153, v165
	v_mul_f32_e32 v155, v74, v155
	v_mul_f32_e32 v172, v77, v172
	v_cvt_pk_bf16_f32 v167, v173, v167
	v_cvt_pk_bf16_f32 v168, v155, v169
	v_cvt_pk_bf16_f32 v169, v174, v172
	global_store_dwordx4 v[170:171], v[166:169], off offset:2304 nt
	v_mul_f32_e32 v170, 0xbfb8aa3b, v101
	v_mul_f32_e32 v153, 0xbfb8aa3b, v102
	v_mul_f32_e32 v166, 0xbfb8aa3b, v99
	v_exp_f32_e32 v166, v166
	v_mul_f32_e32 v167, 0xbfb8aa3b, v104
	v_mul_f32_e32 v168, 0xbfb8aa3b, v100
	v_exp_f32_e32 v167, v167
	v_add_f32_e32 v166, 1.0, v166
	v_rcp_f32_e32 v166, v166
	v_exp_f32_e32 v168, v168
	v_mul_f32_e32 v155, 0xbfb8aa3b, v98
	v_mul_f32_e32 v165, 0xbfb8aa3b, v103
	v_mul_f32_e32 v169, v99, v166
	v_add_f32_e32 v166, 1.0, v167
	v_add_f32_e32 v167, 1.0, v168
	v_mul_f32_e32 v168, 0xbfb8aa3b, v105
	v_exp_f32_e32 v168, v168
	v_exp_f32_e32 v170, v170
	v_exp_f32_e32 v153, v153
	v_exp_f32_e32 v155, v155
	v_exp_f32_e32 v165, v165
	v_add_f32_e32 v168, 1.0, v168
	v_add_f32_e32 v170, 1.0, v170
	v_add_f32_e32 v153, 1.0, v153
	v_add_f32_e32 v155, 1.0, v155
	v_add_f32_e32 v165, 1.0, v165
	v_rcp_f32_e32 v167, v167
	v_rcp_f32_e32 v168, v168
	v_rcp_f32_e32 v170, v170
	v_rcp_f32_e32 v153, v153
	v_rcp_f32_e32 v155, v155
	v_rcp_f32_e32 v165, v165
	v_rcp_f32_e32 v166, v166
	v_mul_f32_e32 v172, v100, v167
	v_mul_f32_e32 v167, v105, v168
	v_mul_f32_e32 v170, v101, v170
	s_mov_b32 s6, 0x5c000
	v_mul_f32_e32 v153, v102, v153
	v_mul_f32_e32 v155, v98, v155
	v_mul_f32_e32 v165, v103, v165
	v_mul_f32_e32 v171, v104, v166
	v_cvt_pk_bf16_f32 v166, v153, v165
	v_cvt_pk_bf16_f32 v167, v171, v167
	v_cvt_pk_bf16_f32 v168, v155, v169
	v_cvt_pk_bf16_f32 v169, v172, v170
	v_add_co_u32_e32 v170, vcc, s6, v158
	v_mul_f32_e32 v153, 0xbfb8aa3b, v70
	s_nop 0
	v_addc_co_u32_e32 v171, vcc, 0, v159, vcc
	global_store_dwordx4 v[170:171], v[166:169], off offset:2048 nt
	v_mul_f32_e32 v165, 0xbfb8aa3b, v71
	v_exp_f32_e32 v153, v153
	v_mul_f32_e32 v166, 0xbfb8aa3b, v67
	v_exp_f32_e32 v166, v166
	v_mul_f32_e32 v167, 0xbfb8aa3b, v72
	v_mul_f32_e32 v168, 0xbfb8aa3b, v68
	v_exp_f32_e32 v167, v167
	v_add_f32_e32 v166, 1.0, v166
	v_rcp_f32_e32 v166, v166
	v_exp_f32_e32 v168, v168
	v_mul_f32_e32 v155, 0xbfb8aa3b, v66
	v_exp_f32_e32 v165, v165
	v_mul_f32_e32 v169, v67, v166
	v_add_f32_e32 v166, 1.0, v167
	v_add_f32_e32 v167, 1.0, v168
	v_mul_f32_e32 v168, 0xbfb8aa3b, v73
	v_exp_f32_e32 v168, v168
	v_mul_f32_e32 v172, 0xbfb8aa3b, v69
	v_exp_f32_e32 v155, v155
	v_exp_f32_e32 v172, v172
	v_add_f32_e32 v153, 1.0, v153
	v_add_f32_e32 v165, 1.0, v165
	v_add_f32_e32 v168, 1.0, v168
	v_rcp_f32_e32 v153, v153
	v_add_f32_e32 v155, 1.0, v155
	v_rcp_f32_e32 v165, v165
	v_rcp_f32_e32 v166, v166
	v_rcp_f32_e32 v167, v167
	v_rcp_f32_e32 v168, v168
	v_add_f32_e32 v172, 1.0, v172
	v_rcp_f32_e32 v155, v155
	v_rcp_f32_e32 v172, v172
	v_mul_f32_e32 v153, v70, v153
	v_mul_f32_e32 v165, v71, v165
	v_mul_f32_e32 v173, v72, v166
	v_mul_f32_e32 v174, v68, v167
	v_mul_f32_e32 v167, v73, v168
	v_cvt_pk_bf16_f32 v166, v153, v165
	v_mul_f32_e32 v155, v66, v155
	v_mul_f32_e32 v172, v69, v172
	v_cvt_pk_bf16_f32 v167, v173, v167
	v_cvt_pk_bf16_f32 v168, v155, v169
	v_cvt_pk_bf16_f32 v169, v174, v172
	global_store_dwordx4 v[170:171], v[166:169], off offset:2304 nt
	v_mul_f32_e32 v170, 0xbfb8aa3b, v61
	v_mul_f32_e32 v153, 0xbfb8aa3b, v62
	v_mul_f32_e32 v166, 0xbfb8aa3b, v59
	v_exp_f32_e32 v166, v166
	v_mul_f32_e32 v167, 0xbfb8aa3b, v64
	v_mul_f32_e32 v168, 0xbfb8aa3b, v60
	v_exp_f32_e32 v167, v167
	v_add_f32_e32 v166, 1.0, v166
	v_rcp_f32_e32 v166, v166
	v_exp_f32_e32 v168, v168
	v_mul_f32_e32 v155, 0xbfb8aa3b, v58
	v_mul_f32_e32 v165, 0xbfb8aa3b, v63
	v_mul_f32_e32 v169, v59, v166
	v_add_f32_e32 v166, 1.0, v167
	v_add_f32_e32 v167, 1.0, v168
	v_mul_f32_e32 v168, 0xbfb8aa3b, v65
	v_exp_f32_e32 v168, v168
	v_exp_f32_e32 v170, v170
	v_exp_f32_e32 v153, v153
	v_exp_f32_e32 v155, v155
	v_exp_f32_e32 v165, v165
	v_add_f32_e32 v168, 1.0, v168
	v_add_f32_e32 v170, 1.0, v170
	v_add_f32_e32 v153, 1.0, v153
	v_add_f32_e32 v155, 1.0, v155
	v_add_f32_e32 v165, 1.0, v165
	v_rcp_f32_e32 v167, v167
	v_rcp_f32_e32 v168, v168
	v_rcp_f32_e32 v170, v170
	v_rcp_f32_e32 v153, v153
	v_rcp_f32_e32 v155, v155
	v_rcp_f32_e32 v165, v165
	v_rcp_f32_e32 v166, v166
	v_mul_f32_e32 v172, v60, v167
	v_mul_f32_e32 v167, v65, v168
	v_mul_f32_e32 v170, v61, v170
	s_mov_b32 s6, 0xfc000
	v_mul_f32_e32 v153, v62, v153
	v_mul_f32_e32 v155, v58, v155
	v_mul_f32_e32 v165, v63, v165
	v_mul_f32_e32 v171, v64, v166
	v_cvt_pk_bf16_f32 v166, v153, v165
	v_cvt_pk_bf16_f32 v167, v171, v167
	v_cvt_pk_bf16_f32 v168, v155, v169
	v_cvt_pk_bf16_f32 v169, v172, v170
	v_add_co_u32_e32 v170, vcc, s6, v158
	v_mul_f32_e32 v153, 0xbfb8aa3b, v30
	s_nop 0
	v_addc_co_u32_e32 v171, vcc, 0, v159, vcc
	global_store_dwordx4 v[170:171], v[166:169], off offset:2048 nt
	v_mul_f32_e32 v165, 0xbfb8aa3b, v31
	v_exp_f32_e32 v153, v153
	v_mul_f32_e32 v166, 0xbfb8aa3b, v27
	v_exp_f32_e32 v166, v166
	v_mul_f32_e32 v167, 0xbfb8aa3b, v32
	v_mul_f32_e32 v168, 0xbfb8aa3b, v28
	v_exp_f32_e32 v167, v167
	v_add_f32_e32 v166, 1.0, v166
	v_rcp_f32_e32 v166, v166
	v_exp_f32_e32 v168, v168
	v_mul_f32_e32 v155, 0xbfb8aa3b, v26
	v_exp_f32_e32 v165, v165
	v_mul_f32_e32 v169, v27, v166
	v_add_f32_e32 v166, 1.0, v167
	v_add_f32_e32 v167, 1.0, v168
	v_mul_f32_e32 v168, 0xbfb8aa3b, v33
	v_exp_f32_e32 v168, v168
	v_mul_f32_e32 v172, 0xbfb8aa3b, v29
	v_exp_f32_e32 v155, v155
	v_exp_f32_e32 v172, v172
	v_add_f32_e32 v153, 1.0, v153
	v_add_f32_e32 v165, 1.0, v165
	v_add_f32_e32 v168, 1.0, v168
	v_rcp_f32_e32 v153, v153
	v_add_f32_e32 v155, 1.0, v155
	v_rcp_f32_e32 v165, v165
	v_rcp_f32_e32 v166, v166
	v_rcp_f32_e32 v167, v167
	v_rcp_f32_e32 v168, v168
	v_add_f32_e32 v172, 1.0, v172
	v_rcp_f32_e32 v155, v155
	v_rcp_f32_e32 v172, v172
	v_mul_f32_e32 v153, v30, v153
	v_mul_f32_e32 v165, v31, v165
	v_mul_f32_e32 v173, v32, v166
	v_mul_f32_e32 v174, v28, v167
	v_mul_f32_e32 v167, v33, v168
	v_cvt_pk_bf16_f32 v166, v153, v165
	v_mul_f32_e32 v155, v26, v155
	v_mul_f32_e32 v172, v29, v172
	v_cvt_pk_bf16_f32 v167, v173, v167
	v_cvt_pk_bf16_f32 v168, v155, v169
	v_cvt_pk_bf16_f32 v169, v174, v172
	global_store_dwordx4 v[170:171], v[166:169], off offset:2304 nt
	v_mul_f32_e32 v170, 0xbfb8aa3b, v53
	v_mul_f32_e32 v153, 0xbfb8aa3b, v54
	v_mul_f32_e32 v166, 0xbfb8aa3b, v51
	v_exp_f32_e32 v166, v166
	v_mul_f32_e32 v167, 0xbfb8aa3b, v56
	v_mul_f32_e32 v168, 0xbfb8aa3b, v52
	v_exp_f32_e32 v167, v167
	v_add_f32_e32 v166, 1.0, v166
	v_rcp_f32_e32 v166, v166
	v_exp_f32_e32 v168, v168
	v_mul_f32_e32 v155, 0xbfb8aa3b, v50
	v_mul_f32_e32 v165, 0xbfb8aa3b, v55
	v_mul_f32_e32 v169, v51, v166
	v_add_f32_e32 v166, 1.0, v167
	v_add_f32_e32 v167, 1.0, v168
	v_mul_f32_e32 v168, 0xbfb8aa3b, v57
	v_exp_f32_e32 v168, v168
	v_exp_f32_e32 v170, v170
	v_exp_f32_e32 v153, v153
	v_exp_f32_e32 v155, v155
	v_exp_f32_e32 v165, v165
	v_add_f32_e32 v168, 1.0, v168
	v_add_f32_e32 v170, 1.0, v170
	v_add_f32_e32 v153, 1.0, v153
	v_add_f32_e32 v155, 1.0, v155
	v_add_f32_e32 v165, 1.0, v165
	v_rcp_f32_e32 v167, v167
	v_rcp_f32_e32 v168, v168
	v_rcp_f32_e32 v170, v170
	v_rcp_f32_e32 v153, v153
	v_rcp_f32_e32 v155, v155
	v_rcp_f32_e32 v165, v165
	v_rcp_f32_e32 v166, v166
	v_mul_f32_e32 v172, v52, v167
	v_mul_f32_e32 v167, v57, v168
	v_mul_f32_e32 v170, v53, v170
	s_mov_b32 s6, 0x11c000
	v_mul_f32_e32 v153, v54, v153
	v_mul_f32_e32 v155, v50, v155
	v_mul_f32_e32 v165, v55, v165
	v_mul_f32_e32 v171, v56, v166
	v_cvt_pk_bf16_f32 v166, v153, v165
	v_cvt_pk_bf16_f32 v167, v171, v167
	v_cvt_pk_bf16_f32 v168, v155, v169
	v_cvt_pk_bf16_f32 v169, v172, v170
	v_add_co_u32_e32 v170, vcc, s6, v158
	v_mul_f32_e32 v153, 0xbfb8aa3b, v22
	s_nop 0
	v_addc_co_u32_e32 v171, vcc, 0, v159, vcc
	global_store_dwordx4 v[170:171], v[166:169], off offset:2048 nt
	v_mul_f32_e32 v165, 0xbfb8aa3b, v23
	v_exp_f32_e32 v153, v153
	v_mul_f32_e32 v166, 0xbfb8aa3b, v19
	v_exp_f32_e32 v166, v166
	v_mul_f32_e32 v167, 0xbfb8aa3b, v24
	v_mul_f32_e32 v168, 0xbfb8aa3b, v20
	v_exp_f32_e32 v167, v167
	v_add_f32_e32 v166, 1.0, v166
	v_rcp_f32_e32 v166, v166
	v_exp_f32_e32 v168, v168
	v_mul_f32_e32 v155, 0xbfb8aa3b, v18
	v_exp_f32_e32 v165, v165
	v_mul_f32_e32 v169, v19, v166
	v_add_f32_e32 v166, 1.0, v167
	v_add_f32_e32 v167, 1.0, v168
	v_mul_f32_e32 v168, 0xbfb8aa3b, v25
	v_exp_f32_e32 v168, v168
	v_mul_f32_e32 v172, 0xbfb8aa3b, v21
	v_exp_f32_e32 v155, v155
	v_exp_f32_e32 v172, v172
	v_add_f32_e32 v153, 1.0, v153
	v_add_f32_e32 v165, 1.0, v165
	v_add_f32_e32 v168, 1.0, v168
	v_rcp_f32_e32 v153, v153
	v_add_f32_e32 v155, 1.0, v155
	v_rcp_f32_e32 v165, v165
	v_rcp_f32_e32 v166, v166
	v_rcp_f32_e32 v167, v167
	v_rcp_f32_e32 v168, v168
	v_add_f32_e32 v172, 1.0, v172
	v_rcp_f32_e32 v155, v155
	v_rcp_f32_e32 v172, v172
	v_mul_f32_e32 v153, v22, v153
	v_mul_f32_e32 v165, v23, v165
	v_mul_f32_e32 v173, v24, v166
	v_mul_f32_e32 v174, v20, v167
	v_mul_f32_e32 v167, v25, v168
	v_cvt_pk_bf16_f32 v166, v153, v165
	v_mul_f32_e32 v155, v18, v155
	v_mul_f32_e32 v172, v21, v172
	v_cvt_pk_bf16_f32 v167, v173, v167
	v_cvt_pk_bf16_f32 v168, v155, v169
	v_cvt_pk_bf16_f32 v169, v174, v172
	global_store_dwordx4 v[170:171], v[166:169], off offset:2304 nt
	v_mul_f32_e32 v170, 0xbfb8aa3b, v45
	v_mul_f32_e32 v153, 0xbfb8aa3b, v46
	v_mul_f32_e32 v166, 0xbfb8aa3b, v43
	v_exp_f32_e32 v166, v166
	v_mul_f32_e32 v167, 0xbfb8aa3b, v48
	v_mul_f32_e32 v168, 0xbfb8aa3b, v44
	v_exp_f32_e32 v167, v167
	v_add_f32_e32 v166, 1.0, v166
	v_rcp_f32_e32 v166, v166
	v_exp_f32_e32 v168, v168
	v_mul_f32_e32 v155, 0xbfb8aa3b, v42
	v_mul_f32_e32 v165, 0xbfb8aa3b, v47
	v_mul_f32_e32 v169, v43, v166
	v_add_f32_e32 v166, 1.0, v167
	v_add_f32_e32 v167, 1.0, v168
	v_mul_f32_e32 v168, 0xbfb8aa3b, v49
	v_exp_f32_e32 v168, v168
	v_exp_f32_e32 v170, v170
	v_exp_f32_e32 v153, v153
	v_exp_f32_e32 v155, v155
	v_exp_f32_e32 v165, v165
	v_add_f32_e32 v168, 1.0, v168
	v_add_f32_e32 v170, 1.0, v170
	v_add_f32_e32 v153, 1.0, v153
	v_add_f32_e32 v155, 1.0, v155
	v_add_f32_e32 v165, 1.0, v165
	v_rcp_f32_e32 v167, v167
	v_rcp_f32_e32 v168, v168
	v_rcp_f32_e32 v170, v170
	v_rcp_f32_e32 v153, v153
	v_rcp_f32_e32 v155, v155
	v_rcp_f32_e32 v165, v165
	v_rcp_f32_e32 v166, v166
	v_mul_f32_e32 v172, v44, v167
	v_mul_f32_e32 v167, v49, v168
	v_mul_f32_e32 v170, v45, v170
	s_mov_b32 s6, 0x13c000
	v_mul_f32_e32 v153, v46, v153
	v_mul_f32_e32 v155, v42, v155
	v_mul_f32_e32 v165, v47, v165
	v_mul_f32_e32 v171, v48, v166
	v_cvt_pk_bf16_f32 v166, v153, v165
	v_cvt_pk_bf16_f32 v167, v171, v167
	v_cvt_pk_bf16_f32 v168, v155, v169
	v_cvt_pk_bf16_f32 v169, v172, v170
	v_add_co_u32_e32 v170, vcc, s6, v158
	v_mul_f32_e32 v153, 0xbfb8aa3b, v14
	s_nop 0
	v_addc_co_u32_e32 v171, vcc, 0, v159, vcc
	global_store_dwordx4 v[170:171], v[166:169], off offset:2048 nt
	v_mul_f32_e32 v165, 0xbfb8aa3b, v15
	v_exp_f32_e32 v153, v153
	v_mul_f32_e32 v166, 0xbfb8aa3b, v11
	v_exp_f32_e32 v166, v166
	v_mul_f32_e32 v167, 0xbfb8aa3b, v16
	v_mul_f32_e32 v168, 0xbfb8aa3b, v12
	v_exp_f32_e32 v167, v167
	v_add_f32_e32 v166, 1.0, v166
	v_rcp_f32_e32 v166, v166
	v_exp_f32_e32 v168, v168
	v_mul_f32_e32 v155, 0xbfb8aa3b, v10
	v_exp_f32_e32 v165, v165
	v_mul_f32_e32 v169, v11, v166
	v_add_f32_e32 v166, 1.0, v167
	v_add_f32_e32 v167, 1.0, v168
	v_mul_f32_e32 v168, 0xbfb8aa3b, v17
	v_exp_f32_e32 v168, v168
	v_mul_f32_e32 v172, 0xbfb8aa3b, v13
	v_exp_f32_e32 v155, v155
	v_exp_f32_e32 v172, v172
	v_add_f32_e32 v153, 1.0, v153
	v_add_f32_e32 v165, 1.0, v165
	v_add_f32_e32 v168, 1.0, v168
	v_rcp_f32_e32 v153, v153
	v_add_f32_e32 v155, 1.0, v155
	v_rcp_f32_e32 v165, v165
	v_rcp_f32_e32 v166, v166
	v_rcp_f32_e32 v167, v167
	v_rcp_f32_e32 v168, v168
	v_add_f32_e32 v172, 1.0, v172
	v_rcp_f32_e32 v155, v155
	v_rcp_f32_e32 v172, v172
	v_mul_f32_e32 v153, v14, v153
	v_mul_f32_e32 v165, v15, v165
	v_mul_f32_e32 v173, v16, v166
	v_mul_f32_e32 v174, v12, v167
	v_mul_f32_e32 v167, v17, v168
	v_cvt_pk_bf16_f32 v166, v153, v165
	v_mul_f32_e32 v155, v10, v155
	v_mul_f32_e32 v172, v13, v172
	v_cvt_pk_bf16_f32 v167, v173, v167
	v_cvt_pk_bf16_f32 v168, v155, v169
	v_cvt_pk_bf16_f32 v169, v174, v172
	global_store_dwordx4 v[170:171], v[166:169], off offset:2304 nt
	v_mul_f32_e32 v153, 0xbfb8aa3b, v38
	v_mul_f32_e32 v165, 0xbfb8aa3b, v39
	v_mul_f32_e32 v166, 0xbfb8aa3b, v35
	v_exp_f32_e32 v166, v166
	v_mul_f32_e32 v167, 0xbfb8aa3b, v40
	v_mul_f32_e32 v168, 0xbfb8aa3b, v36
	v_exp_f32_e32 v167, v167
	v_add_f32_e32 v166, 1.0, v166
	v_rcp_f32_e32 v166, v166
	v_exp_f32_e32 v168, v168
	v_exp_f32_e32 v153, v153
	v_mul_f32_e32 v155, 0xbfb8aa3b, v34
	v_mul_f32_e32 v169, v35, v166
	v_add_f32_e32 v166, 1.0, v167
	v_add_f32_e32 v167, 1.0, v168
	v_mul_f32_e32 v168, 0xbfb8aa3b, v41
	v_exp_f32_e32 v165, v165
	v_exp_f32_e32 v168, v168
	v_mul_f32_e32 v170, 0xbfb8aa3b, v37
	v_exp_f32_e32 v155, v155
	v_exp_f32_e32 v170, v170
	v_add_f32_e32 v153, 1.0, v153
	v_add_f32_e32 v165, 1.0, v165
	v_add_f32_e32 v168, 1.0, v168
	v_rcp_f32_e32 v153, v153
	v_add_f32_e32 v155, 1.0, v155
	v_rcp_f32_e32 v165, v165
	v_rcp_f32_e32 v166, v166
	v_rcp_f32_e32 v167, v167
	v_rcp_f32_e32 v168, v168
	v_add_f32_e32 v170, 1.0, v170
	v_rcp_f32_e32 v155, v155
	v_rcp_f32_e32 v170, v170
	v_add_co_u32_e32 v158, vcc, s59, v158
	v_mul_f32_e32 v153, v38, v153
	v_mul_f32_e32 v165, v39, v165
	v_mul_f32_e32 v171, v40, v166
	v_mul_f32_e32 v172, v36, v167
	v_mul_f32_e32 v167, v41, v168
	v_cvt_pk_bf16_f32 v166, v153, v165
	v_addc_co_u32_e32 v159, vcc, 0, v159, vcc
	v_mul_f32_e32 v155, v34, v155
	v_mul_f32_e32 v170, v37, v170
	v_cvt_pk_bf16_f32 v167, v171, v167
	v_cvt_pk_bf16_f32 v168, v155, v169
	v_cvt_pk_bf16_f32 v169, v172, v170
	global_store_dwordx4 v[158:159], v[166:169], off offset:2048 nt
	v_mul_f32_e32 v153, 0xbfb8aa3b, v6
	v_mul_f32_e32 v155, 0xbfb8aa3b, v2
	v_mul_f32_e32 v166, 0xbfb8aa3b, v3
	v_exp_f32_e32 v166, v166
	v_mul_f32_e32 v167, 0xbfb8aa3b, v8
	v_mul_f32_e32 v168, 0xbfb8aa3b, v4
	v_exp_f32_e32 v167, v167
	v_add_f32_e32 v166, 1.0, v166
	v_rcp_f32_e32 v166, v166
	v_exp_f32_e32 v168, v168
	v_mul_f32_e32 v165, 0xbfb8aa3b, v7
	v_mul_f32_e32 v170, 0xbfb8aa3b, v5
	v_mul_f32_e32 v169, v3, v166
	v_add_f32_e32 v166, 1.0, v167
	v_add_f32_e32 v167, 1.0, v168
	v_mul_f32_e32 v168, 0xbfb8aa3b, v9
	v_exp_f32_e32 v168, v168
	v_exp_f32_e32 v153, v153
	v_exp_f32_e32 v155, v155
	v_exp_f32_e32 v165, v165
	v_exp_f32_e32 v170, v170
	v_add_f32_e32 v168, 1.0, v168
	v_add_f32_e32 v153, 1.0, v153
	v_add_f32_e32 v155, 1.0, v155
	v_add_f32_e32 v165, 1.0, v165
	v_rcp_f32_e32 v167, v167
	v_rcp_f32_e32 v168, v168
	v_add_f32_e32 v170, 1.0, v170
	v_rcp_f32_e32 v153, v153
	v_rcp_f32_e32 v155, v155
	v_rcp_f32_e32 v165, v165
	v_rcp_f32_e32 v166, v166
	v_rcp_f32_e32 v170, v170
	v_mul_f32_e32 v172, v4, v167
	v_mul_f32_e32 v167, v9, v168
	v_mul_f32_e32 v153, v6, v153
	v_mul_f32_e32 v155, v2, v155
	v_mul_f32_e32 v165, v7, v165
	v_mul_f32_e32 v171, v8, v166
	v_mul_f32_e32 v170, v5, v170
	v_cvt_pk_bf16_f32 v166, v153, v165
	v_cvt_pk_bf16_f32 v167, v171, v167
	v_cvt_pk_bf16_f32 v168, v155, v169
	v_cvt_pk_bf16_f32 v169, v172, v170
	global_store_dwordx4 v[158:159], v[166:169], off offset:2304 nt

.LBB0_1144:
	s_andn2_b64 vcc, exec, s[34:35]
	s_cbranch_vccnz .LBB0_1146
	s_lshl_b32 s6, s63, 8
	s_add_i32 s23, s6, 0xffffe800
	s_cmp_lt_i32 s63, 12
	s_cselect_b32 s34, s6, s23
	s_cselect_b32 s6, s61, 0x2dc00000
	s_cselect_b32 s25, s60, 0x400
	s_add_u32 s6, s92, s6
	s_addc_u32 s23, s93, 0
	s_ashr_i32 s35, s34, 31
	s_lshl_b64 s[34:35], s[34:35], 1
	s_add_u32 s34, s6, s34
	s_addc_u32 s35, s23, s35
	v_lshlrev_b32_e32 v158, 1, v142
	v_mov_b32_e32 v159, v139
	v_lshl_add_u64 v[158:159], s[34:35], 0, v[158:159]
	v_mad_u64_u32 v[166:167], s[34:35], v156, s25, 0
	v_mad_i32_i24 v167, v157, s25, v167
	v_lshl_add_u64 v[170:171], v[166:167], 1, v[158:159]
	v_cvt_pk_bf16_f32 v166, v126, v127
	v_cvt_pk_bf16_f32 v167, v128, v129
	v_cvt_pk_bf16_f32 v168, v122, v123
	v_cvt_pk_bf16_f32 v169, v124, v125
	global_store_dwordx4 v[170:171], v[166:169], off nt
	s_lshl_b32 s6, s25, 4
	s_nop 0
	v_cvt_pk_bf16_f32 v166, v94, v95
	v_cvt_pk_bf16_f32 v167, v96, v97
	v_cvt_pk_bf16_f32 v168, v90, v91
	v_cvt_pk_bf16_f32 v169, v92, v93
	global_store_dwordx4 v[170:171], v[166:169], off offset:256 nt
	s_nop 1
	v_mov_b64_e32 v[166:167], s[6:7]
	v_mad_u64_u32 v[170:171], s[34:35], v156, s25, v[166:167]
	v_mad_i32_i24 v171, v157, s25, v171
	v_lshl_add_u64 v[156:157], v[170:171], 1, v[158:159]
	v_cvt_pk_bf16_f32 v166, v118, v119
	v_cvt_pk_bf16_f32 v167, v120, v121
	v_cvt_pk_bf16_f32 v168, v114, v115
	v_cvt_pk_bf16_f32 v169, v116, v117
	global_store_dwordx4 v[156:157], v[166:169], off nt
	s_mul_i32 s34, s25, 0x50
	s_mov_b32 s35, s7
	v_cvt_pk_bf16_f32 v166, v86, v87
	v_cvt_pk_bf16_f32 v167, v88, v89
	v_cvt_pk_bf16_f32 v168, v82, v83
	v_cvt_pk_bf16_f32 v169, v84, v85
	global_store_dwordx4 v[156:157], v[166:169], off offset:256 nt
	v_lshl_add_u64 v[156:157], v[170:171], 0, s[6:7]
	v_lshl_add_u64 v[170:171], v[156:157], 1, v[158:159]
	v_cvt_pk_bf16_f32 v166, v110, v111
	v_cvt_pk_bf16_f32 v167, v112, v113
	v_cvt_pk_bf16_f32 v168, v106, v107
	v_cvt_pk_bf16_f32 v169, v108, v109
	global_store_dwordx4 v[170:171], v[166:169], off nt
	v_lshl_add_u64 v[156:157], v[156:157], 0, s[6:7]
	s_nop 0
	v_cvt_pk_bf16_f32 v166, v78, v79
	v_cvt_pk_bf16_f32 v167, v80, v81
	v_cvt_pk_bf16_f32 v168, v74, v75
	v_cvt_pk_bf16_f32 v169, v76, v77
	global_store_dwordx4 v[170:171], v[166:169], off offset:256 nt
	v_lshl_add_u64 v[170:171], v[156:157], 1, v[158:159]
	v_lshl_add_u64 v[156:157], v[156:157], 0, s[34:35]
	v_cvt_pk_bf16_f32 v166, v102, v103
	v_cvt_pk_bf16_f32 v167, v104, v105
	v_cvt_pk_bf16_f32 v168, v98, v99
	v_cvt_pk_bf16_f32 v169, v100, v101
	global_store_dwordx4 v[170:171], v[166:169], off nt
	s_nop 1
	v_cvt_pk_bf16_f32 v166, v70, v71
	v_cvt_pk_bf16_f32 v167, v72, v73
	v_cvt_pk_bf16_f32 v168, v66, v67
	v_cvt_pk_bf16_f32 v169, v68, v69
	global_store_dwordx4 v[170:171], v[166:169], off offset:256 nt
	v_lshl_add_u64 v[170:171], v[156:157], 1, v[158:159]
	v_lshl_add_u64 v[156:157], v[156:157], 0, s[6:7]
	v_cvt_pk_bf16_f32 v166, v62, v63
	v_cvt_pk_bf16_f32 v167, v64, v65
	v_cvt_pk_bf16_f32 v168, v58, v59
	v_cvt_pk_bf16_f32 v169, v60, v61
	global_store_dwordx4 v[170:171], v[166:169], off nt
	s_nop 1
	v_cvt_pk_bf16_f32 v166, v30, v31
	v_cvt_pk_bf16_f32 v167, v32, v33
	v_cvt_pk_bf16_f32 v168, v26, v27
	v_cvt_pk_bf16_f32 v169, v28, v29
	global_store_dwordx4 v[170:171], v[166:169], off offset:256 nt
	v_lshl_add_u64 v[170:171], v[156:157], 1, v[158:159]
	v_lshl_add_u64 v[156:157], v[156:157], 0, s[6:7]
	v_cvt_pk_bf16_f32 v166, v54, v55
	v_cvt_pk_bf16_f32 v167, v56, v57
	v_cvt_pk_bf16_f32 v168, v50, v51
	v_cvt_pk_bf16_f32 v169, v52, v53
	global_store_dwordx4 v[170:171], v[166:169], off nt
	s_nop 1
	v_cvt_pk_bf16_f32 v166, v22, v23
	v_cvt_pk_bf16_f32 v167, v24, v25
	v_cvt_pk_bf16_f32 v168, v18, v19
	v_cvt_pk_bf16_f32 v169, v20, v21
	global_store_dwordx4 v[170:171], v[166:169], off offset:256 nt
	v_lshl_add_u64 v[170:171], v[156:157], 1, v[158:159]
	v_lshl_add_u64 v[156:157], v[156:157], 0, s[6:7]
	v_cvt_pk_bf16_f32 v166, v46, v47
	v_cvt_pk_bf16_f32 v167, v48, v49
	v_cvt_pk_bf16_f32 v168, v42, v43
	v_cvt_pk_bf16_f32 v169, v44, v45
	global_store_dwordx4 v[170:171], v[166:169], off nt
	s_nop 1
	v_cvt_pk_bf16_f32 v166, v14, v15
	v_cvt_pk_bf16_f32 v167, v16, v17
	v_cvt_pk_bf16_f32 v168, v10, v11
	v_cvt_pk_bf16_f32 v169, v12, v13
	global_store_dwordx4 v[170:171], v[166:169], off offset:256 nt
	s_nop 1
	v_lshl_add_u64 v[166:167], v[156:157], 1, v[158:159]
	v_cvt_pk_bf16_f32 v156, v38, v39
	v_cvt_pk_bf16_f32 v157, v40, v41
	v_cvt_pk_bf16_f32 v158, v34, v35
	v_cvt_pk_bf16_f32 v159, v36, v37
	global_store_dwordx4 v[166:167], v[156:159], off nt
	s_nop 1
	v_cvt_pk_bf16_f32 v156, v6, v7
	v_cvt_pk_bf16_f32 v157, v8, v9
	v_cvt_pk_bf16_f32 v158, v2, v3
	v_cvt_pk_bf16_f32 v159, v4, v5
	global_store_dwordx4 v[166:167], v[156:159], off offset:256 nt

.LBB0_1147:
	s_andn2_b64 vcc, exec, s[34:35]
	s_cbranch_vccnz .LBB0_1149
	v_cvt_pk_bf16_f32 v126, v126, v139
	ds_write_b16 v160, v126
	v_cvt_pk_bf16_f32 v122, v122, v139
	ds_write_b16 v160, v122 offset:256
	v_cvt_pk_bf16_f32 v122, v127, v139
	ds_write_b16 v160, v122 offset:64
	v_cvt_pk_bf16_f32 v122, v123, v139
	s_mul_hi_i32 s6, s30, 0x3e0f83e1
	ds_write_b16 v160, v122 offset:320
	v_cvt_pk_bf16_f32 v122, v128, v139
	s_lshr_b32 s23, s6, 31
	s_ashr_i32 s6, s6, 3
	ds_write_b16 v160, v122 offset:128
	v_cvt_pk_bf16_f32 v122, v124, v139
	s_add_i32 s6, s6, s23
	ds_write_b16 v160, v122 offset:384
	v_cvt_pk_bf16_f32 v122, v129, v139
	s_mul_i32 s23, s6, 33
	s_lshl_b32 s25, s63, 8
	ds_write_b16 v160, v122 offset:192
	v_cvt_pk_bf16_f32 v122, v125, v139
	ds_write_b16 v160, v122 offset:448
	v_cvt_pk_bf16_f32 v118, v118, v139
	ds_write_b16 v160, v118 offset:32
	v_cvt_pk_bf16_f32 v114, v114, v139
	s_sub_i32 s23, s30, s23
	s_add_i32 s30, s25, 0xfffff400
	ds_write_b16 v160, v114 offset:288
	v_cvt_pk_bf16_f32 v114, v119, v139
	s_lshr_b32 s30, s30, 9
	s_mul_i32 s6, s6, 6
	ds_write_b16 v160, v114 offset:96
	v_cvt_pk_bf16_f32 v114, v115, v139
	s_lshl_b32 s23, s23, 3
	s_add_i32 s6, s30, s6
	ds_write_b16 v160, v114 offset:352
	v_cvt_pk_bf16_f32 v114, v120, v139
	s_add_i32 s23, s23, s55
	s_mulk_i32 s6, 0x108
	ds_write_b16 v160, v114 offset:160
	v_cvt_pk_bf16_f32 v114, v116, v139
	s_add_i32 s30, s23, s6
	ds_write_b16 v160, v114 offset:416
	v_cvt_pk_bf16_f32 v114, v121, v139
	s_and_b32 s25, s25, 0x100
	ds_write_b16 v160, v114 offset:224
	v_cvt_pk_bf16_f32 v114, v117, v139
	ds_write_b16 v160, v114 offset:480
	s_ashr_i32 s31, s30, 31
	s_or_b32 s25, s25, s52
	s_waitcnt lgkmcnt(0)
	s_lshl_b64 s[34:35], s[30:31], 15
	s_add_u32 s31, s50, s34
	s_addc_u32 s36, s51, s35
	s_lshl_b32 s6, s25, 6
	ds_read_b128 v[114:117], v143
	ds_read_b128 v[118:121], v143 offset:1024
	s_add_u32 s34, s31, s6
	s_addc_u32 s35, s36, 0
	v_lshl_add_u64 v[122:123], s[34:35], 0, v[138:139]
	v_mov_b32_e32 v155, v139
	v_lshl_add_u64 v[122:123], v[122:123], 0, v[154:155]
	s_waitcnt lgkmcnt(0)
	global_store_dwordx4 v[122:123], v[114:117], off nt
	global_store_dwordx4 v[122:123], v[118:121], off offset:1024 nt
	s_waitcnt lgkmcnt(0)
	v_cvt_pk_bf16_f32 v110, v110, v139
	ds_write_b16 v160, v110
	v_cvt_pk_bf16_f32 v106, v106, v139
	ds_write_b16 v160, v106 offset:256
	v_cvt_pk_bf16_f32 v106, v111, v139
	ds_write_b16 v160, v106 offset:64
	v_cvt_pk_bf16_f32 v106, v107, v139
	ds_write_b16 v160, v106 offset:320
	v_cvt_pk_bf16_f32 v106, v112, v139
	ds_write_b16 v160, v106 offset:128
	v_cvt_pk_bf16_f32 v106, v108, v139
	ds_write_b16 v160, v106 offset:384
	v_cvt_pk_bf16_f32 v106, v113, v139
	ds_write_b16 v160, v106 offset:192
	v_cvt_pk_bf16_f32 v106, v109, v139
	ds_write_b16 v160, v106 offset:448
	v_cvt_pk_bf16_f32 v102, v102, v139
	ds_write_b16 v160, v102 offset:32
	v_cvt_pk_bf16_f32 v98, v98, v139
	ds_write_b16 v160, v98 offset:288
	v_cvt_pk_bf16_f32 v98, v103, v139
	ds_write_b16 v160, v98 offset:96
	v_cvt_pk_bf16_f32 v98, v99, v139
	ds_write_b16 v160, v98 offset:352
	v_cvt_pk_bf16_f32 v98, v104, v139
	ds_write_b16 v160, v98 offset:160
	v_cvt_pk_bf16_f32 v98, v100, v139
	ds_write_b16 v160, v98 offset:416
	v_cvt_pk_bf16_f32 v98, v105, v139
	s_or_b32 s34, s30, 1
	ds_write_b16 v160, v98 offset:224
	v_cvt_pk_bf16_f32 v98, v101, v139
	ds_write_b16 v160, v98 offset:480
	s_ashr_i32 s35, s34, 31
	s_waitcnt lgkmcnt(0)
	s_lshl_b64 s[34:35], s[34:35], 15
	s_add_u32 s25, s50, s34
	s_addc_u32 s37, s51, s35
	ds_read_b128 v[98:101], v143
	ds_read_b128 v[102:105], v143 offset:1024
	s_add_u32 s34, s25, s6
	s_addc_u32 s35, s37, 0
	v_lshl_add_u64 v[106:107], s[34:35], 0, v[138:139]
	v_lshl_add_u64 v[106:107], v[106:107], 0, v[154:155]
	s_waitcnt lgkmcnt(0)
	global_store_dwordx4 v[106:107], v[98:101], off nt
	global_store_dwordx4 v[106:107], v[102:105], off offset:1024 nt
	s_waitcnt lgkmcnt(0)
	v_cvt_pk_bf16_f32 v94, v94, v139
	ds_write_b16 v160, v94
	v_cvt_pk_bf16_f32 v90, v90, v139
	ds_write_b16 v160, v90 offset:256
	v_cvt_pk_bf16_f32 v90, v95, v139
	ds_write_b16 v160, v90 offset:64
	v_cvt_pk_bf16_f32 v90, v91, v139
	ds_write_b16 v160, v90 offset:320
	v_cvt_pk_bf16_f32 v90, v96, v139
	ds_write_b16 v160, v90 offset:128
	v_cvt_pk_bf16_f32 v90, v92, v139
	ds_write_b16 v160, v90 offset:384
	v_cvt_pk_bf16_f32 v90, v97, v139
	ds_write_b16 v160, v90 offset:192
	v_cvt_pk_bf16_f32 v90, v93, v139
	ds_write_b16 v160, v90 offset:448
	v_cvt_pk_bf16_f32 v86, v86, v139
	ds_write_b16 v160, v86 offset:32
	v_cvt_pk_bf16_f32 v82, v82, v139
	ds_write_b16 v160, v82 offset:288
	v_cvt_pk_bf16_f32 v82, v87, v139
	ds_write_b16 v160, v82 offset:96
	v_cvt_pk_bf16_f32 v82, v83, v139
	ds_write_b16 v160, v82 offset:352
	v_cvt_pk_bf16_f32 v82, v88, v139
	ds_write_b16 v160, v82 offset:160
	v_cvt_pk_bf16_f32 v82, v84, v139
	ds_write_b16 v160, v82 offset:416
	v_cvt_pk_bf16_f32 v82, v89, v139
	ds_write_b16 v160, v82 offset:224
	v_cvt_pk_bf16_f32 v82, v85, v139
	ds_write_b16 v160, v82 offset:480
	s_waitcnt lgkmcnt(0)
	s_or_b32 s23, s6, 0x2000
	ds_read_b128 v[82:85], v143
	ds_read_b128 v[86:89], v143 offset:1024
	s_add_u32 s34, s31, s23
	s_addc_u32 s35, s36, 0
	v_lshl_add_u64 v[90:91], s[34:35], 0, v[138:139]
	v_lshl_add_u64 v[90:91], v[90:91], 0, v[154:155]
	s_waitcnt lgkmcnt(0)
	global_store_dwordx4 v[90:91], v[82:85], off nt
	global_store_dwordx4 v[90:91], v[86:89], off offset:1024 nt
	s_waitcnt lgkmcnt(0)
	v_cvt_pk_bf16_f32 v78, v78, v139
	ds_write_b16 v160, v78
	v_cvt_pk_bf16_f32 v74, v74, v139
	ds_write_b16 v160, v74 offset:256
	v_cvt_pk_bf16_f32 v74, v79, v139
	ds_write_b16 v160, v74 offset:64
	v_cvt_pk_bf16_f32 v74, v75, v139
	ds_write_b16 v160, v74 offset:320
	v_cvt_pk_bf16_f32 v74, v80, v139
	ds_write_b16 v160, v74 offset:128
	v_cvt_pk_bf16_f32 v74, v76, v139
	ds_write_b16 v160, v74 offset:384
	v_cvt_pk_bf16_f32 v74, v81, v139
	ds_write_b16 v160, v74 offset:192
	v_cvt_pk_bf16_f32 v74, v77, v139
	ds_write_b16 v160, v74 offset:448
	v_cvt_pk_bf16_f32 v70, v70, v139
	ds_write_b16 v160, v70 offset:32
	v_cvt_pk_bf16_f32 v66, v66, v139
	ds_write_b16 v160, v66 offset:288
	v_cvt_pk_bf16_f32 v66, v71, v139
	ds_write_b16 v160, v66 offset:96
	v_cvt_pk_bf16_f32 v66, v67, v139
	ds_write_b16 v160, v66 offset:352
	v_cvt_pk_bf16_f32 v66, v72, v139
	ds_write_b16 v160, v66 offset:160
	v_cvt_pk_bf16_f32 v66, v68, v139
	ds_write_b16 v160, v66 offset:416
	v_cvt_pk_bf16_f32 v66, v73, v139
	ds_write_b16 v160, v66 offset:224
	v_cvt_pk_bf16_f32 v66, v69, v139
	ds_write_b16 v160, v66 offset:480
	s_waitcnt lgkmcnt(0)
	ds_read_b128 v[66:69], v143
	ds_read_b128 v[70:73], v143 offset:1024
	s_add_u32 s34, s25, s23
	s_addc_u32 s35, s37, 0
	v_lshl_add_u64 v[74:75], s[34:35], 0, v[138:139]
	v_lshl_add_u64 v[74:75], v[74:75], 0, v[154:155]
	s_waitcnt lgkmcnt(0)
	global_store_dwordx4 v[74:75], v[66:69], off nt
	global_store_dwordx4 v[74:75], v[70:73], off offset:1024 nt
	s_waitcnt lgkmcnt(0)
	v_cvt_pk_bf16_f32 v62, v62, v139
	ds_write_b16 v160, v62
	v_cvt_pk_bf16_f32 v58, v58, v139
	ds_write_b16 v160, v58 offset:256
	v_cvt_pk_bf16_f32 v58, v63, v139
	ds_write_b16 v160, v58 offset:64
	v_cvt_pk_bf16_f32 v58, v59, v139
	ds_write_b16 v160, v58 offset:320
	v_cvt_pk_bf16_f32 v58, v64, v139
	ds_write_b16 v160, v58 offset:128
	v_cvt_pk_bf16_f32 v58, v60, v139
	ds_write_b16 v160, v58 offset:384
	v_cvt_pk_bf16_f32 v58, v65, v139
	ds_write_b16 v160, v58 offset:192
	v_cvt_pk_bf16_f32 v58, v61, v139
	ds_write_b16 v160, v58 offset:448
	v_cvt_pk_bf16_f32 v54, v54, v139
	ds_write_b16 v160, v54 offset:32
	v_cvt_pk_bf16_f32 v50, v50, v139
	ds_write_b16 v160, v50 offset:288
	v_cvt_pk_bf16_f32 v50, v55, v139
	ds_write_b16 v160, v50 offset:96
	v_cvt_pk_bf16_f32 v50, v51, v139
	ds_write_b16 v160, v50 offset:352
	v_cvt_pk_bf16_f32 v50, v56, v139
	ds_write_b16 v160, v50 offset:160
	v_cvt_pk_bf16_f32 v50, v52, v139
	s_add_i32 s34, s30, 4
	ds_write_b16 v160, v50 offset:416
	v_cvt_pk_bf16_f32 v50, v57, v139
	ds_write_b16 v160, v50 offset:224
	v_cvt_pk_bf16_f32 v50, v53, v139
	ds_write_b16 v160, v50 offset:480
	s_ashr_i32 s35, s34, 31
	s_waitcnt lgkmcnt(0)
	s_lshl_b64 s[34:35], s[34:35], 15
	s_add_u32 s25, s50, s34
	s_addc_u32 s36, s51, s35
	ds_read_b128 v[50:53], v143
	ds_read_b128 v[54:57], v143 offset:1024
	s_add_u32 s34, s25, s6
	s_addc_u32 s35, s36, 0
	v_lshl_add_u64 v[58:59], s[34:35], 0, v[138:139]
	v_lshl_add_u64 v[58:59], v[58:59], 0, v[154:155]
	s_waitcnt lgkmcnt(0)
	global_store_dwordx4 v[58:59], v[50:53], off nt
	global_store_dwordx4 v[58:59], v[54:57], off offset:1024 nt
	s_waitcnt lgkmcnt(0)
	v_cvt_pk_bf16_f32 v46, v46, v139
	ds_write_b16 v160, v46
	v_cvt_pk_bf16_f32 v42, v42, v139
	ds_write_b16 v160, v42 offset:256
	v_cvt_pk_bf16_f32 v42, v47, v139
	ds_write_b16 v160, v42 offset:64
	v_cvt_pk_bf16_f32 v42, v43, v139
	ds_write_b16 v160, v42 offset:320
	v_cvt_pk_bf16_f32 v42, v48, v139
	ds_write_b16 v160, v42 offset:128
	v_cvt_pk_bf16_f32 v42, v44, v139
	ds_write_b16 v160, v42 offset:384
	v_cvt_pk_bf16_f32 v42, v49, v139
	ds_write_b16 v160, v42 offset:192
	v_cvt_pk_bf16_f32 v42, v45, v139
	ds_write_b16 v160, v42 offset:448
	v_cvt_pk_bf16_f32 v38, v38, v139
	ds_write_b16 v160, v38 offset:32
	v_cvt_pk_bf16_f32 v34, v34, v139
	ds_write_b16 v160, v34 offset:288
	v_cvt_pk_bf16_f32 v34, v39, v139
	ds_write_b16 v160, v34 offset:96
	v_cvt_pk_bf16_f32 v34, v35, v139
	ds_write_b16 v160, v34 offset:352
	v_cvt_pk_bf16_f32 v34, v40, v139
	ds_write_b16 v160, v34 offset:160
	v_cvt_pk_bf16_f32 v34, v36, v139
	ds_write_b16 v160, v34 offset:416
	v_cvt_pk_bf16_f32 v34, v41, v139
	s_add_i32 s30, s30, 5
	ds_write_b16 v160, v34 offset:224
	v_cvt_pk_bf16_f32 v34, v37, v139
	ds_write_b16 v160, v34 offset:480
	s_ashr_i32 s31, s30, 31
	s_waitcnt lgkmcnt(0)
	s_lshl_b64 s[30:31], s[30:31], 15
	s_add_u32 s34, s50, s30
	s_addc_u32 s35, s51, s31
	ds_read_b128 v[34:37], v143
	ds_read_b128 v[38:41], v143 offset:1024
	s_add_u32 s30, s34, s6
	s_addc_u32 s31, s35, 0
	v_lshl_add_u64 v[42:43], s[30:31], 0, v[138:139]
	v_lshl_add_u64 v[42:43], v[42:43], 0, v[154:155]
	s_waitcnt lgkmcnt(0)
	global_store_dwordx4 v[42:43], v[34:37], off nt
	global_store_dwordx4 v[42:43], v[38:41], off offset:1024 nt
	s_waitcnt lgkmcnt(0)
	v_cvt_pk_bf16_f32 v30, v30, v139
	ds_write_b16 v160, v30
	v_cvt_pk_bf16_f32 v26, v26, v139
	ds_write_b16 v160, v26 offset:256
	v_cvt_pk_bf16_f32 v26, v31, v139
	ds_write_b16 v160, v26 offset:64
	v_cvt_pk_bf16_f32 v26, v27, v139
	ds_write_b16 v160, v26 offset:320
	v_cvt_pk_bf16_f32 v26, v32, v139
	ds_write_b16 v160, v26 offset:128
	v_cvt_pk_bf16_f32 v26, v28, v139
	ds_write_b16 v160, v26 offset:384
	v_cvt_pk_bf16_f32 v26, v33, v139
	ds_write_b16 v160, v26 offset:192
	v_cvt_pk_bf16_f32 v26, v29, v139
	ds_write_b16 v160, v26 offset:448
	v_cvt_pk_bf16_f32 v22, v22, v139
	ds_write_b16 v160, v22 offset:32
	v_cvt_pk_bf16_f32 v18, v18, v139
	ds_write_b16 v160, v18 offset:288
	v_cvt_pk_bf16_f32 v18, v23, v139
	ds_write_b16 v160, v18 offset:96
	v_cvt_pk_bf16_f32 v18, v19, v139
	ds_write_b16 v160, v18 offset:352
	v_cvt_pk_bf16_f32 v18, v24, v139
	ds_write_b16 v160, v18 offset:160
	v_cvt_pk_bf16_f32 v18, v20, v139
	ds_write_b16 v160, v18 offset:416
	v_cvt_pk_bf16_f32 v18, v25, v139
	ds_write_b16 v160, v18 offset:224
	v_cvt_pk_bf16_f32 v18, v21, v139
	ds_write_b16 v160, v18 offset:480
	s_waitcnt lgkmcnt(0)
	ds_read_b128 v[18:21], v143
	ds_read_b128 v[22:25], v143 offset:1024
	s_add_u32 s30, s25, s23
	s_addc_u32 s31, s36, 0
	v_lshl_add_u64 v[26:27], s[30:31], 0, v[138:139]
	v_lshl_add_u64 v[26:27], v[26:27], 0, v[154:155]
	s_waitcnt lgkmcnt(0)
	global_store_dwordx4 v[26:27], v[18:21], off nt
	global_store_dwordx4 v[26:27], v[22:25], off offset:1024 nt
	s_waitcnt lgkmcnt(0)
	v_cvt_pk_bf16_f32 v14, v14, v139
	ds_write_b16 v160, v14
	v_cvt_pk_bf16_f32 v10, v10, v139
	ds_write_b16 v160, v10 offset:256
	v_cvt_pk_bf16_f32 v10, v15, v139
	ds_write_b16 v160, v10 offset:64
	v_cvt_pk_bf16_f32 v10, v11, v139
	ds_write_b16 v160, v10 offset:320
	v_cvt_pk_bf16_f32 v10, v16, v139
	ds_write_b16 v160, v10 offset:128
	v_cvt_pk_bf16_f32 v10, v12, v139
	ds_write_b16 v160, v10 offset:384
	v_cvt_pk_bf16_f32 v10, v17, v139
	ds_write_b16 v160, v10 offset:192
	v_cvt_pk_bf16_f32 v10, v13, v139
	ds_write_b16 v160, v10 offset:448
	v_cvt_pk_bf16_f32 v6, v6, v139
	ds_write_b16 v160, v6 offset:32
	v_cvt_pk_bf16_f32 v2, v2, v139
	ds_write_b16 v160, v2 offset:288
	v_cvt_pk_bf16_f32 v2, v7, v139
	ds_write_b16 v160, v2 offset:96
	v_cvt_pk_bf16_f32 v2, v3, v139
	ds_write_b16 v160, v2 offset:352
	v_cvt_pk_bf16_f32 v2, v8, v139
	ds_write_b16 v160, v2 offset:160
	v_cvt_pk_bf16_f32 v2, v4, v139
	ds_write_b16 v160, v2 offset:416
	v_cvt_pk_bf16_f32 v2, v9, v139
	ds_write_b16 v160, v2 offset:224
	v_cvt_pk_bf16_f32 v2, v5, v139
	ds_write_b16 v160, v2 offset:480
	s_waitcnt lgkmcnt(0)
	ds_read_b128 v[2:5], v143
	ds_read_b128 v[6:9], v143 offset:1024
	s_add_u32 s30, s34, s23
	s_addc_u32 s31, s35, 0
	v_lshl_add_u64 v[10:11], s[30:31], 0, v[138:139]
	v_lshl_add_u64 v[10:11], v[10:11], 0, v[154:155]
	s_waitcnt lgkmcnt(0)
	global_store_dwordx4 v[10:11], v[2:5], off nt
	global_store_dwordx4 v[10:11], v[6:9], off offset:1024 nt
	s_waitcnt lgkmcnt(0)
